# v028 + s_setprio 1 moved before the opening barrier and s_setprio 0 after the closing barrier of each MFMA segment
# speedup vs baseline: 1.0024x; 1.0024x over previous
; #define PG8_STAGE(bufoff, gbase, voff) do { _Pragma("unroll") for (int _i = 0; _i < 2; ++_i) \
;         __builtin_amdgcn_global_load_lds((const unsigned*)((const char*)(gbase) + (voff)[_i]), (LAS unsigned*)(lds + (bufoff) + ldsw + _i * 8192), 16, 0, 0); } while (0)
; #define PG8_LDA(dst, b, h) do { _Pragma("unroll") for (int m = 0; m < 4; ++m) _Pragma("unroll") for (int k = 0; k < 2; ++k) dst[m][k] = *(const LAS bf16x8*)(lds + PG8_SA(b, h) + aoff + m * 2048 + k * 1024); } while (0)
; #define PG8_LDB(dst, b, h) do { _Pragma("unroll") for (int n = 0; n < 2; ++n) _Pragma("unroll") for (int k = 0; k < 2; ++k) dst[n][k] = *(const LAS bf16x8*)(lds + PG8_SB(b, h) + boff + n * 2048 + k * 1024); } while (0)
; #define PG8_MMA(ai, bj, At, Bt) do { __builtin_amdgcn_s_setprio(1); _Pragma("unroll") for (int m = 0; m < 4; ++m) _Pragma("unroll") for (int n = 0; n < 2; ++n) _Pragma("unroll") for (int k = 0; k < 2; ++k) \
;         acc[ai][bj][m][n] = __builtin_amdgcn_mfma_f32_16x16x32_bf16(Bt[n][k], At[m][k], acc[ai][bj][m][n], 0, 0, 0); __builtin_amdgcn_s_setprio(0); } while (0)
; #define PG8_WAIT_V(n) asm volatile("s_waitcnt vmcnt(" #n ")" ::: "memory")
; #define PG8_WAIT_L(n) asm volatile("s_waitcnt lgkmcnt(" #n ")" ::: "memory")
; #define PG8_BAR __builtin_amdgcn_s_barrier()
; #define PG8_SCHED __builtin_amdgcn_sched_barrier(0)
; template <class Epi, class Sched>
; DI void gemm_phase(LAS unsigned char* lds, const Gemm g, const Sched& S, const Epi& E) {
;     ...
;         for (int t = 0; t < nt; t += 2) {
;             const bool last = (t == nt - 2);
;             const char* a1 = cA + (size_t)(t + 1) * kstep;
;             const char* a2 = last ? nA : cA + (size_t)(t + 2) * kstep; const char* b2 = last ? nB : cB + (size_t)(t + 2) * kstep;
;             const char* a3 = a2 + kstep; const char* b3 = b2 + kstep;
;             PG8_LDB(B0, 0, 0); PG8_LDB(B1, 0, 1); PG8_SCHED; PG8_LDA(At, 0, 0); PG8_STAGE(PG8_SA(1, 1), a1 + hstepA, voffA);
;             PG8_WAIT_V(8); PG8_WAIT_L(0); PG8_BAR; PG8_MMA(0, 0, At, B0); PG8_MMA(0, 1, At, B1); PG8_BAR; PG8_SCHED;
;             PG8_LDA(At, 0, 1); PG8_STAGE(PG8_SB(0, 0), b2, voffB); PG8_STAGE(PG8_SB(0, 1), b2 + hstepB, voffB); PG8_STAGE(PG8_SA(0, 0), a2, voffA);
;             PG8_WAIT_V(8); PG8_WAIT_L(0); PG8_BAR; PG8_MMA(1, 0, At, B0); PG8_MMA(1, 1, At, B1); PG8_BAR; PG8_SCHED;
.LBB0_179:
	ds_read_b128 v[168:171], v162
	ds_read_b128 v[172:175], v162 offset:1024
	ds_read_b128 v[176:179], v162 offset:2048
	ds_read_b128 v[180:183], v162 offset:3072
	ds_read_b128 v[186:189], v163
	ds_read_b128 v[190:193], v163 offset:1024
	ds_read_b128 v[194:197], v163 offset:2048
	ds_read_b128 v[198:201], v163 offset:3072
	s_add_u32 s42, s40, 0xfffc0080
	s_addc_u32 s43, s41, -1
	s_cmp_eq_u32 s65, 12
	s_cselect_b32 s45, s35, s43
	s_cselect_b32 s44, s61, s42
	s_cselect_b32 s43, s21, s64
	s_cselect_b32 s42, s62, s63
	v_lshl_add_u64 v[234:235], s[40:41], 0, v[138:139]
	s_add_i32 m0, s49, 0xc000
	ds_read_b128 v[202:205], v160
	ds_read_b128 v[206:209], v160 offset:1024
	ds_read_b128 v[210:213], v160 offset:2048
	ds_read_b128 v[214:217], v160 offset:3072
	ds_read_b128 v[218:221], v160 offset:4096
	ds_read_b128 v[222:225], v160 offset:5120
	ds_read_b128 v[226:229], v160 offset:6144
	ds_read_b128 v[230:233], v160 offset:7168
	global_load_lds_dwordx4 v[234:235], off
	v_lshl_add_u64 v[234:235], s[40:41], 0, v[140:141]
	s_add_i32 m0, s49, 0xe000
	s_nop 0
	global_load_lds_dwordx4 v[234:235], off
	s_waitcnt vmcnt(8)
	s_waitcnt lgkmcnt(0)
	s_setprio 1
	s_barrier
	v_mfma_f32_16x16x32_bf16 v[126:129], v[168:171], v[202:205], v[126:129]
	v_mfma_f32_16x16x32_bf16 v[118:121], v[176:179], v[202:205], v[118:121]
	v_mfma_f32_16x16x32_bf16 v[110:113], v[168:171], v[210:213], v[110:113]
	v_mfma_f32_16x16x32_bf16 v[102:105], v[176:179], v[210:213], v[102:105]
	v_mfma_f32_16x16x32_bf16 v[94:97], v[168:171], v[218:221], v[94:97]
	v_mfma_f32_16x16x32_bf16 v[86:89], v[176:179], v[218:221], v[86:89]
	v_mfma_f32_16x16x32_bf16 v[78:81], v[168:171], v[226:229], v[78:81]
	v_mfma_f32_16x16x32_bf16 v[70:73], v[176:179], v[226:229], v[70:73]
	v_mfma_f32_16x16x32_bf16 v[126:129], v[172:175], v[206:209], v[126:129]
	v_mfma_f32_16x16x32_bf16 v[118:121], v[180:183], v[206:209], v[118:121]
	v_mfma_f32_16x16x32_bf16 v[110:113], v[172:175], v[214:217], v[110:113]
	v_mfma_f32_16x16x32_bf16 v[102:105], v[180:183], v[214:217], v[102:105]
	v_mfma_f32_16x16x32_bf16 v[94:97], v[172:175], v[222:225], v[94:97]
	v_mfma_f32_16x16x32_bf16 v[86:89], v[180:183], v[222:225], v[86:89]
	v_mfma_f32_16x16x32_bf16 v[78:81], v[172:175], v[230:233], v[78:81]
	v_mfma_f32_16x16x32_bf16 v[70:73], v[180:183], v[230:233], v[70:73]
	v_mfma_f32_16x16x32_bf16 v[122:125], v[186:189], v[202:205], v[122:125]
	v_mfma_f32_16x16x32_bf16 v[114:117], v[194:197], v[202:205], v[114:117]
	v_mfma_f32_16x16x32_bf16 v[106:109], v[186:189], v[210:213], v[106:109]
	v_mfma_f32_16x16x32_bf16 v[98:101], v[194:197], v[210:213], v[98:101]
	v_mfma_f32_16x16x32_bf16 v[90:93], v[186:189], v[218:221], v[90:93]
	v_mfma_f32_16x16x32_bf16 v[82:85], v[194:197], v[218:221], v[82:85]
	v_mfma_f32_16x16x32_bf16 v[74:77], v[186:189], v[226:229], v[74:77]
	v_mfma_f32_16x16x32_bf16 v[66:69], v[194:197], v[226:229], v[66:69]
	v_mfma_f32_16x16x32_bf16 v[122:125], v[190:193], v[206:209], v[122:125]
	v_mfma_f32_16x16x32_bf16 v[114:117], v[198:201], v[206:209], v[114:117]
	v_mfma_f32_16x16x32_bf16 v[106:109], v[190:193], v[214:217], v[106:109]
	v_mfma_f32_16x16x32_bf16 v[98:101], v[198:201], v[214:217], v[98:101]
	v_mfma_f32_16x16x32_bf16 v[90:93], v[190:193], v[222:225], v[90:93]
	v_mfma_f32_16x16x32_bf16 v[82:85], v[198:201], v[222:225], v[82:85]
	v_mfma_f32_16x16x32_bf16 v[74:77], v[190:193], v[230:233], v[74:77]
	v_mfma_f32_16x16x32_bf16 v[66:69], v[198:201], v[230:233], v[66:69]
	s_barrier
	s_setprio 0
	s_add_i32 s66, s57, s46
	v_lshl_add_u64 v[234:235], s[42:43], 0, v[134:135]
	s_mov_b32 m0, s66
	ds_read_b128 v[202:205], v160 offset:16384
	ds_read_b128 v[206:209], v160 offset:17408
	ds_read_b128 v[210:213], v160 offset:18432
	ds_read_b128 v[214:217], v160 offset:19456
	ds_read_b128 v[218:221], v160 offset:20480
	ds_read_b128 v[222:225], v160 offset:21504
	ds_read_b128 v[226:229], v160 offset:22528
	ds_read_b128 v[230:233], v160 offset:23552
	global_load_lds_dwordx4 v[234:235], off
	s_add_i32 m0, s66, 0x2000
	s_add_u32 s66, s42, 0x40000
	v_lshl_add_u64 v[236:237], s[42:43], 0, v[130:131]
	s_addc_u32 s67, s43, 0
	s_add_i32 s68, s58, s46
	global_load_lds_dwordx4 v[236:237], off
	v_lshl_add_u64 v[238:239], s[66:67], 0, v[134:135]
	s_mov_b32 m0, s68
	v_lshl_add_u64 v[240:241], s[44:45], 0, v[132:133]
	global_load_lds_dwordx4 v[238:239], off
	v_lshl_add_u64 v[238:239], s[66:67], 0, v[130:131]
	s_add_i32 m0, s68, 0x2000
	s_nop 0
	global_load_lds_dwordx4 v[238:239], off
	v_lshl_add_u64 v[238:239], s[44:45], 0, v[136:137]
	s_mov_b32 m0, s49
	s_nop 0
	global_load_lds_dwordx4 v[238:239], off
	s_mov_b32 m0, s50
	s_nop 0
	global_load_lds_dwordx4 v[240:241], off
	s_waitcnt vmcnt(8)
	s_waitcnt lgkmcnt(0)
	s_setprio 1
	s_barrier
; #define PG8_STAGE(bufoff, gbase, voff) do { _Pragma("unroll") for (int _i = 0; _i < 2; ++_i) \
;         __builtin_amdgcn_global_load_lds((const unsigned*)((const char*)(gbase) + (voff)[_i]), (LAS unsigned*)(lds + (bufoff) + ldsw + _i * 8192), 16, 0, 0); } while (0)
; #define PG8_LDA(dst, b, h) do { _Pragma("unroll") for (int m = 0; m < 4; ++m) _Pragma("unroll") for (int k = 0; k < 2; ++k) dst[m][k] = *(const LAS bf16x8*)(lds + PG8_SA(b, h) + aoff + m * 2048 + k * 1024); } while (0)
; #define PG8_LDB(dst, b, h) do { _Pragma("unroll") for (int n = 0; n < 2; ++n) _Pragma("unroll") for (int k = 0; k < 2; ++k) dst[n][k] = *(const LAS bf16x8*)(lds + PG8_SB(b, h) + boff + n * 2048 + k * 1024); } while (0)
; #define PG8_MMA(ai, bj, At, Bt) do { __builtin_amdgcn_s_setprio(1); _Pragma("unroll") for (int m = 0; m < 4; ++m) _Pragma("unroll") for (int n = 0; n < 2; ++n) _Pragma("unroll") for (int k = 0; k < 2; ++k) \
;         acc[ai][bj][m][n] = __builtin_amdgcn_mfma_f32_16x16x32_bf16(Bt[n][k], At[m][k], acc[ai][bj][m][n], 0, 0, 0); __builtin_amdgcn_s_setprio(0); } while (0)
; #define PG8_WAIT_V(n) asm volatile("s_waitcnt vmcnt(" #n ")" ::: "memory")
; #define PG8_WAIT_L(n) asm volatile("s_waitcnt lgkmcnt(" #n ")" ::: "memory")
; #define PG8_BAR __builtin_amdgcn_s_barrier()
; #define PG8_SCHED __builtin_amdgcn_sched_barrier(0)
; template <class Epi, class Sched>
; DI void gemm_phase(LAS unsigned char* lds, const Gemm g, const Sched& S, const Epi& E) {
;     ...
;             PG8_WAIT_V(8); PG8_WAIT_L(0); PG8_BAR; PG8_MMA(1, 0, At, B0); PG8_MMA(1, 1, At, B1); PG8_BAR; PG8_SCHED;
;             PG8_LDB(B0, 1, 0); PG8_LDB(B1, 1, 1); PG8_SCHED; PG8_LDA(At, 1, 0); PG8_STAGE(PG8_SA(0, 1), a2 + hstepA, voffA);
;             PG8_WAIT_V(8); PG8_WAIT_L(0); PG8_BAR; PG8_MMA(0, 0, At, B0); PG8_MMA(0, 1, At, B1); PG8_BAR; PG8_SCHED;
	v_mfma_f32_16x16x32_bf16 v[62:65], v[168:171], v[202:205], v[62:65]
	v_mfma_f32_16x16x32_bf16 v[54:57], v[176:179], v[202:205], v[54:57]
	v_mfma_f32_16x16x32_bf16 v[46:49], v[168:171], v[210:213], v[46:49]
	v_mfma_f32_16x16x32_bf16 v[38:41], v[176:179], v[210:213], v[38:41]
	v_mfma_f32_16x16x32_bf16 v[30:33], v[168:171], v[218:221], v[30:33]
	v_mfma_f32_16x16x32_bf16 v[22:25], v[176:179], v[218:221], v[22:25]
	v_mfma_f32_16x16x32_bf16 v[14:17], v[168:171], v[226:229], v[14:17]
	v_mfma_f32_16x16x32_bf16 v[6:9], v[176:179], v[226:229], v[6:9]
	v_mfma_f32_16x16x32_bf16 v[62:65], v[172:175], v[206:209], v[62:65]
	v_mfma_f32_16x16x32_bf16 v[54:57], v[180:183], v[206:209], v[54:57]
	v_mfma_f32_16x16x32_bf16 v[46:49], v[172:175], v[214:217], v[46:49]
	v_mfma_f32_16x16x32_bf16 v[38:41], v[180:183], v[214:217], v[38:41]
	v_mfma_f32_16x16x32_bf16 v[30:33], v[172:175], v[222:225], v[30:33]
	v_mfma_f32_16x16x32_bf16 v[22:25], v[180:183], v[222:225], v[22:25]
	v_mfma_f32_16x16x32_bf16 v[14:17], v[172:175], v[230:233], v[14:17]
	v_mfma_f32_16x16x32_bf16 v[6:9], v[180:183], v[230:233], v[6:9]
	v_mfma_f32_16x16x32_bf16 v[58:61], v[186:189], v[202:205], v[58:61]
	v_mfma_f32_16x16x32_bf16 v[50:53], v[194:197], v[202:205], v[50:53]
	v_mfma_f32_16x16x32_bf16 v[42:45], v[186:189], v[210:213], v[42:45]
	v_mfma_f32_16x16x32_bf16 v[34:37], v[194:197], v[210:213], v[34:37]
	v_mfma_f32_16x16x32_bf16 v[26:29], v[186:189], v[218:221], v[26:29]
	v_mfma_f32_16x16x32_bf16 v[18:21], v[194:197], v[218:221], v[18:21]
	v_mfma_f32_16x16x32_bf16 v[10:13], v[186:189], v[226:229], v[10:13]
	v_mfma_f32_16x16x32_bf16 v[2:5], v[194:197], v[226:229], v[2:5]
	v_mfma_f32_16x16x32_bf16 v[58:61], v[190:193], v[206:209], v[58:61]
	v_mfma_f32_16x16x32_bf16 v[50:53], v[198:201], v[206:209], v[50:53]
	v_mfma_f32_16x16x32_bf16 v[42:45], v[190:193], v[214:217], v[42:45]
	v_mfma_f32_16x16x32_bf16 v[34:37], v[198:201], v[214:217], v[34:37]
	v_mfma_f32_16x16x32_bf16 v[26:29], v[190:193], v[222:225], v[26:29]
	v_mfma_f32_16x16x32_bf16 v[18:21], v[198:201], v[222:225], v[18:21]
	v_mfma_f32_16x16x32_bf16 v[10:13], v[190:193], v[230:233], v[10:13]
	v_mfma_f32_16x16x32_bf16 v[2:5], v[198:201], v[230:233], v[2:5]
	s_barrier
	s_setprio 0
	s_add_i32 s66, 0, 0x18000
	v_add_u32_e32 v167, s66, v158
	s_add_i32 s67, 0, 0x1c000
	ds_read_b128 v[168:171], v167
	ds_read_b128 v[172:175], v167 offset:1024
	ds_read_b128 v[176:179], v167 offset:2048
	ds_read_b128 v[180:183], v167 offset:3072
	v_add_u32_e32 v167, s67, v158
	ds_read_b128 v[186:189], v167
	ds_read_b128 v[190:193], v167 offset:1024
	ds_read_b128 v[194:197], v167 offset:2048
	ds_read_b128 v[198:201], v167 offset:3072
	s_add_u32 s44, s44, 0x40000
	s_addc_u32 s45, s45, 0
	s_mov_b32 m0, s51
	v_lshl_add_u64 v[242:243], s[44:45], 0, v[136:137]
	ds_read_b128 v[202:205], v160 offset:32768
	ds_read_b128 v[206:209], v160 offset:33792
	ds_read_b128 v[210:213], v160 offset:34816
	ds_read_b128 v[214:217], v160 offset:35840
	ds_read_b128 v[218:221], v160 offset:36864
	ds_read_b128 v[222:225], v160 offset:37888
	ds_read_b128 v[226:229], v160 offset:38912
	ds_read_b128 v[230:233], v160 offset:39936
	global_load_lds_dwordx4 v[242:243], off
	v_lshl_add_u64 v[242:243], s[44:45], 0, v[132:133]
	s_mov_b32 m0, s52
	s_nop 0
	global_load_lds_dwordx4 v[242:243], off
	s_waitcnt vmcnt(8)
	s_waitcnt lgkmcnt(0)
	s_setprio 1
	s_barrier
	v_mfma_f32_16x16x32_bf16 v[126:129], v[168:171], v[202:205], v[126:129]
	v_mfma_f32_16x16x32_bf16 v[118:121], v[176:179], v[202:205], v[118:121]
	v_mfma_f32_16x16x32_bf16 v[110:113], v[168:171], v[210:213], v[110:113]
	v_mfma_f32_16x16x32_bf16 v[102:105], v[176:179], v[210:213], v[102:105]
	v_mfma_f32_16x16x32_bf16 v[94:97], v[168:171], v[218:221], v[94:97]
	v_mfma_f32_16x16x32_bf16 v[86:89], v[176:179], v[218:221], v[86:89]
	v_mfma_f32_16x16x32_bf16 v[78:81], v[168:171], v[226:229], v[78:81]
	v_mfma_f32_16x16x32_bf16 v[70:73], v[176:179], v[226:229], v[70:73]
	v_mfma_f32_16x16x32_bf16 v[126:129], v[172:175], v[206:209], v[126:129]
	v_mfma_f32_16x16x32_bf16 v[118:121], v[180:183], v[206:209], v[118:121]
	v_mfma_f32_16x16x32_bf16 v[110:113], v[172:175], v[214:217], v[110:113]
	v_mfma_f32_16x16x32_bf16 v[102:105], v[180:183], v[214:217], v[102:105]
	v_mfma_f32_16x16x32_bf16 v[94:97], v[172:175], v[222:225], v[94:97]
	v_mfma_f32_16x16x32_bf16 v[86:89], v[180:183], v[222:225], v[86:89]
	v_mfma_f32_16x16x32_bf16 v[78:81], v[172:175], v[230:233], v[78:81]
	v_mfma_f32_16x16x32_bf16 v[70:73], v[180:183], v[230:233], v[70:73]
	v_mfma_f32_16x16x32_bf16 v[122:125], v[186:189], v[202:205], v[122:125]
	v_mfma_f32_16x16x32_bf16 v[114:117], v[194:197], v[202:205], v[114:117]
	v_mfma_f32_16x16x32_bf16 v[106:109], v[186:189], v[210:213], v[106:109]
	v_mfma_f32_16x16x32_bf16 v[98:101], v[194:197], v[210:213], v[98:101]
	v_mfma_f32_16x16x32_bf16 v[90:93], v[186:189], v[218:221], v[90:93]
	v_mfma_f32_16x16x32_bf16 v[82:85], v[194:197], v[218:221], v[82:85]
	v_mfma_f32_16x16x32_bf16 v[74:77], v[186:189], v[226:229], v[74:77]
	v_mfma_f32_16x16x32_bf16 v[66:69], v[194:197], v[226:229], v[66:69]
	v_mfma_f32_16x16x32_bf16 v[122:125], v[190:193], v[206:209], v[122:125]
	v_mfma_f32_16x16x32_bf16 v[114:117], v[198:201], v[206:209], v[114:117]
	v_mfma_f32_16x16x32_bf16 v[106:109], v[190:193], v[214:217], v[106:109]
	v_mfma_f32_16x16x32_bf16 v[98:101], v[198:201], v[214:217], v[98:101]
	v_mfma_f32_16x16x32_bf16 v[90:93], v[190:193], v[222:225], v[90:93]
	v_mfma_f32_16x16x32_bf16 v[82:85], v[198:201], v[222:225], v[82:85]
	v_mfma_f32_16x16x32_bf16 v[74:77], v[190:193], v[230:233], v[74:77]
	v_mfma_f32_16x16x32_bf16 v[66:69], v[198:201], v[230:233], v[66:69]
	s_barrier
; #define PG8_STAGE(bufoff, gbase, voff) do { _Pragma("unroll") for (int _i = 0; _i < 2; ++_i) \
;         __builtin_amdgcn_global_load_lds((const unsigned*)((const char*)(gbase) + (voff)[_i]), (LAS unsigned*)(lds + (bufoff) + ldsw + _i * 8192), 16, 0, 0); } while (0)
; #define PG8_LDA(dst, b, h) do { _Pragma("unroll") for (int m = 0; m < 4; ++m) _Pragma("unroll") for (int k = 0; k < 2; ++k) dst[m][k] = *(const LAS bf16x8*)(lds + PG8_SA(b, h) + aoff + m * 2048 + k * 1024); } while (0)
; #define PG8_MMA(ai, bj, At, Bt) do { __builtin_amdgcn_s_setprio(1); _Pragma("unroll") for (int m = 0; m < 4; ++m) _Pragma("unroll") for (int n = 0; n < 2; ++n) _Pragma("unroll") for (int k = 0; k < 2; ++k) \
;         acc[ai][bj][m][n] = __builtin_amdgcn_mfma_f32_16x16x32_bf16(Bt[n][k], At[m][k], acc[ai][bj][m][n], 0, 0, 0); __builtin_amdgcn_s_setprio(0); } while (0)
; #define PG8_WAIT_V(n) asm volatile("s_waitcnt vmcnt(" #n ")" ::: "memory")
; #define PG8_WAIT_L(n) asm volatile("s_waitcnt lgkmcnt(" #n ")" ::: "memory")
; #define PG8_BAR __builtin_amdgcn_s_barrier()
; #define PG8_SCHED __builtin_amdgcn_sched_barrier(0)
; template <class Epi, class Sched>
; DI void gemm_phase(LAS unsigned char* lds, const Gemm g, const Sched& S, const Epi& E) {
;     ...
;             PG8_LDA(At, 1, 1); PG8_STAGE(PG8_SB(1, 0), b3, voffB); PG8_STAGE(PG8_SB(1, 1), b3 + hstepB, voffB); PG8_STAGE(PG8_SA(1, 0), a3, voffA);
;             PG8_WAIT_V(8); PG8_WAIT_L(0); PG8_BAR; PG8_MMA(1, 0, At, B0); PG8_MMA(1, 1, At, B1); PG8_BAR; PG8_SCHED;
;         }
;         if (wr == 0) PG8_BAR;
	s_setprio 0
	s_add_i32 s44, s66, s46
	v_lshl_add_u64 v[234:235], v[234:235], 0, s[16:17]
	s_mov_b32 m0, s44
	ds_read_b128 v[202:205], v160 offset:49152
	ds_read_b128 v[206:209], v160 offset:50176
	ds_read_b128 v[210:213], v160 offset:51200
	ds_read_b128 v[214:217], v160 offset:52224
	ds_read_b128 v[218:221], v160 offset:53248
	ds_read_b128 v[222:225], v160 offset:54272
	ds_read_b128 v[226:229], v160 offset:55296
	ds_read_b128 v[230:233], v160 offset:56320
	global_load_lds_dwordx4 v[234:235], off
	s_add_i32 m0, s44, 0x2000
	s_add_u32 s42, s42, 0x40080
	v_lshl_add_u64 v[234:235], v[236:237], 0, s[16:17]
	s_addc_u32 s43, s43, 0
	s_add_i32 s44, s67, s46
	global_load_lds_dwordx4 v[234:235], off
	v_lshl_add_u64 v[234:235], s[42:43], 0, v[134:135]
	s_mov_b32 m0, s44
	s_nop 0
	global_load_lds_dwordx4 v[234:235], off
	v_lshl_add_u64 v[234:235], s[42:43], 0, v[130:131]
	s_add_i32 m0, s44, 0x2000
	s_nop 0
	global_load_lds_dwordx4 v[234:235], off
	v_lshl_add_u64 v[234:235], v[238:239], 0, s[16:17]
	s_mov_b32 m0, s54
	s_nop 0
	global_load_lds_dwordx4 v[234:235], off
	v_lshl_add_u64 v[234:235], v[240:241], 0, s[16:17]
	s_mov_b32 m0, s55
	s_nop 0
	global_load_lds_dwordx4 v[234:235], off
	s_waitcnt vmcnt(8)
	s_waitcnt lgkmcnt(0)
	s_setprio 1
	s_barrier
	v_mfma_f32_16x16x32_bf16 v[62:65], v[168:171], v[202:205], v[62:65]
	v_mfma_f32_16x16x32_bf16 v[54:57], v[176:179], v[202:205], v[54:57]
	v_mfma_f32_16x16x32_bf16 v[46:49], v[168:171], v[210:213], v[46:49]
	v_mfma_f32_16x16x32_bf16 v[38:41], v[176:179], v[210:213], v[38:41]
	v_mfma_f32_16x16x32_bf16 v[30:33], v[168:171], v[218:221], v[30:33]
	v_mfma_f32_16x16x32_bf16 v[22:25], v[176:179], v[218:221], v[22:25]
	v_mfma_f32_16x16x32_bf16 v[14:17], v[168:171], v[226:229], v[14:17]
	v_mfma_f32_16x16x32_bf16 v[6:9], v[176:179], v[226:229], v[6:9]
	v_mfma_f32_16x16x32_bf16 v[62:65], v[172:175], v[206:209], v[62:65]
	v_mfma_f32_16x16x32_bf16 v[54:57], v[180:183], v[206:209], v[54:57]
	v_mfma_f32_16x16x32_bf16 v[46:49], v[172:175], v[214:217], v[46:49]
	v_mfma_f32_16x16x32_bf16 v[38:41], v[180:183], v[214:217], v[38:41]
	v_mfma_f32_16x16x32_bf16 v[30:33], v[172:175], v[222:225], v[30:33]
	v_mfma_f32_16x16x32_bf16 v[22:25], v[180:183], v[222:225], v[22:25]
	v_mfma_f32_16x16x32_bf16 v[14:17], v[172:175], v[230:233], v[14:17]
	v_mfma_f32_16x16x32_bf16 v[6:9], v[180:183], v[230:233], v[6:9]
	v_mfma_f32_16x16x32_bf16 v[58:61], v[186:189], v[202:205], v[58:61]
	v_mfma_f32_16x16x32_bf16 v[50:53], v[194:197], v[202:205], v[50:53]
	v_mfma_f32_16x16x32_bf16 v[42:45], v[186:189], v[210:213], v[42:45]
	v_mfma_f32_16x16x32_bf16 v[34:37], v[194:197], v[210:213], v[34:37]
	v_mfma_f32_16x16x32_bf16 v[26:29], v[186:189], v[218:221], v[26:29]
	v_mfma_f32_16x16x32_bf16 v[18:21], v[194:197], v[218:221], v[18:21]
	v_mfma_f32_16x16x32_bf16 v[10:13], v[186:189], v[226:229], v[10:13]
	v_mfma_f32_16x16x32_bf16 v[2:5], v[194:197], v[226:229], v[2:5]
	v_mfma_f32_16x16x32_bf16 v[58:61], v[190:193], v[206:209], v[58:61]
	v_mfma_f32_16x16x32_bf16 v[50:53], v[198:201], v[206:209], v[50:53]
	v_mfma_f32_16x16x32_bf16 v[42:45], v[190:193], v[214:217], v[42:45]
	v_mfma_f32_16x16x32_bf16 v[34:37], v[198:201], v[214:217], v[34:37]
	v_mfma_f32_16x16x32_bf16 v[26:29], v[190:193], v[222:225], v[26:29]
	v_mfma_f32_16x16x32_bf16 v[18:21], v[198:201], v[222:225], v[18:21]
	v_mfma_f32_16x16x32_bf16 v[10:13], v[190:193], v[230:233], v[10:13]
	v_mfma_f32_16x16x32_bf16 v[2:5], v[198:201], v[230:233], v[2:5]
	s_barrier
	s_setprio 0
	s_add_i32 s65, s65, 2
	s_add_u32 s40, s40, 0x100
	s_addc_u32 s41, s41, 0
	s_add_u32 s63, s63, 0x100
	s_addc_u32 s64, s64, 0
	s_cmp_gt_u32 s65, 13
	s_cbranch_scc0 .LBB0_179
	s_and_b64 vcc, exec, s[18:19]
	s_cbranch_vccz .LBB0_182
	s_barrier

; #define PG8_STAGE(bufoff, gbase, voff) do { _Pragma("unroll") for (int _i = 0; _i < 2; ++_i) \
;         __builtin_amdgcn_global_load_lds((const unsigned*)((const char*)(gbase) + (voff)[_i]), (LAS unsigned*)(lds + (bufoff) + ldsw + _i * 8192), 16, 0, 0); } while (0)
; #define PG8_LDA(dst, b, h) do { _Pragma("unroll") for (int m = 0; m < 4; ++m) _Pragma("unroll") for (int k = 0; k < 2; ++k) dst[m][k] = *(const LAS bf16x8*)(lds + PG8_SA(b, h) + aoff + m * 2048 + k * 1024); } while (0)
; #define PG8_LDB(dst, b, h) do { _Pragma("unroll") for (int n = 0; n < 2; ++n) _Pragma("unroll") for (int k = 0; k < 2; ++k) dst[n][k] = *(const LAS bf16x8*)(lds + PG8_SB(b, h) + boff + n * 2048 + k * 1024); } while (0)
; #define PG8_MMA(ai, bj, At, Bt) do { __builtin_amdgcn_s_setprio(1); _Pragma("unroll") for (int m = 0; m < 4; ++m) _Pragma("unroll") for (int n = 0; n < 2; ++n) _Pragma("unroll") for (int k = 0; k < 2; ++k) \
;         acc[ai][bj][m][n] = __builtin_amdgcn_mfma_f32_16x16x32_bf16(Bt[n][k], At[m][k], acc[ai][bj][m][n], 0, 0, 0); __builtin_amdgcn_s_setprio(0); } while (0)
; #define PG8_WAIT_V(n) asm volatile("s_waitcnt vmcnt(" #n ")" ::: "memory")
; #define PG8_WAIT_L(n) asm volatile("s_waitcnt lgkmcnt(" #n ")" ::: "memory")
; #define PG8_BAR __builtin_amdgcn_s_barrier()
; #define PG8_SCHED __builtin_amdgcn_sched_barrier(0)
; template <class Epi, class Sched>
; DI void gemm_phase(LAS unsigned char* lds, const Gemm g, const Sched& S, const Epi& E) {
;     ...
;         for (int t = 0; t < nt; t += 2) {
;             const bool last = (t == nt - 2);
;             const char* a1 = cA + (size_t)(t + 1) * kstep;
;             const char* a2 = last ? nA : cA + (size_t)(t + 2) * kstep; const char* b2 = last ? nB : cB + (size_t)(t + 2) * kstep;
;             const char* a3 = a2 + kstep; const char* b3 = b2 + kstep;
;             PG8_LDB(B0, 0, 0); PG8_LDB(B1, 0, 1); PG8_SCHED; PG8_LDA(At, 0, 0); PG8_STAGE(PG8_SA(1, 1), a1 + hstepA, voffA);
;             PG8_WAIT_V(8); PG8_WAIT_L(0); PG8_BAR; PG8_MMA(0, 0, At, B0); PG8_MMA(0, 1, At, B1); PG8_BAR; PG8_SCHED;
.LBB0_278:
	ds_read_b128 v[148:151], v154
	ds_read_b128 v[158:161], v154 offset:1024
	ds_read_b128 v[162:165], v154 offset:2048
	ds_read_b128 v[166:169], v154 offset:3072
	ds_read_b128 v[170:173], v155
	ds_read_b128 v[174:177], v155 offset:1024
	ds_read_b128 v[178:181], v155 offset:2048
	ds_read_b128 v[186:189], v155 offset:3072
	s_add_u32 s38, s36, 0xfff50080
	s_addc_u32 s39, s37, -1
	s_cmp_eq_u32 s62, 40
	s_cselect_b32 s41, s9, s39
	s_cselect_b32 s40, s8, s38
	s_cselect_b32 s39, s35, s61
	s_cselect_b32 s38, s34, s60
	v_lshl_add_u64 v[182:183], s[36:37], 0, v[138:139]
	s_add_i32 m0, s45, 0xc000
	ds_read_b128 v[190:193], v156
	ds_read_b128 v[194:197], v156 offset:1024
	ds_read_b128 v[198:201], v156 offset:2048
	ds_read_b128 v[202:205], v156 offset:3072
	ds_read_b128 v[206:209], v156 offset:4096
	ds_read_b128 v[210:213], v156 offset:5120
	ds_read_b128 v[214:217], v156 offset:6144
	ds_read_b128 v[218:221], v156 offset:7168
	global_load_lds_dwordx4 v[182:183], off
	v_lshl_add_u64 v[182:183], s[36:37], 0, v[140:141]
	s_add_i32 m0, s45, 0xe000
	s_nop 0
	global_load_lds_dwordx4 v[182:183], off
	s_waitcnt vmcnt(8)
	s_waitcnt lgkmcnt(0)
	s_setprio 1
	s_barrier
	v_mfma_f32_16x16x32_bf16 v[126:129], v[148:151], v[190:193], v[126:129]
	v_mfma_f32_16x16x32_bf16 v[122:125], v[162:165], v[190:193], v[122:125]
	v_mfma_f32_16x16x32_bf16 v[110:113], v[148:151], v[198:201], v[110:113]
	v_mfma_f32_16x16x32_bf16 v[106:109], v[162:165], v[198:201], v[106:109]
	v_mfma_f32_16x16x32_bf16 v[94:97], v[148:151], v[206:209], v[94:97]
	v_mfma_f32_16x16x32_bf16 v[90:93], v[162:165], v[206:209], v[90:93]
	v_mfma_f32_16x16x32_bf16 v[78:81], v[148:151], v[214:217], v[78:81]
	v_mfma_f32_16x16x32_bf16 v[74:77], v[162:165], v[214:217], v[74:77]
	v_mfma_f32_16x16x32_bf16 v[126:129], v[158:161], v[194:197], v[126:129]
	v_mfma_f32_16x16x32_bf16 v[122:125], v[166:169], v[194:197], v[122:125]
	v_mfma_f32_16x16x32_bf16 v[110:113], v[158:161], v[202:205], v[110:113]
	v_mfma_f32_16x16x32_bf16 v[106:109], v[166:169], v[202:205], v[106:109]
	v_mfma_f32_16x16x32_bf16 v[94:97], v[158:161], v[210:213], v[94:97]
	v_mfma_f32_16x16x32_bf16 v[90:93], v[166:169], v[210:213], v[90:93]
	v_mfma_f32_16x16x32_bf16 v[78:81], v[158:161], v[218:221], v[78:81]
	v_mfma_f32_16x16x32_bf16 v[74:77], v[166:169], v[218:221], v[74:77]
	v_mfma_f32_16x16x32_bf16 v[118:121], v[170:173], v[190:193], v[118:121]
	v_mfma_f32_16x16x32_bf16 v[114:117], v[178:181], v[190:193], v[114:117]
	v_mfma_f32_16x16x32_bf16 v[102:105], v[170:173], v[198:201], v[102:105]
	v_mfma_f32_16x16x32_bf16 v[98:101], v[178:181], v[198:201], v[98:101]
	v_mfma_f32_16x16x32_bf16 v[86:89], v[170:173], v[206:209], v[86:89]
	v_mfma_f32_16x16x32_bf16 v[82:85], v[178:181], v[206:209], v[82:85]
	v_mfma_f32_16x16x32_bf16 v[70:73], v[170:173], v[214:217], v[70:73]
	v_mfma_f32_16x16x32_bf16 v[66:69], v[178:181], v[214:217], v[66:69]
	v_mfma_f32_16x16x32_bf16 v[118:121], v[174:177], v[194:197], v[118:121]
	v_mfma_f32_16x16x32_bf16 v[114:117], v[186:189], v[194:197], v[114:117]
	v_mfma_f32_16x16x32_bf16 v[102:105], v[174:177], v[202:205], v[102:105]
	v_mfma_f32_16x16x32_bf16 v[98:101], v[186:189], v[202:205], v[98:101]
	v_mfma_f32_16x16x32_bf16 v[86:89], v[174:177], v[210:213], v[86:89]
	v_mfma_f32_16x16x32_bf16 v[82:85], v[186:189], v[210:213], v[82:85]
	v_mfma_f32_16x16x32_bf16 v[70:73], v[174:177], v[218:221], v[70:73]
	v_mfma_f32_16x16x32_bf16 v[66:69], v[186:189], v[218:221], v[66:69]
	s_barrier
	s_setprio 0
	s_add_i32 s63, s54, s44
	v_lshl_add_u64 v[182:183], s[38:39], 0, v[132:133]
	s_mov_b32 m0, s63
	ds_read_b128 v[190:193], v156 offset:16384
	ds_read_b128 v[194:197], v156 offset:17408
	ds_read_b128 v[198:201], v156 offset:18432
	ds_read_b128 v[202:205], v156 offset:19456
	ds_read_b128 v[206:209], v156 offset:20480
	ds_read_b128 v[210:213], v156 offset:21504
	ds_read_b128 v[214:217], v156 offset:22528
	ds_read_b128 v[218:221], v156 offset:23552
	global_load_lds_dwordx4 v[182:183], off
	s_add_i32 m0, s63, 0x2000
	s_add_u32 s64, s38, 0xb0000
	v_lshl_add_u64 v[222:223], s[38:39], 0, v[136:137]
	s_addc_u32 s65, s39, 0
	s_add_i32 s63, s55, s44
	global_load_lds_dwordx4 v[222:223], off
	v_lshl_add_u64 v[224:225], s[64:65], 0, v[132:133]
	s_mov_b32 m0, s63
	v_lshl_add_u64 v[226:227], s[40:41], 0, v[134:135]
	global_load_lds_dwordx4 v[224:225], off
	v_lshl_add_u64 v[224:225], s[64:65], 0, v[136:137]
	s_add_i32 m0, s63, 0x2000
	s_nop 0
	global_load_lds_dwordx4 v[224:225], off
	v_lshl_add_u64 v[224:225], s[40:41], 0, v[130:131]
	s_mov_b32 m0, s45
	s_nop 0
	global_load_lds_dwordx4 v[224:225], off
	s_mov_b32 m0, s46
	s_nop 0
	global_load_lds_dwordx4 v[226:227], off
	s_waitcnt vmcnt(8)
	s_waitcnt lgkmcnt(0)
	s_setprio 1
	s_barrier
; #define PG8_STAGE(bufoff, gbase, voff) do { _Pragma("unroll") for (int _i = 0; _i < 2; ++_i) \
;         __builtin_amdgcn_global_load_lds((const unsigned*)((const char*)(gbase) + (voff)[_i]), (LAS unsigned*)(lds + (bufoff) + ldsw + _i * 8192), 16, 0, 0); } while (0)
; #define PG8_LDA(dst, b, h) do { _Pragma("unroll") for (int m = 0; m < 4; ++m) _Pragma("unroll") for (int k = 0; k < 2; ++k) dst[m][k] = *(const LAS bf16x8*)(lds + PG8_SA(b, h) + aoff + m * 2048 + k * 1024); } while (0)
; #define PG8_LDB(dst, b, h) do { _Pragma("unroll") for (int n = 0; n < 2; ++n) _Pragma("unroll") for (int k = 0; k < 2; ++k) dst[n][k] = *(const LAS bf16x8*)(lds + PG8_SB(b, h) + boff + n * 2048 + k * 1024); } while (0)
; #define PG8_MMA(ai, bj, At, Bt) do { __builtin_amdgcn_s_setprio(1); _Pragma("unroll") for (int m = 0; m < 4; ++m) _Pragma("unroll") for (int n = 0; n < 2; ++n) _Pragma("unroll") for (int k = 0; k < 2; ++k) \
;         acc[ai][bj][m][n] = __builtin_amdgcn_mfma_f32_16x16x32_bf16(Bt[n][k], At[m][k], acc[ai][bj][m][n], 0, 0, 0); __builtin_amdgcn_s_setprio(0); } while (0)
; #define PG8_WAIT_V(n) asm volatile("s_waitcnt vmcnt(" #n ")" ::: "memory")
; #define PG8_WAIT_L(n) asm volatile("s_waitcnt lgkmcnt(" #n ")" ::: "memory")
; #define PG8_BAR __builtin_amdgcn_s_barrier()
; #define PG8_SCHED __builtin_amdgcn_sched_barrier(0)
; template <class Epi, class Sched>
; DI void gemm_phase(LAS unsigned char* lds, const Gemm g, const Sched& S, const Epi& E) {
;     ...
;             PG8_WAIT_V(8); PG8_WAIT_L(0); PG8_BAR; PG8_MMA(0, 0, At, B0); PG8_MMA(0, 1, At, B1); PG8_BAR; PG8_SCHED;
;             PG8_LDA(At, 0, 1); PG8_STAGE(PG8_SB(0, 0), b2, voffB); PG8_STAGE(PG8_SB(0, 1), b2 + hstepB, voffB); PG8_STAGE(PG8_SA(0, 0), a2, voffA);
;             PG8_WAIT_V(8); PG8_WAIT_L(0); PG8_BAR; PG8_MMA(1, 0, At, B0); PG8_MMA(1, 1, At, B1); PG8_BAR; PG8_SCHED;
;             PG8_LDB(B0, 1, 0); PG8_LDB(B1, 1, 1); PG8_SCHED; PG8_LDA(At, 1, 0); PG8_STAGE(PG8_SA(0, 1), a2 + hstepA, voffA);
;             PG8_WAIT_V(8); PG8_WAIT_L(0); PG8_BAR; PG8_MMA(0, 0, At, B0); PG8_MMA(0, 1, At, B1); PG8_BAR; PG8_SCHED;
	v_mfma_f32_16x16x32_bf16 v[62:65], v[148:151], v[190:193], v[62:65]
	v_mfma_f32_16x16x32_bf16 v[58:61], v[162:165], v[190:193], v[58:61]
	v_mfma_f32_16x16x32_bf16 v[46:49], v[148:151], v[198:201], v[46:49]
	v_mfma_f32_16x16x32_bf16 v[42:45], v[162:165], v[198:201], v[42:45]
	v_mfma_f32_16x16x32_bf16 v[30:33], v[148:151], v[206:209], v[30:33]
	v_mfma_f32_16x16x32_bf16 v[26:29], v[162:165], v[206:209], v[26:29]
	v_mfma_f32_16x16x32_bf16 v[14:17], v[148:151], v[214:217], v[14:17]
	v_mfma_f32_16x16x32_bf16 v[10:13], v[162:165], v[214:217], v[10:13]
	v_mfma_f32_16x16x32_bf16 v[62:65], v[158:161], v[194:197], v[62:65]
	v_mfma_f32_16x16x32_bf16 v[58:61], v[166:169], v[194:197], v[58:61]
	v_mfma_f32_16x16x32_bf16 v[46:49], v[158:161], v[202:205], v[46:49]
	v_mfma_f32_16x16x32_bf16 v[42:45], v[166:169], v[202:205], v[42:45]
	v_mfma_f32_16x16x32_bf16 v[30:33], v[158:161], v[210:213], v[30:33]
	v_mfma_f32_16x16x32_bf16 v[26:29], v[166:169], v[210:213], v[26:29]
	v_mfma_f32_16x16x32_bf16 v[14:17], v[158:161], v[218:221], v[14:17]
	v_mfma_f32_16x16x32_bf16 v[10:13], v[166:169], v[218:221], v[10:13]
	v_mfma_f32_16x16x32_bf16 v[54:57], v[170:173], v[190:193], v[54:57]
	v_mfma_f32_16x16x32_bf16 v[50:53], v[178:181], v[190:193], v[50:53]
	v_mfma_f32_16x16x32_bf16 v[38:41], v[170:173], v[198:201], v[38:41]
	v_mfma_f32_16x16x32_bf16 v[34:37], v[178:181], v[198:201], v[34:37]
	v_mfma_f32_16x16x32_bf16 v[22:25], v[170:173], v[206:209], v[22:25]
	v_mfma_f32_16x16x32_bf16 v[18:21], v[178:181], v[206:209], v[18:21]
	v_mfma_f32_16x16x32_bf16 v[6:9], v[170:173], v[214:217], v[6:9]
	v_mfma_f32_16x16x32_bf16 v[2:5], v[178:181], v[214:217], v[2:5]
	v_mfma_f32_16x16x32_bf16 v[54:57], v[174:177], v[194:197], v[54:57]
	v_mfma_f32_16x16x32_bf16 v[50:53], v[186:189], v[194:197], v[50:53]
	v_mfma_f32_16x16x32_bf16 v[38:41], v[174:177], v[202:205], v[38:41]
	v_mfma_f32_16x16x32_bf16 v[34:37], v[186:189], v[202:205], v[34:37]
	v_mfma_f32_16x16x32_bf16 v[22:25], v[174:177], v[210:213], v[22:25]
	v_mfma_f32_16x16x32_bf16 v[18:21], v[186:189], v[210:213], v[18:21]
	v_mfma_f32_16x16x32_bf16 v[6:9], v[174:177], v[218:221], v[6:9]
	v_mfma_f32_16x16x32_bf16 v[2:5], v[186:189], v[218:221], v[2:5]
	s_barrier
	s_setprio 0
	s_add_i32 s63, 0, 0x18000
	s_add_i32 s64, 0, 0x1c000
	v_add_u32_e32 v166, s63, v152
	v_add_u32_e32 v185, s64, v152
	ds_read_b128 v[148:151], v166
	ds_read_b128 v[158:161], v166 offset:1024
	ds_read_b128 v[162:165], v166 offset:2048
	ds_read_b128 v[166:169], v166 offset:3072
	ds_read_b128 v[170:173], v185
	ds_read_b128 v[174:177], v185 offset:1024
	ds_read_b128 v[178:181], v185 offset:2048
	ds_read_b128 v[186:189], v185 offset:3072
	s_add_u32 s40, s40, 0xb0000
	s_addc_u32 s41, s41, 0
	s_mov_b32 m0, s47
	v_lshl_add_u64 v[228:229], s[40:41], 0, v[130:131]
	ds_read_b128 v[190:193], v156 offset:32768
	ds_read_b128 v[194:197], v156 offset:33792
	ds_read_b128 v[198:201], v156 offset:34816
	ds_read_b128 v[202:205], v156 offset:35840
	ds_read_b128 v[206:209], v156 offset:36864
	ds_read_b128 v[210:213], v156 offset:37888
	ds_read_b128 v[214:217], v156 offset:38912
	ds_read_b128 v[218:221], v156 offset:39936
	global_load_lds_dwordx4 v[228:229], off
	v_lshl_add_u64 v[228:229], s[40:41], 0, v[134:135]
	s_mov_b32 m0, s48
	s_nop 0
	global_load_lds_dwordx4 v[228:229], off
	s_waitcnt vmcnt(8)
	s_waitcnt lgkmcnt(0)
	s_setprio 1
	s_barrier
	v_mfma_f32_16x16x32_bf16 v[126:129], v[148:151], v[190:193], v[126:129]
	v_mfma_f32_16x16x32_bf16 v[122:125], v[162:165], v[190:193], v[122:125]
	v_mfma_f32_16x16x32_bf16 v[110:113], v[148:151], v[198:201], v[110:113]
	v_mfma_f32_16x16x32_bf16 v[106:109], v[162:165], v[198:201], v[106:109]
	v_mfma_f32_16x16x32_bf16 v[94:97], v[148:151], v[206:209], v[94:97]
	v_mfma_f32_16x16x32_bf16 v[90:93], v[162:165], v[206:209], v[90:93]
	v_mfma_f32_16x16x32_bf16 v[78:81], v[148:151], v[214:217], v[78:81]
	v_mfma_f32_16x16x32_bf16 v[74:77], v[162:165], v[214:217], v[74:77]
	v_mfma_f32_16x16x32_bf16 v[126:129], v[158:161], v[194:197], v[126:129]
	v_mfma_f32_16x16x32_bf16 v[122:125], v[166:169], v[194:197], v[122:125]
	v_mfma_f32_16x16x32_bf16 v[110:113], v[158:161], v[202:205], v[110:113]
	v_mfma_f32_16x16x32_bf16 v[106:109], v[166:169], v[202:205], v[106:109]
	v_mfma_f32_16x16x32_bf16 v[94:97], v[158:161], v[210:213], v[94:97]
	v_mfma_f32_16x16x32_bf16 v[90:93], v[166:169], v[210:213], v[90:93]
	v_mfma_f32_16x16x32_bf16 v[78:81], v[158:161], v[218:221], v[78:81]
	v_mfma_f32_16x16x32_bf16 v[74:77], v[166:169], v[218:221], v[74:77]
	v_mfma_f32_16x16x32_bf16 v[118:121], v[170:173], v[190:193], v[118:121]
	v_mfma_f32_16x16x32_bf16 v[114:117], v[178:181], v[190:193], v[114:117]
	v_mfma_f32_16x16x32_bf16 v[102:105], v[170:173], v[198:201], v[102:105]
	v_mfma_f32_16x16x32_bf16 v[98:101], v[178:181], v[198:201], v[98:101]
	v_mfma_f32_16x16x32_bf16 v[86:89], v[170:173], v[206:209], v[86:89]
	v_mfma_f32_16x16x32_bf16 v[82:85], v[178:181], v[206:209], v[82:85]
	v_mfma_f32_16x16x32_bf16 v[70:73], v[170:173], v[214:217], v[70:73]
	v_mfma_f32_16x16x32_bf16 v[66:69], v[178:181], v[214:217], v[66:69]
	v_mfma_f32_16x16x32_bf16 v[118:121], v[174:177], v[194:197], v[118:121]
	v_mfma_f32_16x16x32_bf16 v[114:117], v[186:189], v[194:197], v[114:117]
	v_mfma_f32_16x16x32_bf16 v[102:105], v[174:177], v[202:205], v[102:105]
	v_mfma_f32_16x16x32_bf16 v[98:101], v[186:189], v[202:205], v[98:101]
	v_mfma_f32_16x16x32_bf16 v[86:89], v[174:177], v[210:213], v[86:89]
	v_mfma_f32_16x16x32_bf16 v[82:85], v[186:189], v[210:213], v[82:85]
	v_mfma_f32_16x16x32_bf16 v[70:73], v[174:177], v[218:221], v[70:73]
	v_mfma_f32_16x16x32_bf16 v[66:69], v[186:189], v[218:221], v[66:69]
	s_barrier
; #define PG8_STAGE(bufoff, gbase, voff) do { _Pragma("unroll") for (int _i = 0; _i < 2; ++_i) \
;         __builtin_amdgcn_global_load_lds((const unsigned*)((const char*)(gbase) + (voff)[_i]), (LAS unsigned*)(lds + (bufoff) + ldsw + _i * 8192), 16, 0, 0); } while (0)
; #define PG8_LDA(dst, b, h) do { _Pragma("unroll") for (int m = 0; m < 4; ++m) _Pragma("unroll") for (int k = 0; k < 2; ++k) dst[m][k] = *(const LAS bf16x8*)(lds + PG8_SA(b, h) + aoff + m * 2048 + k * 1024); } while (0)
; #define PG8_MMA(ai, bj, At, Bt) do { __builtin_amdgcn_s_setprio(1); _Pragma("unroll") for (int m = 0; m < 4; ++m) _Pragma("unroll") for (int n = 0; n < 2; ++n) _Pragma("unroll") for (int k = 0; k < 2; ++k) \
;         acc[ai][bj][m][n] = __builtin_amdgcn_mfma_f32_16x16x32_bf16(Bt[n][k], At[m][k], acc[ai][bj][m][n], 0, 0, 0); __builtin_amdgcn_s_setprio(0); } while (0)
; #define PG8_WAIT_V(n) asm volatile("s_waitcnt vmcnt(" #n ")" ::: "memory")
; #define PG8_WAIT_L(n) asm volatile("s_waitcnt lgkmcnt(" #n ")" ::: "memory")
; #define PG8_BAR __builtin_amdgcn_s_barrier()
; #define PG8_SCHED __builtin_amdgcn_sched_barrier(0)
; template <class Epi, class Sched>
; DI void gemm_phase(LAS unsigned char* lds, const Gemm g, const Sched& S, const Epi& E) {
;     ...
;             PG8_LDA(At, 1, 1); PG8_STAGE(PG8_SB(1, 0), b3, voffB); PG8_STAGE(PG8_SB(1, 1), b3 + hstepB, voffB); PG8_STAGE(PG8_SA(1, 0), a3, voffA);
;             PG8_WAIT_V(8); PG8_WAIT_L(0); PG8_BAR; PG8_MMA(1, 0, At, B0); PG8_MMA(1, 1, At, B1); PG8_BAR; PG8_SCHED;
;         }
;         if (wr == 0) PG8_BAR;
	s_setprio 0
	s_add_i32 s40, s63, s44
	v_lshl_add_u64 v[182:183], v[182:183], 0, s[16:17]
	s_mov_b32 m0, s40
	ds_read_b128 v[190:193], v156 offset:49152
	ds_read_b128 v[194:197], v156 offset:50176
	ds_read_b128 v[198:201], v156 offset:51200
	ds_read_b128 v[202:205], v156 offset:52224
	ds_read_b128 v[206:209], v156 offset:53248
	ds_read_b128 v[210:213], v156 offset:54272
	ds_read_b128 v[214:217], v156 offset:55296
	ds_read_b128 v[218:221], v156 offset:56320
	global_load_lds_dwordx4 v[182:183], off
	s_add_i32 m0, s40, 0x2000
	s_add_u32 s38, s38, 0xb0080
	v_lshl_add_u64 v[182:183], v[222:223], 0, s[16:17]
	s_addc_u32 s39, s39, 0
	s_add_i32 s40, s64, s44
	global_load_lds_dwordx4 v[182:183], off
	v_lshl_add_u64 v[182:183], s[38:39], 0, v[132:133]
	s_mov_b32 m0, s40
	s_nop 0
	global_load_lds_dwordx4 v[182:183], off
	v_lshl_add_u64 v[182:183], s[38:39], 0, v[136:137]
	s_add_i32 m0, s40, 0x2000
	s_nop 0
	global_load_lds_dwordx4 v[182:183], off
	v_lshl_add_u64 v[182:183], v[224:225], 0, s[16:17]
	s_mov_b32 m0, s50
	s_nop 0
	global_load_lds_dwordx4 v[182:183], off
	v_lshl_add_u64 v[182:183], v[226:227], 0, s[16:17]
	s_mov_b32 m0, s51
	s_nop 0
	global_load_lds_dwordx4 v[182:183], off
	s_waitcnt vmcnt(8)
	s_waitcnt lgkmcnt(0)
	s_setprio 1
	s_barrier
	v_mfma_f32_16x16x32_bf16 v[62:65], v[148:151], v[190:193], v[62:65]
	v_mfma_f32_16x16x32_bf16 v[58:61], v[162:165], v[190:193], v[58:61]
	v_mfma_f32_16x16x32_bf16 v[46:49], v[148:151], v[198:201], v[46:49]
	v_mfma_f32_16x16x32_bf16 v[42:45], v[162:165], v[198:201], v[42:45]
	v_mfma_f32_16x16x32_bf16 v[30:33], v[148:151], v[206:209], v[30:33]
	v_mfma_f32_16x16x32_bf16 v[26:29], v[162:165], v[206:209], v[26:29]
	v_mfma_f32_16x16x32_bf16 v[14:17], v[148:151], v[214:217], v[14:17]
	v_mfma_f32_16x16x32_bf16 v[10:13], v[162:165], v[214:217], v[10:13]
	v_mfma_f32_16x16x32_bf16 v[62:65], v[158:161], v[194:197], v[62:65]
	v_mfma_f32_16x16x32_bf16 v[58:61], v[166:169], v[194:197], v[58:61]
	v_mfma_f32_16x16x32_bf16 v[46:49], v[158:161], v[202:205], v[46:49]
	v_mfma_f32_16x16x32_bf16 v[42:45], v[166:169], v[202:205], v[42:45]
	v_mfma_f32_16x16x32_bf16 v[30:33], v[158:161], v[210:213], v[30:33]
	v_mfma_f32_16x16x32_bf16 v[26:29], v[166:169], v[210:213], v[26:29]
	v_mfma_f32_16x16x32_bf16 v[14:17], v[158:161], v[218:221], v[14:17]
	v_mfma_f32_16x16x32_bf16 v[10:13], v[166:169], v[218:221], v[10:13]
	v_mfma_f32_16x16x32_bf16 v[54:57], v[170:173], v[190:193], v[54:57]
	v_mfma_f32_16x16x32_bf16 v[50:53], v[178:181], v[190:193], v[50:53]
	v_mfma_f32_16x16x32_bf16 v[38:41], v[170:173], v[198:201], v[38:41]
	v_mfma_f32_16x16x32_bf16 v[34:37], v[178:181], v[198:201], v[34:37]
	v_mfma_f32_16x16x32_bf16 v[22:25], v[170:173], v[206:209], v[22:25]
	v_mfma_f32_16x16x32_bf16 v[18:21], v[178:181], v[206:209], v[18:21]
	v_mfma_f32_16x16x32_bf16 v[6:9], v[170:173], v[214:217], v[6:9]
	v_mfma_f32_16x16x32_bf16 v[2:5], v[178:181], v[214:217], v[2:5]
	v_mfma_f32_16x16x32_bf16 v[54:57], v[174:177], v[194:197], v[54:57]
	v_mfma_f32_16x16x32_bf16 v[50:53], v[186:189], v[194:197], v[50:53]
	v_mfma_f32_16x16x32_bf16 v[38:41], v[174:177], v[202:205], v[38:41]
	v_mfma_f32_16x16x32_bf16 v[34:37], v[186:189], v[202:205], v[34:37]
	v_mfma_f32_16x16x32_bf16 v[22:25], v[174:177], v[210:213], v[22:25]
	v_mfma_f32_16x16x32_bf16 v[18:21], v[186:189], v[210:213], v[18:21]
	v_mfma_f32_16x16x32_bf16 v[6:9], v[174:177], v[218:221], v[6:9]
	v_mfma_f32_16x16x32_bf16 v[2:5], v[186:189], v[218:221], v[2:5]
	s_barrier
	s_setprio 0
	s_add_i32 s62, s62, 2
	s_add_u32 s36, s36, 0x100
	s_addc_u32 s37, s37, 0
	s_add_u32 s60, s60, 0x100
	s_addc_u32 s61, s61, 0
	s_cmp_gt_u32 s62, 41
	s_cbranch_scc0 .LBB0_278
	s_and_b64 vcc, exec, s[18:19]
	s_cbranch_vccz .LBB0_281
	s_barrier

; #define PG8_STAGE(bufoff, gbase, voff) do { _Pragma("unroll") for (int _i = 0; _i < 2; ++_i) \
;         __builtin_amdgcn_global_load_lds((const unsigned*)((const char*)(gbase) + (voff)[_i]), (LAS unsigned*)(lds + (bufoff) + ldsw + _i * 8192), 16, 0, 0); } while (0)
; #define PG8_LDA(dst, b, h) do { _Pragma("unroll") for (int m = 0; m < 4; ++m) _Pragma("unroll") for (int k = 0; k < 2; ++k) dst[m][k] = *(const LAS bf16x8*)(lds + PG8_SA(b, h) + aoff + m * 2048 + k * 1024); } while (0)
; #define PG8_LDB(dst, b, h) do { _Pragma("unroll") for (int n = 0; n < 2; ++n) _Pragma("unroll") for (int k = 0; k < 2; ++k) dst[n][k] = *(const LAS bf16x8*)(lds + PG8_SB(b, h) + boff + n * 2048 + k * 1024); } while (0)
; #define PG8_MMA(ai, bj, At, Bt) do { __builtin_amdgcn_s_setprio(1); _Pragma("unroll") for (int m = 0; m < 4; ++m) _Pragma("unroll") for (int n = 0; n < 2; ++n) _Pragma("unroll") for (int k = 0; k < 2; ++k) \
;         acc[ai][bj][m][n] = __builtin_amdgcn_mfma_f32_16x16x32_bf16(Bt[n][k], At[m][k], acc[ai][bj][m][n], 0, 0, 0); __builtin_amdgcn_s_setprio(0); } while (0)
; #define PG8_WAIT_V(n) asm volatile("s_waitcnt vmcnt(" #n ")" ::: "memory")
; #define PG8_WAIT_L(n) asm volatile("s_waitcnt lgkmcnt(" #n ")" ::: "memory")
; #define PG8_BAR __builtin_amdgcn_s_barrier()
; #define PG8_SCHED __builtin_amdgcn_sched_barrier(0)
; template <class Epi, class Sched>
; DI void gemm_phase(LAS unsigned char* lds, const Gemm g, const Sched& S, const Epi& E) {
;     ...
;         for (int t = 0; t < nt; t += 2) {
;             const bool last = (t == nt - 2);
;             const char* a1 = cA + (size_t)(t + 1) * kstep;
;             const char* a2 = last ? nA : cA + (size_t)(t + 2) * kstep; const char* b2 = last ? nB : cB + (size_t)(t + 2) * kstep;
;             const char* a3 = a2 + kstep; const char* b3 = b2 + kstep;
;             PG8_LDB(B0, 0, 0); PG8_LDB(B1, 0, 1); PG8_SCHED; PG8_LDA(At, 0, 0); PG8_STAGE(PG8_SA(1, 1), a1 + hstepA, voffA);
;             PG8_WAIT_V(8); PG8_WAIT_L(0); PG8_BAR; PG8_MMA(0, 0, At, B0); PG8_MMA(0, 1, At, B1); PG8_BAR; PG8_SCHED;
;             PG8_LDA(At, 0, 1); PG8_STAGE(PG8_SB(0, 0), b2, voffB); PG8_STAGE(PG8_SB(0, 1), b2 + hstepB, voffB); PG8_STAGE(PG8_SA(0, 0), a2, voffA);
;             PG8_WAIT_V(8); PG8_WAIT_L(0); PG8_BAR; PG8_MMA(1, 0, At, B0); PG8_MMA(1, 1, At, B1); PG8_BAR; PG8_SCHED;
.LBB0_381:
	ds_read_b128 v[138:141], v188
	ds_read_b128 v[142:145], v188 offset:1024
	ds_read_b128 v[176:179], v188 offset:2048
	ds_read_b128 v[198:201], v188 offset:3072
	ds_read_b128 v[202:205], v189
	ds_read_b128 v[206:209], v189 offset:1024
	ds_read_b128 v[210:213], v189 offset:2048
	ds_read_b128 v[214:217], v189 offset:3072
	s_add_u32 s64, s10, 0xfffc0080
	s_addc_u32 s65, s11, -1
	s_cmp_eq_u32 s69, 12
	s_cselect_b32 s67, s13, s65
	s_cselect_b32 s66, s29, s64
	s_cselect_b32 s65, s36, s68
	s_cselect_b32 s64, s57, s59
	v_lshl_add_u64 v[172:173], s[10:11], 0, v[162:163]
	s_add_i32 m0, s79, 0xc000
	ds_read_b128 v[218:221], v186
	ds_read_b128 v[222:225], v186 offset:1024
	ds_read_b128 v[226:229], v186 offset:2048
	ds_read_b128 v[230:233], v186 offset:3072
	ds_read_b128 v[234:237], v186 offset:4096
	ds_read_b128 v[238:241], v186 offset:5120
	ds_read_b128 v[242:245], v186 offset:6144
	ds_read_b128 v[246:249], v186 offset:7168
	global_load_lds_dwordx4 v[172:173], off
	v_lshl_add_u64 v[172:173], s[10:11], 0, v[164:165]
	s_add_i32 m0, s79, 0xe000
	s_nop 0
	global_load_lds_dwordx4 v[172:173], off
	s_waitcnt vmcnt(8)
	s_waitcnt lgkmcnt(0)
	s_setprio 1
	s_barrier
	v_mfma_f32_16x16x32_bf16 v[126:129], v[138:141], v[218:221], v[126:129]
	v_mfma_f32_16x16x32_bf16 v[122:125], v[176:179], v[218:221], v[122:125]
	v_mfma_f32_16x16x32_bf16 v[110:113], v[138:141], v[226:229], v[110:113]
	v_mfma_f32_16x16x32_bf16 v[106:109], v[176:179], v[226:229], v[106:109]
	v_mfma_f32_16x16x32_bf16 v[94:97], v[138:141], v[234:237], v[94:97]
	v_mfma_f32_16x16x32_bf16 v[90:93], v[176:179], v[234:237], v[90:93]
	v_mfma_f32_16x16x32_bf16 v[78:81], v[138:141], v[242:245], v[78:81]
	v_mfma_f32_16x16x32_bf16 v[74:77], v[176:179], v[242:245], v[74:77]
	v_mfma_f32_16x16x32_bf16 v[126:129], v[142:145], v[222:225], v[126:129]
	v_mfma_f32_16x16x32_bf16 v[122:125], v[198:201], v[222:225], v[122:125]
	v_mfma_f32_16x16x32_bf16 v[110:113], v[142:145], v[230:233], v[110:113]
	v_mfma_f32_16x16x32_bf16 v[106:109], v[198:201], v[230:233], v[106:109]
	v_mfma_f32_16x16x32_bf16 v[94:97], v[142:145], v[238:241], v[94:97]
	v_mfma_f32_16x16x32_bf16 v[90:93], v[198:201], v[238:241], v[90:93]
	v_mfma_f32_16x16x32_bf16 v[78:81], v[142:145], v[246:249], v[78:81]
	v_mfma_f32_16x16x32_bf16 v[74:77], v[198:201], v[246:249], v[74:77]
	v_mfma_f32_16x16x32_bf16 v[118:121], v[202:205], v[218:221], v[118:121]
	v_mfma_f32_16x16x32_bf16 v[114:117], v[210:213], v[218:221], v[114:117]
	v_mfma_f32_16x16x32_bf16 v[102:105], v[202:205], v[226:229], v[102:105]
	v_mfma_f32_16x16x32_bf16 v[98:101], v[210:213], v[226:229], v[98:101]
	v_mfma_f32_16x16x32_bf16 v[86:89], v[202:205], v[234:237], v[86:89]
	v_mfma_f32_16x16x32_bf16 v[82:85], v[210:213], v[234:237], v[82:85]
	v_mfma_f32_16x16x32_bf16 v[70:73], v[202:205], v[242:245], v[70:73]
	v_mfma_f32_16x16x32_bf16 v[66:69], v[210:213], v[242:245], v[66:69]
	v_mfma_f32_16x16x32_bf16 v[118:121], v[206:209], v[222:225], v[118:121]
	v_mfma_f32_16x16x32_bf16 v[114:117], v[214:217], v[222:225], v[114:117]
	v_mfma_f32_16x16x32_bf16 v[102:105], v[206:209], v[230:233], v[102:105]
	v_mfma_f32_16x16x32_bf16 v[98:101], v[214:217], v[230:233], v[98:101]
	v_mfma_f32_16x16x32_bf16 v[86:89], v[206:209], v[238:241], v[86:89]
	v_mfma_f32_16x16x32_bf16 v[82:85], v[214:217], v[238:241], v[82:85]
	v_mfma_f32_16x16x32_bf16 v[70:73], v[206:209], v[246:249], v[70:73]
	v_mfma_f32_16x16x32_bf16 v[66:69], v[214:217], v[246:249], v[66:69]
	s_barrier
	s_setprio 0
	s_add_i32 s70, s94, s78
	v_lshl_add_u64 v[172:173], s[64:65], 0, v[150:151]
	s_mov_b32 m0, s70
	ds_read_b128 v[218:221], v186 offset:16384
	ds_read_b128 v[222:225], v186 offset:17408
	ds_read_b128 v[226:229], v186 offset:18432
	ds_read_b128 v[230:233], v186 offset:19456
	ds_read_b128 v[234:237], v186 offset:20480
	ds_read_b128 v[238:241], v186 offset:21504
	ds_read_b128 v[242:245], v186 offset:22528
	ds_read_b128 v[246:249], v186 offset:23552
	global_load_lds_dwordx4 v[172:173], off
	s_add_i32 m0, s70, 0x2000
	s_add_u32 s70, s64, 0x40000
	v_lshl_add_u64 v[180:181], s[64:65], 0, v[154:155]
	s_addc_u32 s71, s65, 0
	s_add_i32 s72, s95, s78
	global_load_lds_dwordx4 v[180:181], off
	v_lshl_add_u64 v[250:251], s[70:71], 0, v[150:151]
	s_mov_b32 m0, s72
	v_lshl_add_u64 v[252:253], s[66:67], 0, v[152:153]
	global_load_lds_dwordx4 v[250:251], off
	v_lshl_add_u64 v[250:251], s[70:71], 0, v[154:155]
	s_add_i32 m0, s72, 0x2000
	s_nop 0
	global_load_lds_dwordx4 v[250:251], off
	v_lshl_add_u64 v[250:251], s[66:67], 0, v[148:149]
	s_mov_b32 m0, s79
	s_nop 0
	global_load_lds_dwordx4 v[250:251], off
	s_mov_b32 m0, s80
	s_nop 0
	global_load_lds_dwordx4 v[252:253], off
	s_waitcnt vmcnt(8)
	s_waitcnt lgkmcnt(0)
	s_setprio 1
	s_barrier
; #define PG8_STAGE(bufoff, gbase, voff) do { _Pragma("unroll") for (int _i = 0; _i < 2; ++_i) \
;         __builtin_amdgcn_global_load_lds((const unsigned*)((const char*)(gbase) + (voff)[_i]), (LAS unsigned*)(lds + (bufoff) + ldsw + _i * 8192), 16, 0, 0); } while (0)
; #define PG8_LDA(dst, b, h) do { _Pragma("unroll") for (int m = 0; m < 4; ++m) _Pragma("unroll") for (int k = 0; k < 2; ++k) dst[m][k] = *(const LAS bf16x8*)(lds + PG8_SA(b, h) + aoff + m * 2048 + k * 1024); } while (0)
; #define PG8_LDB(dst, b, h) do { _Pragma("unroll") for (int n = 0; n < 2; ++n) _Pragma("unroll") for (int k = 0; k < 2; ++k) dst[n][k] = *(const LAS bf16x8*)(lds + PG8_SB(b, h) + boff + n * 2048 + k * 1024); } while (0)
; #define PG8_MMA(ai, bj, At, Bt) do { __builtin_amdgcn_s_setprio(1); _Pragma("unroll") for (int m = 0; m < 4; ++m) _Pragma("unroll") for (int n = 0; n < 2; ++n) _Pragma("unroll") for (int k = 0; k < 2; ++k) \
;         acc[ai][bj][m][n] = __builtin_amdgcn_mfma_f32_16x16x32_bf16(Bt[n][k], At[m][k], acc[ai][bj][m][n], 0, 0, 0); __builtin_amdgcn_s_setprio(0); } while (0)
; #define PG8_WAIT_V(n) asm volatile("s_waitcnt vmcnt(" #n ")" ::: "memory")
; #define PG8_WAIT_L(n) asm volatile("s_waitcnt lgkmcnt(" #n ")" ::: "memory")
; #define PG8_BAR __builtin_amdgcn_s_barrier()
; #define PG8_SCHED __builtin_amdgcn_sched_barrier(0)
; template <class Epi, class Sched>
; DI void gemm_phase(LAS unsigned char* lds, const Gemm g, const Sched& S, const Epi& E) {
;     ...
;             PG8_WAIT_V(8); PG8_WAIT_L(0); PG8_BAR; PG8_MMA(1, 0, At, B0); PG8_MMA(1, 1, At, B1); PG8_BAR; PG8_SCHED;
;             PG8_LDB(B0, 1, 0); PG8_LDB(B1, 1, 1); PG8_SCHED; PG8_LDA(At, 1, 0); PG8_STAGE(PG8_SA(0, 1), a2 + hstepA, voffA);
;             PG8_WAIT_V(8); PG8_WAIT_L(0); PG8_BAR; PG8_MMA(0, 0, At, B0); PG8_MMA(0, 1, At, B1); PG8_BAR; PG8_SCHED;
	v_mfma_f32_16x16x32_bf16 v[62:65], v[138:141], v[218:221], v[62:65]
	v_mfma_f32_16x16x32_bf16 v[58:61], v[176:179], v[218:221], v[58:61]
	v_mfma_f32_16x16x32_bf16 v[46:49], v[138:141], v[226:229], v[46:49]
	v_mfma_f32_16x16x32_bf16 v[42:45], v[176:179], v[226:229], v[42:45]
	v_mfma_f32_16x16x32_bf16 v[30:33], v[138:141], v[234:237], v[30:33]
	v_mfma_f32_16x16x32_bf16 v[26:29], v[176:179], v[234:237], v[26:29]
	v_mfma_f32_16x16x32_bf16 v[14:17], v[138:141], v[242:245], v[14:17]
	v_mfma_f32_16x16x32_bf16 v[10:13], v[176:179], v[242:245], v[10:13]
	v_mfma_f32_16x16x32_bf16 v[62:65], v[142:145], v[222:225], v[62:65]
	v_mfma_f32_16x16x32_bf16 v[58:61], v[198:201], v[222:225], v[58:61]
	v_mfma_f32_16x16x32_bf16 v[46:49], v[142:145], v[230:233], v[46:49]
	v_mfma_f32_16x16x32_bf16 v[42:45], v[198:201], v[230:233], v[42:45]
	v_mfma_f32_16x16x32_bf16 v[30:33], v[142:145], v[238:241], v[30:33]
	v_mfma_f32_16x16x32_bf16 v[26:29], v[198:201], v[238:241], v[26:29]
	v_mfma_f32_16x16x32_bf16 v[14:17], v[142:145], v[246:249], v[14:17]
	v_mfma_f32_16x16x32_bf16 v[10:13], v[198:201], v[246:249], v[10:13]
	v_mfma_f32_16x16x32_bf16 v[54:57], v[202:205], v[218:221], v[54:57]
	v_mfma_f32_16x16x32_bf16 v[50:53], v[210:213], v[218:221], v[50:53]
	v_mfma_f32_16x16x32_bf16 v[38:41], v[202:205], v[226:229], v[38:41]
	v_mfma_f32_16x16x32_bf16 v[34:37], v[210:213], v[226:229], v[34:37]
	v_mfma_f32_16x16x32_bf16 v[22:25], v[202:205], v[234:237], v[22:25]
	v_mfma_f32_16x16x32_bf16 v[18:21], v[210:213], v[234:237], v[18:21]
	v_mfma_f32_16x16x32_bf16 v[6:9], v[202:205], v[242:245], v[6:9]
	v_mfma_f32_16x16x32_bf16 v[2:5], v[210:213], v[242:245], v[2:5]
	v_mfma_f32_16x16x32_bf16 v[54:57], v[206:209], v[222:225], v[54:57]
	v_mfma_f32_16x16x32_bf16 v[50:53], v[214:217], v[222:225], v[50:53]
	v_mfma_f32_16x16x32_bf16 v[38:41], v[206:209], v[230:233], v[38:41]
	v_mfma_f32_16x16x32_bf16 v[34:37], v[214:217], v[230:233], v[34:37]
	v_mfma_f32_16x16x32_bf16 v[22:25], v[206:209], v[238:241], v[22:25]
	v_mfma_f32_16x16x32_bf16 v[18:21], v[214:217], v[238:241], v[18:21]
	v_mfma_f32_16x16x32_bf16 v[6:9], v[206:209], v[246:249], v[6:9]
	v_mfma_f32_16x16x32_bf16 v[2:5], v[214:217], v[246:249], v[2:5]
	s_barrier
	s_setprio 0
	s_add_i32 s70, 0, 0x18000
	v_add_u32_e32 v156, s70, v159
	s_add_i32 s71, 0, 0x1c000
	ds_read_b128 v[138:141], v156
	ds_read_b128 v[142:145], v156 offset:1024
	ds_read_b128 v[176:179], v156 offset:2048
	ds_read_b128 v[198:201], v156 offset:3072
	v_add_u32_e32 v156, s71, v159
	ds_read_b128 v[202:205], v156
	ds_read_b128 v[206:209], v156 offset:1024
	ds_read_b128 v[210:213], v156 offset:2048
	ds_read_b128 v[214:217], v156 offset:3072
	s_add_u32 s66, s66, 0x40000
	s_addc_u32 s67, s67, 0
	s_mov_b32 m0, s81
	v_lshl_add_u64 v[254:255], s[66:67], 0, v[148:149]
	ds_read_b128 v[218:221], v186 offset:32768
	ds_read_b128 v[222:225], v186 offset:33792
	ds_read_b128 v[226:229], v186 offset:34816
	ds_read_b128 v[230:233], v186 offset:35840
	ds_read_b128 v[234:237], v186 offset:36864
	ds_read_b128 v[238:241], v186 offset:37888
	ds_read_b128 v[242:245], v186 offset:38912
	ds_read_b128 v[246:249], v186 offset:39936
	global_load_lds_dwordx4 v[254:255], off
	v_lshl_add_u64 v[254:255], s[66:67], 0, v[152:153]
	s_mov_b32 m0, s82
	s_nop 0
	global_load_lds_dwordx4 v[254:255], off
	s_waitcnt vmcnt(8)
	s_waitcnt lgkmcnt(0)
	s_setprio 1
	s_barrier
	v_mfma_f32_16x16x32_bf16 v[126:129], v[138:141], v[218:221], v[126:129]
	v_mfma_f32_16x16x32_bf16 v[122:125], v[176:179], v[218:221], v[122:125]
	v_mfma_f32_16x16x32_bf16 v[110:113], v[138:141], v[226:229], v[110:113]
	v_mfma_f32_16x16x32_bf16 v[106:109], v[176:179], v[226:229], v[106:109]
	v_mfma_f32_16x16x32_bf16 v[94:97], v[138:141], v[234:237], v[94:97]
	v_mfma_f32_16x16x32_bf16 v[90:93], v[176:179], v[234:237], v[90:93]
	v_mfma_f32_16x16x32_bf16 v[78:81], v[138:141], v[242:245], v[78:81]
	v_mfma_f32_16x16x32_bf16 v[74:77], v[176:179], v[242:245], v[74:77]
	v_mfma_f32_16x16x32_bf16 v[126:129], v[142:145], v[222:225], v[126:129]
	v_mfma_f32_16x16x32_bf16 v[122:125], v[198:201], v[222:225], v[122:125]
	v_mfma_f32_16x16x32_bf16 v[110:113], v[142:145], v[230:233], v[110:113]
	v_mfma_f32_16x16x32_bf16 v[106:109], v[198:201], v[230:233], v[106:109]
	v_mfma_f32_16x16x32_bf16 v[94:97], v[142:145], v[238:241], v[94:97]
	v_mfma_f32_16x16x32_bf16 v[90:93], v[198:201], v[238:241], v[90:93]
	v_mfma_f32_16x16x32_bf16 v[78:81], v[142:145], v[246:249], v[78:81]
	v_mfma_f32_16x16x32_bf16 v[74:77], v[198:201], v[246:249], v[74:77]
	v_mfma_f32_16x16x32_bf16 v[118:121], v[202:205], v[218:221], v[118:121]
	v_mfma_f32_16x16x32_bf16 v[114:117], v[210:213], v[218:221], v[114:117]
	v_mfma_f32_16x16x32_bf16 v[102:105], v[202:205], v[226:229], v[102:105]
	v_mfma_f32_16x16x32_bf16 v[98:101], v[210:213], v[226:229], v[98:101]
	v_mfma_f32_16x16x32_bf16 v[86:89], v[202:205], v[234:237], v[86:89]
	v_mfma_f32_16x16x32_bf16 v[82:85], v[210:213], v[234:237], v[82:85]
	v_mfma_f32_16x16x32_bf16 v[70:73], v[202:205], v[242:245], v[70:73]
	v_mfma_f32_16x16x32_bf16 v[66:69], v[210:213], v[242:245], v[66:69]
	v_mfma_f32_16x16x32_bf16 v[118:121], v[206:209], v[222:225], v[118:121]
	v_mfma_f32_16x16x32_bf16 v[114:117], v[214:217], v[222:225], v[114:117]
	v_mfma_f32_16x16x32_bf16 v[102:105], v[206:209], v[230:233], v[102:105]
	v_mfma_f32_16x16x32_bf16 v[98:101], v[214:217], v[230:233], v[98:101]
	v_mfma_f32_16x16x32_bf16 v[86:89], v[206:209], v[238:241], v[86:89]
	v_mfma_f32_16x16x32_bf16 v[82:85], v[214:217], v[238:241], v[82:85]
	v_mfma_f32_16x16x32_bf16 v[70:73], v[206:209], v[246:249], v[70:73]
	v_mfma_f32_16x16x32_bf16 v[66:69], v[214:217], v[246:249], v[66:69]
	s_barrier
; #define PG8_STAGE(bufoff, gbase, voff) do { _Pragma("unroll") for (int _i = 0; _i < 2; ++_i) \
;         __builtin_amdgcn_global_load_lds((const unsigned*)((const char*)(gbase) + (voff)[_i]), (LAS unsigned*)(lds + (bufoff) + ldsw + _i * 8192), 16, 0, 0); } while (0)
; #define PG8_LDA(dst, b, h) do { _Pragma("unroll") for (int m = 0; m < 4; ++m) _Pragma("unroll") for (int k = 0; k < 2; ++k) dst[m][k] = *(const LAS bf16x8*)(lds + PG8_SA(b, h) + aoff + m * 2048 + k * 1024); } while (0)
; #define PG8_LDB(dst, b, h) do { _Pragma("unroll") for (int n = 0; n < 2; ++n) _Pragma("unroll") for (int k = 0; k < 2; ++k) dst[n][k] = *(const LAS bf16x8*)(lds + PG8_SB(b, h) + boff + n * 2048 + k * 1024); } while (0)
; #define PG8_MMA(ai, bj, At, Bt) do { __builtin_amdgcn_s_setprio(1); _Pragma("unroll") for (int m = 0; m < 4; ++m) _Pragma("unroll") for (int n = 0; n < 2; ++n) _Pragma("unroll") for (int k = 0; k < 2; ++k) \
;         acc[ai][bj][m][n] = __builtin_amdgcn_mfma_f32_16x16x32_bf16(Bt[n][k], At[m][k], acc[ai][bj][m][n], 0, 0, 0); __builtin_amdgcn_s_setprio(0); } while (0)
; #define PG8_WAIT_V(n) asm volatile("s_waitcnt vmcnt(" #n ")" ::: "memory")
; #define PG8_WAIT_L(n) asm volatile("s_waitcnt lgkmcnt(" #n ")" ::: "memory")
; #define PG8_BAR __builtin_amdgcn_s_barrier()
; #define PG8_SCHED __builtin_amdgcn_sched_barrier(0)
; template <class Epi, class Sched>
; DI void gemm_phase(LAS unsigned char* lds, const Gemm g, const Sched& S, const Epi& E) {
;     ...
;             PG8_LDB(B0, 1, 0); PG8_LDB(B1, 1, 1); PG8_SCHED; PG8_LDA(At, 1, 0); PG8_STAGE(PG8_SA(0, 1), a2 + hstepA, voffA);
;             PG8_WAIT_V(8); PG8_WAIT_L(0); PG8_BAR; PG8_MMA(0, 0, At, B0); PG8_MMA(0, 1, At, B1); PG8_BAR; PG8_SCHED;
;             PG8_LDA(At, 1, 1); PG8_STAGE(PG8_SB(1, 0), b3, voffB); PG8_STAGE(PG8_SB(1, 1), b3 + hstepB, voffB); PG8_STAGE(PG8_SA(1, 0), a3, voffA);
;             PG8_WAIT_V(8); PG8_WAIT_L(0); PG8_BAR; PG8_MMA(1, 0, At, B0); PG8_MMA(1, 1, At, B1); PG8_BAR; PG8_SCHED;
;         }
;         if (wr == 0) PG8_BAR;
	s_setprio 0
	s_add_i32 s66, s70, s78
	v_lshl_add_u64 v[172:173], v[172:173], 0, s[50:51]
	s_mov_b32 m0, s66
	ds_read_b128 v[218:221], v186 offset:49152
	ds_read_b128 v[222:225], v186 offset:50176
	ds_read_b128 v[226:229], v186 offset:51200
	ds_read_b128 v[230:233], v186 offset:52224
	ds_read_b128 v[234:237], v186 offset:53248
	ds_read_b128 v[238:241], v186 offset:54272
	ds_read_b128 v[242:245], v186 offset:55296
	ds_read_b128 v[246:249], v186 offset:56320
	global_load_lds_dwordx4 v[172:173], off
	s_add_i32 m0, s66, 0x2000
	s_add_u32 s64, s64, 0x40080
	v_lshl_add_u64 v[172:173], v[180:181], 0, s[50:51]
	s_addc_u32 s65, s65, 0
	s_add_i32 s66, s71, s78
	global_load_lds_dwordx4 v[172:173], off
	v_lshl_add_u64 v[172:173], s[64:65], 0, v[150:151]
	s_mov_b32 m0, s66
	s_nop 0
	global_load_lds_dwordx4 v[172:173], off
	v_lshl_add_u64 v[172:173], s[64:65], 0, v[154:155]
	s_add_i32 m0, s66, 0x2000
	s_nop 0
	global_load_lds_dwordx4 v[172:173], off
	v_lshl_add_u64 v[172:173], v[250:251], 0, s[50:51]
	s_mov_b32 m0, s86
	s_nop 0
	global_load_lds_dwordx4 v[172:173], off
	v_lshl_add_u64 v[172:173], v[252:253], 0, s[50:51]
	s_mov_b32 m0, s87
	s_nop 0
	global_load_lds_dwordx4 v[172:173], off
	s_waitcnt vmcnt(8)
	s_waitcnt lgkmcnt(0)
	s_setprio 1
	s_barrier
	v_mfma_f32_16x16x32_bf16 v[62:65], v[138:141], v[218:221], v[62:65]
	v_mfma_f32_16x16x32_bf16 v[58:61], v[176:179], v[218:221], v[58:61]
	v_mfma_f32_16x16x32_bf16 v[46:49], v[138:141], v[226:229], v[46:49]
	v_mfma_f32_16x16x32_bf16 v[42:45], v[176:179], v[226:229], v[42:45]
	v_mfma_f32_16x16x32_bf16 v[30:33], v[138:141], v[234:237], v[30:33]
	v_mfma_f32_16x16x32_bf16 v[26:29], v[176:179], v[234:237], v[26:29]
	v_mfma_f32_16x16x32_bf16 v[14:17], v[138:141], v[242:245], v[14:17]
	v_mfma_f32_16x16x32_bf16 v[10:13], v[176:179], v[242:245], v[10:13]
	v_mfma_f32_16x16x32_bf16 v[62:65], v[142:145], v[222:225], v[62:65]
	v_mfma_f32_16x16x32_bf16 v[58:61], v[198:201], v[222:225], v[58:61]
	v_mfma_f32_16x16x32_bf16 v[46:49], v[142:145], v[230:233], v[46:49]
	v_mfma_f32_16x16x32_bf16 v[42:45], v[198:201], v[230:233], v[42:45]
	v_mfma_f32_16x16x32_bf16 v[30:33], v[142:145], v[238:241], v[30:33]
	v_mfma_f32_16x16x32_bf16 v[26:29], v[198:201], v[238:241], v[26:29]
	v_mfma_f32_16x16x32_bf16 v[14:17], v[142:145], v[246:249], v[14:17]
	v_mfma_f32_16x16x32_bf16 v[10:13], v[198:201], v[246:249], v[10:13]
	v_mfma_f32_16x16x32_bf16 v[54:57], v[202:205], v[218:221], v[54:57]
	v_mfma_f32_16x16x32_bf16 v[50:53], v[210:213], v[218:221], v[50:53]
	v_mfma_f32_16x16x32_bf16 v[38:41], v[202:205], v[226:229], v[38:41]
	v_mfma_f32_16x16x32_bf16 v[34:37], v[210:213], v[226:229], v[34:37]
	v_mfma_f32_16x16x32_bf16 v[22:25], v[202:205], v[234:237], v[22:25]
	v_mfma_f32_16x16x32_bf16 v[18:21], v[210:213], v[234:237], v[18:21]
	v_mfma_f32_16x16x32_bf16 v[6:9], v[202:205], v[242:245], v[6:9]
	v_mfma_f32_16x16x32_bf16 v[2:5], v[210:213], v[242:245], v[2:5]
	v_mfma_f32_16x16x32_bf16 v[54:57], v[206:209], v[222:225], v[54:57]
	v_mfma_f32_16x16x32_bf16 v[50:53], v[214:217], v[222:225], v[50:53]
	v_mfma_f32_16x16x32_bf16 v[38:41], v[206:209], v[230:233], v[38:41]
	v_mfma_f32_16x16x32_bf16 v[34:37], v[214:217], v[230:233], v[34:37]
	v_mfma_f32_16x16x32_bf16 v[22:25], v[206:209], v[238:241], v[22:25]
	v_mfma_f32_16x16x32_bf16 v[18:21], v[214:217], v[238:241], v[18:21]
	v_mfma_f32_16x16x32_bf16 v[6:9], v[206:209], v[246:249], v[6:9]
	v_mfma_f32_16x16x32_bf16 v[2:5], v[214:217], v[246:249], v[2:5]
	s_barrier
	s_setprio 0
	s_add_i32 s69, s69, 2
	s_add_u32 s10, s10, 0x100
	s_addc_u32 s11, s11, 0
	s_add_u32 s59, s59, 0x100
	s_addc_u32 s68, s68, 0
	s_cmp_gt_u32 s69, 13
	s_cbranch_scc0 .LBB0_381
	s_and_b64 vcc, exec, s[52:53]
	s_cbranch_vccnz .LBB0_386
	s_cmp_gt_i32 s12, 4
	s_mov_b64 s[10:11], -1
	s_cbranch_scc1 .LBB0_387

; #define PG8_STAGE(bufoff, gbase, voff) do { _Pragma("unroll") for (int _i = 0; _i < 2; ++_i) \
;         __builtin_amdgcn_global_load_lds((const unsigned*)((const char*)(gbase) + (voff)[_i]), (LAS unsigned*)(lds + (bufoff) + ldsw + _i * 8192), 16, 0, 0); } while (0)
; #define PG8_LDA(dst, b, h) do { _Pragma("unroll") for (int m = 0; m < 4; ++m) _Pragma("unroll") for (int k = 0; k < 2; ++k) dst[m][k] = *(const LAS bf16x8*)(lds + PG8_SA(b, h) + aoff + m * 2048 + k * 1024); } while (0)
; #define PG8_LDB(dst, b, h) do { _Pragma("unroll") for (int n = 0; n < 2; ++n) _Pragma("unroll") for (int k = 0; k < 2; ++k) dst[n][k] = *(const LAS bf16x8*)(lds + PG8_SB(b, h) + boff + n * 2048 + k * 1024); } while (0)
; #define PG8_MMA(ai, bj, At, Bt) do { __builtin_amdgcn_s_setprio(1); _Pragma("unroll") for (int m = 0; m < 4; ++m) _Pragma("unroll") for (int n = 0; n < 2; ++n) _Pragma("unroll") for (int k = 0; k < 2; ++k) \
;         acc[ai][bj][m][n] = __builtin_amdgcn_mfma_f32_16x16x32_bf16(Bt[n][k], At[m][k], acc[ai][bj][m][n], 0, 0, 0); __builtin_amdgcn_s_setprio(0); } while (0)
; #define PG8_WAIT_V(n) asm volatile("s_waitcnt vmcnt(" #n ")" ::: "memory")
; #define PG8_WAIT_L(n) asm volatile("s_waitcnt lgkmcnt(" #n ")" ::: "memory")
; #define PG8_BAR __builtin_amdgcn_s_barrier()
; #define PG8_SCHED __builtin_amdgcn_sched_barrier(0)
; template <class Epi, class Sched>
; DI void gemm_phase(LAS unsigned char* lds, const Gemm g, const Sched& S, const Epi& E) {
;     ...
;             PG8_LDB(B0, 0, 0); PG8_LDB(B1, 0, 1); PG8_SCHED; PG8_LDA(At, 0, 0); PG8_STAGE(PG8_SA(1, 1), a1 + hstepA, voffA);
;             PG8_WAIT_V(8); PG8_WAIT_L(0); PG8_BAR; PG8_MMA(0, 0, At, B0); PG8_MMA(0, 1, At, B1); PG8_BAR; PG8_SCHED;
;             PG8_LDA(At, 0, 1); PG8_STAGE(PG8_SB(0, 0), b2, voffB); PG8_STAGE(PG8_SB(0, 1), b2 + hstepB, voffB); PG8_STAGE(PG8_SA(0, 0), a2, voffA);
.LBB0_579:
	ds_read_b128 v[150:153], v142
	ds_read_b128 v[154:157], v142 offset:1024
	ds_read_b128 v[158:161], v142 offset:2048
	ds_read_b128 v[162:165], v142 offset:3072
	ds_read_b128 v[166:169], v143
	ds_read_b128 v[170:173], v143 offset:1024
	ds_read_b128 v[174:177], v143 offset:2048
	ds_read_b128 v[178:181], v143 offset:3072
	s_add_u32 s16, s8, s12
	s_addc_u32 s17, s9, s13
	s_add_u32 s16, s16, 0x100
	s_addc_u32 s17, s17, 0
	s_add_u32 s52, s39, s12
	s_addc_u32 s53, s40, s13
	s_cmpk_eq_i32 s12, 0xf00
	s_cselect_b32 s19, s9, s17
	s_cselect_b32 s18, s8, s16
	s_cselect_b32 s17, s7, s53
	s_cselect_b32 s16, s6, s52
	s_mov_b32 m0, s42
	v_lshl_add_u64 v[182:183], v[138:139], 0, s[12:13]
	ds_read_b128 v[186:189], v145
	ds_read_b128 v[190:193], v145 offset:1024
	ds_read_b128 v[194:197], v145 offset:2048
	ds_read_b128 v[198:201], v145 offset:3072
	ds_read_b128 v[202:205], v145 offset:4096
	ds_read_b128 v[206:209], v145 offset:5120
	ds_read_b128 v[210:213], v145 offset:6144
	ds_read_b128 v[214:217], v145 offset:7168
	global_load_lds_dwordx4 v[182:183], off
	v_lshl_add_u64 v[182:183], v[140:141], 0, s[12:13]
	s_mov_b32 m0, s43
	s_nop 0
	global_load_lds_dwordx4 v[182:183], off
	s_waitcnt vmcnt(8)
	s_waitcnt lgkmcnt(0)
	s_setprio 1
	s_barrier
	v_mfma_f32_16x16x32_bf16 v[126:129], v[150:153], v[186:189], v[126:129]
	v_mfma_f32_16x16x32_bf16 v[122:125], v[158:161], v[186:189], v[122:125]
	v_mfma_f32_16x16x32_bf16 v[118:121], v[150:153], v[194:197], v[118:121]
	v_mfma_f32_16x16x32_bf16 v[114:117], v[158:161], v[194:197], v[114:117]
	v_mfma_f32_16x16x32_bf16 v[110:113], v[150:153], v[202:205], v[110:113]
	v_mfma_f32_16x16x32_bf16 v[106:109], v[158:161], v[202:205], v[106:109]
	v_mfma_f32_16x16x32_bf16 v[102:105], v[150:153], v[210:213], v[102:105]
	v_mfma_f32_16x16x32_bf16 v[98:101], v[158:161], v[210:213], v[98:101]
	v_mfma_f32_16x16x32_bf16 v[126:129], v[154:157], v[190:193], v[126:129]
	v_mfma_f32_16x16x32_bf16 v[122:125], v[162:165], v[190:193], v[122:125]
	v_mfma_f32_16x16x32_bf16 v[118:121], v[154:157], v[198:201], v[118:121]
	v_mfma_f32_16x16x32_bf16 v[114:117], v[162:165], v[198:201], v[114:117]
	v_mfma_f32_16x16x32_bf16 v[110:113], v[154:157], v[206:209], v[110:113]
	v_mfma_f32_16x16x32_bf16 v[106:109], v[162:165], v[206:209], v[106:109]
	v_mfma_f32_16x16x32_bf16 v[102:105], v[154:157], v[214:217], v[102:105]
	v_mfma_f32_16x16x32_bf16 v[98:101], v[162:165], v[214:217], v[98:101]
	v_mfma_f32_16x16x32_bf16 v[62:65], v[166:169], v[186:189], v[62:65]
	v_mfma_f32_16x16x32_bf16 v[58:61], v[174:177], v[186:189], v[58:61]
	v_mfma_f32_16x16x32_bf16 v[54:57], v[166:169], v[194:197], v[54:57]
	v_mfma_f32_16x16x32_bf16 v[50:53], v[174:177], v[194:197], v[50:53]
	v_mfma_f32_16x16x32_bf16 v[46:49], v[166:169], v[202:205], v[46:49]
	v_mfma_f32_16x16x32_bf16 v[42:45], v[174:177], v[202:205], v[42:45]
	v_mfma_f32_16x16x32_bf16 v[38:41], v[166:169], v[210:213], v[38:41]
	v_mfma_f32_16x16x32_bf16 v[34:37], v[174:177], v[210:213], v[34:37]
	v_mfma_f32_16x16x32_bf16 v[62:65], v[170:173], v[190:193], v[62:65]
	v_mfma_f32_16x16x32_bf16 v[58:61], v[178:181], v[190:193], v[58:61]
	v_mfma_f32_16x16x32_bf16 v[54:57], v[170:173], v[198:201], v[54:57]
	v_mfma_f32_16x16x32_bf16 v[50:53], v[178:181], v[198:201], v[50:53]
	v_mfma_f32_16x16x32_bf16 v[46:49], v[170:173], v[206:209], v[46:49]
	v_mfma_f32_16x16x32_bf16 v[42:45], v[178:181], v[206:209], v[42:45]
	v_mfma_f32_16x16x32_bf16 v[38:41], v[170:173], v[214:217], v[38:41]
	v_mfma_f32_16x16x32_bf16 v[34:37], v[178:181], v[214:217], v[34:37]
	s_barrier
	s_setprio 0
	s_mov_b32 m0, s44
	v_lshl_add_u64 v[182:183], s[16:17], 0, v[134:135]
	s_add_u32 s52, s16, 0x80000
	ds_read_b128 v[186:189], v145 offset:16384
	ds_read_b128 v[190:193], v145 offset:17408
	ds_read_b128 v[194:197], v145 offset:18432
	ds_read_b128 v[198:201], v145 offset:19456
	ds_read_b128 v[202:205], v145 offset:20480
	ds_read_b128 v[206:209], v145 offset:21504
	ds_read_b128 v[210:213], v145 offset:22528
	ds_read_b128 v[214:217], v145 offset:23552
	global_load_lds_dwordx4 v[182:183], off
	v_lshl_add_u64 v[218:219], s[16:17], 0, v[130:131]
	s_mov_b32 m0, s45
	s_addc_u32 s53, s17, 0
	global_load_lds_dwordx4 v[218:219], off
	v_lshl_add_u64 v[220:221], s[52:53], 0, v[134:135]
	s_mov_b32 m0, s46
	v_lshl_add_u64 v[222:223], s[18:19], 0, v[132:133]
	global_load_lds_dwordx4 v[220:221], off
	v_lshl_add_u64 v[220:221], s[52:53], 0, v[130:131]
	s_mov_b32 m0, s47
	s_nop 0
	global_load_lds_dwordx4 v[220:221], off
	v_lshl_add_u64 v[220:221], s[18:19], 0, v[136:137]
	s_mov_b32 m0, s28
	s_nop 0
	global_load_lds_dwordx4 v[220:221], off
	s_mov_b32 m0, s29
	s_nop 0
	global_load_lds_dwordx4 v[222:223], off
	s_waitcnt vmcnt(8)
	s_waitcnt lgkmcnt(0)
	s_setprio 1
	s_barrier
; #define PG8_STAGE(bufoff, gbase, voff) do { _Pragma("unroll") for (int _i = 0; _i < 2; ++_i) \
;         __builtin_amdgcn_global_load_lds((const unsigned*)((const char*)(gbase) + (voff)[_i]), (LAS unsigned*)(lds + (bufoff) + ldsw + _i * 8192), 16, 0, 0); } while (0)
; #define PG8_LDA(dst, b, h) do { _Pragma("unroll") for (int m = 0; m < 4; ++m) _Pragma("unroll") for (int k = 0; k < 2; ++k) dst[m][k] = *(const LAS bf16x8*)(lds + PG8_SA(b, h) + aoff + m * 2048 + k * 1024); } while (0)
; #define PG8_LDB(dst, b, h) do { _Pragma("unroll") for (int n = 0; n < 2; ++n) _Pragma("unroll") for (int k = 0; k < 2; ++k) dst[n][k] = *(const LAS bf16x8*)(lds + PG8_SB(b, h) + boff + n * 2048 + k * 1024); } while (0)
; #define PG8_MMA(ai, bj, At, Bt) do { __builtin_amdgcn_s_setprio(1); _Pragma("unroll") for (int m = 0; m < 4; ++m) _Pragma("unroll") for (int n = 0; n < 2; ++n) _Pragma("unroll") for (int k = 0; k < 2; ++k) \
;         acc[ai][bj][m][n] = __builtin_amdgcn_mfma_f32_16x16x32_bf16(Bt[n][k], At[m][k], acc[ai][bj][m][n], 0, 0, 0); __builtin_amdgcn_s_setprio(0); } while (0)
; #define PG8_WAIT_V(n) asm volatile("s_waitcnt vmcnt(" #n ")" ::: "memory")
; #define PG8_WAIT_L(n) asm volatile("s_waitcnt lgkmcnt(" #n ")" ::: "memory")
; #define PG8_BAR __builtin_amdgcn_s_barrier()
; #define PG8_SCHED __builtin_amdgcn_sched_barrier(0)
; template <class Epi, class Sched>
; DI void gemm_phase(LAS unsigned char* lds, const Gemm g, const Sched& S, const Epi& E) {
;     ...
;             PG8_LDA(At, 0, 1); PG8_STAGE(PG8_SB(0, 0), b2, voffB); PG8_STAGE(PG8_SB(0, 1), b2 + hstepB, voffB); PG8_STAGE(PG8_SA(0, 0), a2, voffA);
;             PG8_WAIT_V(8); PG8_WAIT_L(0); PG8_BAR; PG8_MMA(1, 0, At, B0); PG8_MMA(1, 1, At, B1); PG8_BAR; PG8_SCHED;
;             PG8_LDB(B0, 1, 0); PG8_LDB(B1, 1, 1); PG8_SCHED; PG8_LDA(At, 1, 0); PG8_STAGE(PG8_SA(0, 1), a2 + hstepA, voffA);
;             PG8_WAIT_V(8); PG8_WAIT_L(0); PG8_BAR; PG8_MMA(0, 0, At, B0); PG8_MMA(0, 1, At, B1); PG8_BAR; PG8_SCHED;
	v_mfma_f32_16x16x32_bf16 v[94:97], v[150:153], v[186:189], v[94:97]
	v_mfma_f32_16x16x32_bf16 v[90:93], v[158:161], v[186:189], v[90:93]
	v_mfma_f32_16x16x32_bf16 v[86:89], v[150:153], v[194:197], v[86:89]
	v_mfma_f32_16x16x32_bf16 v[82:85], v[158:161], v[194:197], v[82:85]
	v_mfma_f32_16x16x32_bf16 v[78:81], v[150:153], v[202:205], v[78:81]
	v_mfma_f32_16x16x32_bf16 v[74:77], v[158:161], v[202:205], v[74:77]
	v_mfma_f32_16x16x32_bf16 v[70:73], v[150:153], v[210:213], v[70:73]
	v_mfma_f32_16x16x32_bf16 v[66:69], v[158:161], v[210:213], v[66:69]
	v_mfma_f32_16x16x32_bf16 v[94:97], v[154:157], v[190:193], v[94:97]
	v_mfma_f32_16x16x32_bf16 v[90:93], v[162:165], v[190:193], v[90:93]
	v_mfma_f32_16x16x32_bf16 v[86:89], v[154:157], v[198:201], v[86:89]
	v_mfma_f32_16x16x32_bf16 v[82:85], v[162:165], v[198:201], v[82:85]
	v_mfma_f32_16x16x32_bf16 v[78:81], v[154:157], v[206:209], v[78:81]
	v_mfma_f32_16x16x32_bf16 v[74:77], v[162:165], v[206:209], v[74:77]
	v_mfma_f32_16x16x32_bf16 v[70:73], v[154:157], v[214:217], v[70:73]
	v_mfma_f32_16x16x32_bf16 v[66:69], v[162:165], v[214:217], v[66:69]
	v_mfma_f32_16x16x32_bf16 v[30:33], v[166:169], v[186:189], v[30:33]
	v_mfma_f32_16x16x32_bf16 v[26:29], v[174:177], v[186:189], v[26:29]
	v_mfma_f32_16x16x32_bf16 v[22:25], v[166:169], v[194:197], v[22:25]
	v_mfma_f32_16x16x32_bf16 v[18:21], v[174:177], v[194:197], v[18:21]
	v_mfma_f32_16x16x32_bf16 v[14:17], v[166:169], v[202:205], v[14:17]
	v_mfma_f32_16x16x32_bf16 v[10:13], v[174:177], v[202:205], v[10:13]
	v_mfma_f32_16x16x32_bf16 v[6:9], v[166:169], v[210:213], v[6:9]
	v_mfma_f32_16x16x32_bf16 v[2:5], v[174:177], v[210:213], v[2:5]
	v_mfma_f32_16x16x32_bf16 v[30:33], v[170:173], v[190:193], v[30:33]
	v_mfma_f32_16x16x32_bf16 v[26:29], v[178:181], v[190:193], v[26:29]
	v_mfma_f32_16x16x32_bf16 v[22:25], v[170:173], v[198:201], v[22:25]
	v_mfma_f32_16x16x32_bf16 v[18:21], v[178:181], v[198:201], v[18:21]
	v_mfma_f32_16x16x32_bf16 v[14:17], v[170:173], v[206:209], v[14:17]
	v_mfma_f32_16x16x32_bf16 v[10:13], v[178:181], v[206:209], v[10:13]
	v_mfma_f32_16x16x32_bf16 v[6:9], v[170:173], v[214:217], v[6:9]
	v_mfma_f32_16x16x32_bf16 v[2:5], v[178:181], v[214:217], v[2:5]
	s_barrier
	s_setprio 0
	ds_read_b128 v[150:153], v147
	ds_read_b128 v[154:157], v147 offset:1024
	ds_read_b128 v[158:161], v147 offset:2048
	ds_read_b128 v[162:165], v147 offset:3072
	ds_read_b128 v[166:169], v148
	ds_read_b128 v[170:173], v148 offset:1024
	ds_read_b128 v[174:177], v148 offset:2048
	ds_read_b128 v[178:181], v148 offset:3072
	s_add_u32 s18, s18, 0x40000
	s_addc_u32 s19, s19, 0
	s_mov_b32 m0, s34
	v_lshl_add_u64 v[224:225], s[18:19], 0, v[136:137]
	ds_read_b128 v[186:189], v145 offset:32768
	ds_read_b128 v[190:193], v145 offset:33792
	ds_read_b128 v[194:197], v145 offset:34816
	ds_read_b128 v[198:201], v145 offset:35840
	ds_read_b128 v[202:205], v145 offset:36864
	ds_read_b128 v[206:209], v145 offset:37888
	ds_read_b128 v[210:213], v145 offset:38912
	ds_read_b128 v[214:217], v145 offset:39936
	global_load_lds_dwordx4 v[224:225], off
	v_lshl_add_u64 v[224:225], s[18:19], 0, v[132:133]
	s_mov_b32 m0, s35
	s_nop 0
	global_load_lds_dwordx4 v[224:225], off
	s_waitcnt vmcnt(8)
	s_waitcnt lgkmcnt(0)
	s_setprio 1
	s_barrier
	v_mfma_f32_16x16x32_bf16 v[126:129], v[150:153], v[186:189], v[126:129]
	v_mfma_f32_16x16x32_bf16 v[122:125], v[158:161], v[186:189], v[122:125]
	v_mfma_f32_16x16x32_bf16 v[118:121], v[150:153], v[194:197], v[118:121]
	v_mfma_f32_16x16x32_bf16 v[114:117], v[158:161], v[194:197], v[114:117]
	v_mfma_f32_16x16x32_bf16 v[110:113], v[150:153], v[202:205], v[110:113]
	v_mfma_f32_16x16x32_bf16 v[106:109], v[158:161], v[202:205], v[106:109]
	v_mfma_f32_16x16x32_bf16 v[102:105], v[150:153], v[210:213], v[102:105]
	v_mfma_f32_16x16x32_bf16 v[98:101], v[158:161], v[210:213], v[98:101]
	v_mfma_f32_16x16x32_bf16 v[126:129], v[154:157], v[190:193], v[126:129]
	v_mfma_f32_16x16x32_bf16 v[122:125], v[162:165], v[190:193], v[122:125]
	v_mfma_f32_16x16x32_bf16 v[118:121], v[154:157], v[198:201], v[118:121]
	v_mfma_f32_16x16x32_bf16 v[114:117], v[162:165], v[198:201], v[114:117]
	v_mfma_f32_16x16x32_bf16 v[110:113], v[154:157], v[206:209], v[110:113]
	v_mfma_f32_16x16x32_bf16 v[106:109], v[162:165], v[206:209], v[106:109]
	v_mfma_f32_16x16x32_bf16 v[102:105], v[154:157], v[214:217], v[102:105]
	v_mfma_f32_16x16x32_bf16 v[98:101], v[162:165], v[214:217], v[98:101]
	v_mfma_f32_16x16x32_bf16 v[62:65], v[166:169], v[186:189], v[62:65]
	v_mfma_f32_16x16x32_bf16 v[58:61], v[174:177], v[186:189], v[58:61]
	v_mfma_f32_16x16x32_bf16 v[54:57], v[166:169], v[194:197], v[54:57]
	v_mfma_f32_16x16x32_bf16 v[50:53], v[174:177], v[194:197], v[50:53]
	v_mfma_f32_16x16x32_bf16 v[46:49], v[166:169], v[202:205], v[46:49]
	v_mfma_f32_16x16x32_bf16 v[42:45], v[174:177], v[202:205], v[42:45]
	v_mfma_f32_16x16x32_bf16 v[38:41], v[166:169], v[210:213], v[38:41]
	v_mfma_f32_16x16x32_bf16 v[34:37], v[174:177], v[210:213], v[34:37]
	v_mfma_f32_16x16x32_bf16 v[62:65], v[170:173], v[190:193], v[62:65]
	v_mfma_f32_16x16x32_bf16 v[58:61], v[178:181], v[190:193], v[58:61]
	v_mfma_f32_16x16x32_bf16 v[54:57], v[170:173], v[198:201], v[54:57]
	v_mfma_f32_16x16x32_bf16 v[50:53], v[178:181], v[198:201], v[50:53]
	v_mfma_f32_16x16x32_bf16 v[46:49], v[170:173], v[206:209], v[46:49]
	v_mfma_f32_16x16x32_bf16 v[42:45], v[178:181], v[206:209], v[42:45]
	v_mfma_f32_16x16x32_bf16 v[38:41], v[170:173], v[214:217], v[38:41]
	v_mfma_f32_16x16x32_bf16 v[34:37], v[178:181], v[214:217], v[34:37]
	s_barrier
; #define PG8_STAGE(bufoff, gbase, voff) do { _Pragma("unroll") for (int _i = 0; _i < 2; ++_i) \
;         __builtin_amdgcn_global_load_lds((const unsigned*)((const char*)(gbase) + (voff)[_i]), (LAS unsigned*)(lds + (bufoff) + ldsw + _i * 8192), 16, 0, 0); } while (0)
; #define PG8_LDA(dst, b, h) do { _Pragma("unroll") for (int m = 0; m < 4; ++m) _Pragma("unroll") for (int k = 0; k < 2; ++k) dst[m][k] = *(const LAS bf16x8*)(lds + PG8_SA(b, h) + aoff + m * 2048 + k * 1024); } while (0)
; #define PG8_MMA(ai, bj, At, Bt) do { __builtin_amdgcn_s_setprio(1); _Pragma("unroll") for (int m = 0; m < 4; ++m) _Pragma("unroll") for (int n = 0; n < 2; ++n) _Pragma("unroll") for (int k = 0; k < 2; ++k) \
;         acc[ai][bj][m][n] = __builtin_amdgcn_mfma_f32_16x16x32_bf16(Bt[n][k], At[m][k], acc[ai][bj][m][n], 0, 0, 0); __builtin_amdgcn_s_setprio(0); } while (0)
; #define PG8_WAIT_V(n) asm volatile("s_waitcnt vmcnt(" #n ")" ::: "memory")
; #define PG8_WAIT_L(n) asm volatile("s_waitcnt lgkmcnt(" #n ")" ::: "memory")
; #define PG8_BAR __builtin_amdgcn_s_barrier()
; #define PG8_SCHED __builtin_amdgcn_sched_barrier(0)
; template <class Epi, class Sched>
; DI void gemm_phase(LAS unsigned char* lds, const Gemm g, const Sched& S, const Epi& E) {
;     ...
;             PG8_LDA(At, 1, 1); PG8_STAGE(PG8_SB(1, 0), b3, voffB); PG8_STAGE(PG8_SB(1, 1), b3 + hstepB, voffB); PG8_STAGE(PG8_SA(1, 0), a3, voffA);
;             PG8_WAIT_V(8); PG8_WAIT_L(0); PG8_BAR; PG8_MMA(1, 0, At, B0); PG8_MMA(1, 1, At, B1); PG8_BAR; PG8_SCHED;
;         }
;         if (wr == 0) PG8_BAR;
	s_setprio 0
	s_mov_b32 m0, s48
	v_lshl_add_u64 v[182:183], v[182:183], 0, s[10:11]
	s_add_u32 s16, s16, 0x80080
	ds_read_b128 v[186:189], v145 offset:49152
	ds_read_b128 v[190:193], v145 offset:50176
	ds_read_b128 v[194:197], v145 offset:51200
	ds_read_b128 v[198:201], v145 offset:52224
	ds_read_b128 v[202:205], v145 offset:53248
	ds_read_b128 v[206:209], v145 offset:54272
	ds_read_b128 v[210:213], v145 offset:55296
	ds_read_b128 v[214:217], v145 offset:56320
	global_load_lds_dwordx4 v[182:183], off
	v_lshl_add_u64 v[182:183], v[218:219], 0, s[10:11]
	s_mov_b32 m0, s49
	s_addc_u32 s17, s17, 0
	global_load_lds_dwordx4 v[182:183], off
	v_lshl_add_u64 v[182:183], s[16:17], 0, v[134:135]
	s_mov_b32 m0, s50
	s_nop 0
	global_load_lds_dwordx4 v[182:183], off
	v_lshl_add_u64 v[182:183], s[16:17], 0, v[130:131]
	s_mov_b32 m0, s51
	s_nop 0
	global_load_lds_dwordx4 v[182:183], off
	v_lshl_add_u64 v[182:183], v[220:221], 0, s[10:11]
	s_mov_b32 m0, s37
	s_nop 0
	global_load_lds_dwordx4 v[182:183], off
	v_lshl_add_u64 v[182:183], v[222:223], 0, s[10:11]
	s_mov_b32 m0, s38
	s_nop 0
	global_load_lds_dwordx4 v[182:183], off
	s_waitcnt vmcnt(8)
	s_waitcnt lgkmcnt(0)
	s_setprio 1
	s_barrier
	v_mfma_f32_16x16x32_bf16 v[94:97], v[150:153], v[186:189], v[94:97]
	v_mfma_f32_16x16x32_bf16 v[90:93], v[158:161], v[186:189], v[90:93]
	v_mfma_f32_16x16x32_bf16 v[86:89], v[150:153], v[194:197], v[86:89]
	v_mfma_f32_16x16x32_bf16 v[82:85], v[158:161], v[194:197], v[82:85]
	v_mfma_f32_16x16x32_bf16 v[78:81], v[150:153], v[202:205], v[78:81]
	v_mfma_f32_16x16x32_bf16 v[74:77], v[158:161], v[202:205], v[74:77]
	v_mfma_f32_16x16x32_bf16 v[70:73], v[150:153], v[210:213], v[70:73]
	v_mfma_f32_16x16x32_bf16 v[66:69], v[158:161], v[210:213], v[66:69]
	v_mfma_f32_16x16x32_bf16 v[94:97], v[154:157], v[190:193], v[94:97]
	v_mfma_f32_16x16x32_bf16 v[90:93], v[162:165], v[190:193], v[90:93]
	v_mfma_f32_16x16x32_bf16 v[86:89], v[154:157], v[198:201], v[86:89]
	v_mfma_f32_16x16x32_bf16 v[82:85], v[162:165], v[198:201], v[82:85]
	v_mfma_f32_16x16x32_bf16 v[78:81], v[154:157], v[206:209], v[78:81]
	v_mfma_f32_16x16x32_bf16 v[74:77], v[162:165], v[206:209], v[74:77]
	v_mfma_f32_16x16x32_bf16 v[70:73], v[154:157], v[214:217], v[70:73]
	v_mfma_f32_16x16x32_bf16 v[66:69], v[162:165], v[214:217], v[66:69]
	v_mfma_f32_16x16x32_bf16 v[30:33], v[166:169], v[186:189], v[30:33]
	v_mfma_f32_16x16x32_bf16 v[26:29], v[174:177], v[186:189], v[26:29]
	v_mfma_f32_16x16x32_bf16 v[22:25], v[166:169], v[194:197], v[22:25]
	v_mfma_f32_16x16x32_bf16 v[18:21], v[174:177], v[194:197], v[18:21]
	v_mfma_f32_16x16x32_bf16 v[14:17], v[166:169], v[202:205], v[14:17]
	v_mfma_f32_16x16x32_bf16 v[10:13], v[174:177], v[202:205], v[10:13]
	v_mfma_f32_16x16x32_bf16 v[6:9], v[166:169], v[210:213], v[6:9]
	v_mfma_f32_16x16x32_bf16 v[2:5], v[174:177], v[210:213], v[2:5]
	v_mfma_f32_16x16x32_bf16 v[30:33], v[170:173], v[190:193], v[30:33]
	v_mfma_f32_16x16x32_bf16 v[26:29], v[178:181], v[190:193], v[26:29]
	v_mfma_f32_16x16x32_bf16 v[22:25], v[170:173], v[198:201], v[22:25]
	v_mfma_f32_16x16x32_bf16 v[18:21], v[178:181], v[198:201], v[18:21]
	v_mfma_f32_16x16x32_bf16 v[14:17], v[170:173], v[206:209], v[14:17]
	v_mfma_f32_16x16x32_bf16 v[10:13], v[178:181], v[206:209], v[10:13]
	v_mfma_f32_16x16x32_bf16 v[6:9], v[170:173], v[214:217], v[6:9]
	v_mfma_f32_16x16x32_bf16 v[2:5], v[178:181], v[214:217], v[2:5]
	s_barrier
	s_setprio 0
	s_add_i32 s41, s41, 2
	s_add_u32 s12, s12, 0x100
	s_addc_u32 s13, s13, 0
	s_cmp_gt_u32 s41, 29
	s_cbranch_scc0 .LBB0_579
	s_cmpk_lt_u32 s21, 0x100
	s_cbranch_scc0 .LBB0_582
	s_barrier

; #define PG8_STAGE(bufoff, gbase, voff) do { _Pragma("unroll") for (int _i = 0; _i < 2; ++_i) \
;         __builtin_amdgcn_global_load_lds((const unsigned*)((const char*)(gbase) + (voff)[_i]), (LAS unsigned*)(lds + (bufoff) + ldsw + _i * 8192), 16, 0, 0); } while (0)
; #define PG8_LDA(dst, b, h) do { _Pragma("unroll") for (int m = 0; m < 4; ++m) _Pragma("unroll") for (int k = 0; k < 2; ++k) dst[m][k] = *(const LAS bf16x8*)(lds + PG8_SA(b, h) + aoff + m * 2048 + k * 1024); } while (0)
; #define PG8_LDB(dst, b, h) do { _Pragma("unroll") for (int n = 0; n < 2; ++n) _Pragma("unroll") for (int k = 0; k < 2; ++k) dst[n][k] = *(const LAS bf16x8*)(lds + PG8_SB(b, h) + boff + n * 2048 + k * 1024); } while (0)
; #define PG8_MMA(ai, bj, At, Bt) do { __builtin_amdgcn_s_setprio(1); _Pragma("unroll") for (int m = 0; m < 4; ++m) _Pragma("unroll") for (int n = 0; n < 2; ++n) _Pragma("unroll") for (int k = 0; k < 2; ++k) \
;         acc[ai][bj][m][n] = __builtin_amdgcn_mfma_f32_16x16x32_bf16(Bt[n][k], At[m][k], acc[ai][bj][m][n], 0, 0, 0); __builtin_amdgcn_s_setprio(0); } while (0)
; #define PG8_WAIT_V(n) asm volatile("s_waitcnt vmcnt(" #n ")" ::: "memory")
; #define PG8_WAIT_L(n) asm volatile("s_waitcnt lgkmcnt(" #n ")" ::: "memory")
; #define PG8_BAR __builtin_amdgcn_s_barrier()
; template <class Epi, class Sched>
; DI void gemm_phase(LAS unsigned char* lds, const Gemm g, const Sched& S, const Epi& E) {
;     ...
;         const char* nA = has_next ? (const char*)(nxt.src ? g.A1 : g.A0) + (size_t)nxt.pm * tstepA : cA; const char* nB = has_next ? (const char*)(nxt.src ? g.B1 : g.B0) + (size_t)nxt.pn * tstepB : cB;
;         for (int t = 0; t < nt; t += 2) {
;             const bool last = (t == nt - 2);
;             const char* a1 = cA + (size_t)(t + 1) * kstep;
;             const char* a2 = last ? nA : cA + (size_t)(t + 2) * kstep; const char* b2 = last ? nB : cB + (size_t)(t + 2) * kstep;
;             const char* a3 = a2 + kstep; const char* b3 = b2 + kstep;
;             PG8_LDB(B0, 0, 0); PG8_LDB(B1, 0, 1); PG8_SCHED; PG8_LDA(At, 0, 0); PG8_STAGE(PG8_SA(1, 1), a1 + hstepA, voffA);
;             PG8_WAIT_V(8); PG8_WAIT_L(0); PG8_BAR; PG8_MMA(0, 0, At, B0); PG8_MMA(0, 1, At, B1); PG8_BAR; PG8_SCHED;
;             PG8_LDA(At, 0, 1); PG8_STAGE(PG8_SB(0, 0), b2, voffB); PG8_STAGE(PG8_SB(0, 1), b2 + hstepB, voffB); PG8_STAGE(PG8_SA(0, 0), a2, voffA);
.LBB0_972:
	v_add_u32_e32 v158, s64, v162
	v_add_u32_e32 v180, s65, v162
	ds_read_b128 v[146:149], v158
	ds_read_b128 v[150:153], v158 offset:1024
	ds_read_b128 v[154:157], v158 offset:2048
	ds_read_b128 v[158:161], v158 offset:3072
	ds_read_b128 v[168:171], v180
	ds_read_b128 v[172:175], v180 offset:1024
	ds_read_b128 v[176:179], v180 offset:2048
	ds_read_b128 v[180:183], v180 offset:3072
	s_add_u32 s46, s44, 0xfffe0080
	s_addc_u32 s47, s45, -1
	s_cmp_eq_u32 s72, 4
	s_cselect_b32 s49, s39, s47
	s_cselect_b32 s48, s68, s46
	s_cselect_b32 s47, s37, s71
	s_cselect_b32 s46, s69, s70
	v_lshl_add_u64 v[218:219], s[44:45], 0, v[138:139]
	s_add_i32 m0, s53, 0xc000
	ds_read_b128 v[186:189], v167
	ds_read_b128 v[190:193], v167 offset:1024
	ds_read_b128 v[194:197], v167 offset:2048
	ds_read_b128 v[198:201], v167 offset:3072
	ds_read_b128 v[202:205], v167 offset:4096
	ds_read_b128 v[206:209], v167 offset:5120
	ds_read_b128 v[210:213], v167 offset:6144
	ds_read_b128 v[214:217], v167 offset:7168
	global_load_lds_dwordx4 v[218:219], off
	v_lshl_add_u64 v[218:219], s[44:45], 0, v[140:141]
	s_add_i32 m0, s53, 0xe000
	s_nop 0
	global_load_lds_dwordx4 v[218:219], off
	s_waitcnt vmcnt(8)
	s_waitcnt lgkmcnt(0)
	s_setprio 1
	s_barrier
	v_mfma_f32_16x16x32_bf16 v[126:129], v[146:149], v[186:189], v[126:129]
	v_mfma_f32_16x16x32_bf16 v[122:125], v[154:157], v[186:189], v[122:125]
	v_mfma_f32_16x16x32_bf16 v[118:121], v[146:149], v[194:197], v[118:121]
	v_mfma_f32_16x16x32_bf16 v[114:117], v[154:157], v[194:197], v[114:117]
	v_mfma_f32_16x16x32_bf16 v[110:113], v[146:149], v[202:205], v[110:113]
	v_mfma_f32_16x16x32_bf16 v[106:109], v[154:157], v[202:205], v[106:109]
	v_mfma_f32_16x16x32_bf16 v[102:105], v[146:149], v[210:213], v[102:105]
	v_mfma_f32_16x16x32_bf16 v[98:101], v[154:157], v[210:213], v[98:101]
	v_mfma_f32_16x16x32_bf16 v[126:129], v[150:153], v[190:193], v[126:129]
	v_mfma_f32_16x16x32_bf16 v[122:125], v[158:161], v[190:193], v[122:125]
	v_mfma_f32_16x16x32_bf16 v[118:121], v[150:153], v[198:201], v[118:121]
	v_mfma_f32_16x16x32_bf16 v[114:117], v[158:161], v[198:201], v[114:117]
	v_mfma_f32_16x16x32_bf16 v[110:113], v[150:153], v[206:209], v[110:113]
	v_mfma_f32_16x16x32_bf16 v[106:109], v[158:161], v[206:209], v[106:109]
	v_mfma_f32_16x16x32_bf16 v[102:105], v[150:153], v[214:217], v[102:105]
	v_mfma_f32_16x16x32_bf16 v[98:101], v[158:161], v[214:217], v[98:101]
	v_mfma_f32_16x16x32_bf16 v[94:97], v[168:171], v[186:189], v[94:97]
	v_mfma_f32_16x16x32_bf16 v[90:93], v[176:179], v[186:189], v[90:93]
	v_mfma_f32_16x16x32_bf16 v[86:89], v[168:171], v[194:197], v[86:89]
	v_mfma_f32_16x16x32_bf16 v[82:85], v[176:179], v[194:197], v[82:85]
	v_mfma_f32_16x16x32_bf16 v[78:81], v[168:171], v[202:205], v[78:81]
	v_mfma_f32_16x16x32_bf16 v[74:77], v[176:179], v[202:205], v[74:77]
	v_mfma_f32_16x16x32_bf16 v[70:73], v[168:171], v[210:213], v[70:73]
	v_mfma_f32_16x16x32_bf16 v[66:69], v[176:179], v[210:213], v[66:69]
	v_mfma_f32_16x16x32_bf16 v[94:97], v[172:175], v[190:193], v[94:97]
	v_mfma_f32_16x16x32_bf16 v[90:93], v[180:183], v[190:193], v[90:93]
	v_mfma_f32_16x16x32_bf16 v[86:89], v[172:175], v[198:201], v[86:89]
	v_mfma_f32_16x16x32_bf16 v[82:85], v[180:183], v[198:201], v[82:85]
	v_mfma_f32_16x16x32_bf16 v[78:81], v[172:175], v[206:209], v[78:81]
	v_mfma_f32_16x16x32_bf16 v[74:77], v[180:183], v[206:209], v[74:77]
	v_mfma_f32_16x16x32_bf16 v[70:73], v[172:175], v[214:217], v[70:73]
	v_mfma_f32_16x16x32_bf16 v[66:69], v[180:183], v[214:217], v[66:69]
	s_barrier
	s_setprio 0
	s_add_i32 s73, s64, s52
	v_lshl_add_u64 v[218:219], s[46:47], 0, v[132:133]
	s_mov_b32 m0, s73
	ds_read_b128 v[186:189], v167 offset:16384
	ds_read_b128 v[190:193], v167 offset:17408
	ds_read_b128 v[194:197], v167 offset:18432
	ds_read_b128 v[198:201], v167 offset:19456
	ds_read_b128 v[202:205], v167 offset:20480
	ds_read_b128 v[206:209], v167 offset:21504
	ds_read_b128 v[210:213], v167 offset:22528
	ds_read_b128 v[214:217], v167 offset:23552
	global_load_lds_dwordx4 v[218:219], off
	s_add_i32 m0, s73, 0x2000
	s_add_u32 s74, s46, 0x20000
	v_lshl_add_u64 v[220:221], s[46:47], 0, v[136:137]
	s_addc_u32 s75, s47, 0
	s_add_i32 s73, s65, s52
	global_load_lds_dwordx4 v[220:221], off
	v_lshl_add_u64 v[222:223], s[74:75], 0, v[132:133]
	s_mov_b32 m0, s73
	v_lshl_add_u64 v[224:225], s[48:49], 0, v[134:135]
	global_load_lds_dwordx4 v[222:223], off
	v_lshl_add_u64 v[222:223], s[74:75], 0, v[136:137]
	s_add_i32 m0, s73, 0x2000
	s_nop 0
	global_load_lds_dwordx4 v[222:223], off
	v_lshl_add_u64 v[222:223], s[48:49], 0, v[130:131]
	s_mov_b32 m0, s53
	s_nop 0
	global_load_lds_dwordx4 v[222:223], off
	s_mov_b32 m0, s54
	s_nop 0
	global_load_lds_dwordx4 v[224:225], off
	s_waitcnt vmcnt(8)
	s_waitcnt lgkmcnt(0)
	s_setprio 1
	s_barrier
; #define PG8_STAGE(bufoff, gbase, voff) do { _Pragma("unroll") for (int _i = 0; _i < 2; ++_i) \
;         __builtin_amdgcn_global_load_lds((const unsigned*)((const char*)(gbase) + (voff)[_i]), (LAS unsigned*)(lds + (bufoff) + ldsw + _i * 8192), 16, 0, 0); } while (0)
; #define PG8_LDA(dst, b, h) do { _Pragma("unroll") for (int m = 0; m < 4; ++m) _Pragma("unroll") for (int k = 0; k < 2; ++k) dst[m][k] = *(const LAS bf16x8*)(lds + PG8_SA(b, h) + aoff + m * 2048 + k * 1024); } while (0)
; #define PG8_LDB(dst, b, h) do { _Pragma("unroll") for (int n = 0; n < 2; ++n) _Pragma("unroll") for (int k = 0; k < 2; ++k) dst[n][k] = *(const LAS bf16x8*)(lds + PG8_SB(b, h) + boff + n * 2048 + k * 1024); } while (0)
; #define PG8_MMA(ai, bj, At, Bt) do { __builtin_amdgcn_s_setprio(1); _Pragma("unroll") for (int m = 0; m < 4; ++m) _Pragma("unroll") for (int n = 0; n < 2; ++n) _Pragma("unroll") for (int k = 0; k < 2; ++k) \
;         acc[ai][bj][m][n] = __builtin_amdgcn_mfma_f32_16x16x32_bf16(Bt[n][k], At[m][k], acc[ai][bj][m][n], 0, 0, 0); __builtin_amdgcn_s_setprio(0); } while (0)
; #define PG8_WAIT_V(n) asm volatile("s_waitcnt vmcnt(" #n ")" ::: "memory")
; #define PG8_WAIT_L(n) asm volatile("s_waitcnt lgkmcnt(" #n ")" ::: "memory")
; #define PG8_BAR __builtin_amdgcn_s_barrier()
; #define PG8_SCHED __builtin_amdgcn_sched_barrier(0)
; template <class Epi, class Sched>
; DI void gemm_phase(LAS unsigned char* lds, const Gemm g, const Sched& S, const Epi& E) {
;     ...
;             PG8_WAIT_V(8); PG8_WAIT_L(0); PG8_BAR; PG8_MMA(1, 0, At, B0); PG8_MMA(1, 1, At, B1); PG8_BAR; PG8_SCHED;
;             PG8_LDB(B0, 1, 0); PG8_LDB(B1, 1, 1); PG8_SCHED; PG8_LDA(At, 1, 0); PG8_STAGE(PG8_SA(0, 1), a2 + hstepA, voffA);
;             PG8_WAIT_V(8); PG8_WAIT_L(0); PG8_BAR; PG8_MMA(0, 0, At, B0); PG8_MMA(0, 1, At, B1); PG8_BAR; PG8_SCHED;
	v_mfma_f32_16x16x32_bf16 v[62:65], v[146:149], v[186:189], v[62:65]
	v_mfma_f32_16x16x32_bf16 v[58:61], v[154:157], v[186:189], v[58:61]
	v_mfma_f32_16x16x32_bf16 v[54:57], v[146:149], v[194:197], v[54:57]
	v_mfma_f32_16x16x32_bf16 v[50:53], v[154:157], v[194:197], v[50:53]
	v_mfma_f32_16x16x32_bf16 v[46:49], v[146:149], v[202:205], v[46:49]
	v_mfma_f32_16x16x32_bf16 v[42:45], v[154:157], v[202:205], v[42:45]
	v_mfma_f32_16x16x32_bf16 v[38:41], v[146:149], v[210:213], v[38:41]
	v_mfma_f32_16x16x32_bf16 v[34:37], v[154:157], v[210:213], v[34:37]
	v_mfma_f32_16x16x32_bf16 v[62:65], v[150:153], v[190:193], v[62:65]
	v_mfma_f32_16x16x32_bf16 v[58:61], v[158:161], v[190:193], v[58:61]
	v_mfma_f32_16x16x32_bf16 v[54:57], v[150:153], v[198:201], v[54:57]
	v_mfma_f32_16x16x32_bf16 v[50:53], v[158:161], v[198:201], v[50:53]
	v_mfma_f32_16x16x32_bf16 v[46:49], v[150:153], v[206:209], v[46:49]
	v_mfma_f32_16x16x32_bf16 v[42:45], v[158:161], v[206:209], v[42:45]
	v_mfma_f32_16x16x32_bf16 v[38:41], v[150:153], v[214:217], v[38:41]
	v_mfma_f32_16x16x32_bf16 v[34:37], v[158:161], v[214:217], v[34:37]
	v_mfma_f32_16x16x32_bf16 v[30:33], v[168:171], v[186:189], v[30:33]
	v_mfma_f32_16x16x32_bf16 v[26:29], v[176:179], v[186:189], v[26:29]
	v_mfma_f32_16x16x32_bf16 v[22:25], v[168:171], v[194:197], v[22:25]
	v_mfma_f32_16x16x32_bf16 v[18:21], v[176:179], v[194:197], v[18:21]
	v_mfma_f32_16x16x32_bf16 v[14:17], v[168:171], v[202:205], v[14:17]
	v_mfma_f32_16x16x32_bf16 v[10:13], v[176:179], v[202:205], v[10:13]
	v_mfma_f32_16x16x32_bf16 v[6:9], v[168:171], v[210:213], v[6:9]
	v_mfma_f32_16x16x32_bf16 v[2:5], v[176:179], v[210:213], v[2:5]
	v_mfma_f32_16x16x32_bf16 v[30:33], v[172:175], v[190:193], v[30:33]
	v_mfma_f32_16x16x32_bf16 v[26:29], v[180:183], v[190:193], v[26:29]
	v_mfma_f32_16x16x32_bf16 v[22:25], v[172:175], v[198:201], v[22:25]
	v_mfma_f32_16x16x32_bf16 v[18:21], v[180:183], v[198:201], v[18:21]
	v_mfma_f32_16x16x32_bf16 v[14:17], v[172:175], v[206:209], v[14:17]
	v_mfma_f32_16x16x32_bf16 v[10:13], v[180:183], v[206:209], v[10:13]
	v_mfma_f32_16x16x32_bf16 v[6:9], v[172:175], v[214:217], v[6:9]
	v_mfma_f32_16x16x32_bf16 v[2:5], v[180:183], v[214:217], v[2:5]
	s_barrier
	s_setprio 0
	s_add_i32 s73, 0, 0x18000
	s_add_i32 s74, 0, 0x1c000
	v_add_u32_e32 v158, s73, v162
	v_add_u32_e32 v180, s74, v162
	ds_read_b128 v[146:149], v158
	ds_read_b128 v[150:153], v158 offset:1024
	ds_read_b128 v[154:157], v158 offset:2048
	ds_read_b128 v[158:161], v158 offset:3072
	ds_read_b128 v[168:171], v180
	ds_read_b128 v[172:175], v180 offset:1024
	ds_read_b128 v[176:179], v180 offset:2048
	ds_read_b128 v[180:183], v180 offset:3072
	s_add_u32 s48, s48, 0x20000
	s_addc_u32 s49, s49, 0
	s_mov_b32 m0, s55
	v_lshl_add_u64 v[226:227], s[48:49], 0, v[130:131]
	ds_read_b128 v[186:189], v167 offset:32768
	ds_read_b128 v[190:193], v167 offset:33792
	ds_read_b128 v[194:197], v167 offset:34816
	ds_read_b128 v[198:201], v167 offset:35840
	ds_read_b128 v[202:205], v167 offset:36864
	ds_read_b128 v[206:209], v167 offset:37888
	ds_read_b128 v[210:213], v167 offset:38912
	ds_read_b128 v[214:217], v167 offset:39936
	global_load_lds_dwordx4 v[226:227], off
	v_lshl_add_u64 v[226:227], s[48:49], 0, v[134:135]
	s_mov_b32 m0, s56
	s_nop 0
	global_load_lds_dwordx4 v[226:227], off
	s_waitcnt vmcnt(8)
	s_waitcnt lgkmcnt(0)
	s_setprio 1
	s_barrier
	v_mfma_f32_16x16x32_bf16 v[126:129], v[146:149], v[186:189], v[126:129]
	v_mfma_f32_16x16x32_bf16 v[122:125], v[154:157], v[186:189], v[122:125]
	v_mfma_f32_16x16x32_bf16 v[118:121], v[146:149], v[194:197], v[118:121]
	v_mfma_f32_16x16x32_bf16 v[114:117], v[154:157], v[194:197], v[114:117]
	v_mfma_f32_16x16x32_bf16 v[110:113], v[146:149], v[202:205], v[110:113]
	v_mfma_f32_16x16x32_bf16 v[106:109], v[154:157], v[202:205], v[106:109]
	v_mfma_f32_16x16x32_bf16 v[102:105], v[146:149], v[210:213], v[102:105]
	v_mfma_f32_16x16x32_bf16 v[98:101], v[154:157], v[210:213], v[98:101]
	v_mfma_f32_16x16x32_bf16 v[126:129], v[150:153], v[190:193], v[126:129]
	v_mfma_f32_16x16x32_bf16 v[122:125], v[158:161], v[190:193], v[122:125]
	v_mfma_f32_16x16x32_bf16 v[118:121], v[150:153], v[198:201], v[118:121]
	v_mfma_f32_16x16x32_bf16 v[114:117], v[158:161], v[198:201], v[114:117]
	v_mfma_f32_16x16x32_bf16 v[110:113], v[150:153], v[206:209], v[110:113]
	v_mfma_f32_16x16x32_bf16 v[106:109], v[158:161], v[206:209], v[106:109]
	v_mfma_f32_16x16x32_bf16 v[102:105], v[150:153], v[214:217], v[102:105]
	v_mfma_f32_16x16x32_bf16 v[98:101], v[158:161], v[214:217], v[98:101]
	v_mfma_f32_16x16x32_bf16 v[94:97], v[168:171], v[186:189], v[94:97]
	v_mfma_f32_16x16x32_bf16 v[90:93], v[176:179], v[186:189], v[90:93]
	v_mfma_f32_16x16x32_bf16 v[86:89], v[168:171], v[194:197], v[86:89]
	v_mfma_f32_16x16x32_bf16 v[82:85], v[176:179], v[194:197], v[82:85]
	v_mfma_f32_16x16x32_bf16 v[78:81], v[168:171], v[202:205], v[78:81]
	v_mfma_f32_16x16x32_bf16 v[74:77], v[176:179], v[202:205], v[74:77]
	v_mfma_f32_16x16x32_bf16 v[70:73], v[168:171], v[210:213], v[70:73]
	v_mfma_f32_16x16x32_bf16 v[66:69], v[176:179], v[210:213], v[66:69]
	v_mfma_f32_16x16x32_bf16 v[94:97], v[172:175], v[190:193], v[94:97]
	v_mfma_f32_16x16x32_bf16 v[90:93], v[180:183], v[190:193], v[90:93]
	v_mfma_f32_16x16x32_bf16 v[86:89], v[172:175], v[198:201], v[86:89]
	v_mfma_f32_16x16x32_bf16 v[82:85], v[180:183], v[198:201], v[82:85]
	v_mfma_f32_16x16x32_bf16 v[78:81], v[172:175], v[206:209], v[78:81]
	v_mfma_f32_16x16x32_bf16 v[74:77], v[180:183], v[206:209], v[74:77]
	v_mfma_f32_16x16x32_bf16 v[70:73], v[172:175], v[214:217], v[70:73]
	v_mfma_f32_16x16x32_bf16 v[66:69], v[180:183], v[214:217], v[66:69]
	s_barrier
; #define PG8_STAGE(bufoff, gbase, voff) do { _Pragma("unroll") for (int _i = 0; _i < 2; ++_i) \
;         __builtin_amdgcn_global_load_lds((const unsigned*)((const char*)(gbase) + (voff)[_i]), (LAS unsigned*)(lds + (bufoff) + ldsw + _i * 8192), 16, 0, 0); } while (0)
; #define PG8_LDA(dst, b, h) do { _Pragma("unroll") for (int m = 0; m < 4; ++m) _Pragma("unroll") for (int k = 0; k < 2; ++k) dst[m][k] = *(const LAS bf16x8*)(lds + PG8_SA(b, h) + aoff + m * 2048 + k * 1024); } while (0)
; #define PG8_MMA(ai, bj, At, Bt) do { __builtin_amdgcn_s_setprio(1); _Pragma("unroll") for (int m = 0; m < 4; ++m) _Pragma("unroll") for (int n = 0; n < 2; ++n) _Pragma("unroll") for (int k = 0; k < 2; ++k) \
;         acc[ai][bj][m][n] = __builtin_amdgcn_mfma_f32_16x16x32_bf16(Bt[n][k], At[m][k], acc[ai][bj][m][n], 0, 0, 0); __builtin_amdgcn_s_setprio(0); } while (0)
; #define PG8_WAIT_V(n) asm volatile("s_waitcnt vmcnt(" #n ")" ::: "memory")
; #define PG8_WAIT_L(n) asm volatile("s_waitcnt lgkmcnt(" #n ")" ::: "memory")
; #define PG8_BAR __builtin_amdgcn_s_barrier()
; #define PG8_SCHED __builtin_amdgcn_sched_barrier(0)
; template <class Epi, class Sched>
; DI void gemm_phase(LAS unsigned char* lds, const Gemm g, const Sched& S, const Epi& E) {
;     ...
;             PG8_LDA(At, 1, 1); PG8_STAGE(PG8_SB(1, 0), b3, voffB); PG8_STAGE(PG8_SB(1, 1), b3 + hstepB, voffB); PG8_STAGE(PG8_SA(1, 0), a3, voffA);
;             PG8_WAIT_V(8); PG8_WAIT_L(0); PG8_BAR; PG8_MMA(1, 0, At, B0); PG8_MMA(1, 1, At, B1); PG8_BAR; PG8_SCHED;
;         }
;         if (wr == 0) PG8_BAR;
	s_setprio 0
	s_add_i32 s48, s73, s52
	v_lshl_add_u64 v[218:219], v[218:219], 0, s[20:21]
	s_mov_b32 m0, s48
	ds_read_b128 v[186:189], v167 offset:49152
	ds_read_b128 v[190:193], v167 offset:50176
	ds_read_b128 v[194:197], v167 offset:51200
	ds_read_b128 v[198:201], v167 offset:52224
	ds_read_b128 v[202:205], v167 offset:53248
	ds_read_b128 v[206:209], v167 offset:54272
	ds_read_b128 v[210:213], v167 offset:55296
	ds_read_b128 v[214:217], v167 offset:56320
	global_load_lds_dwordx4 v[218:219], off
	s_add_i32 m0, s48, 0x2000
	s_add_u32 s46, s46, 0x20080
	v_lshl_add_u64 v[218:219], v[220:221], 0, s[20:21]
	s_addc_u32 s47, s47, 0
	s_add_i32 s48, s74, s52
	global_load_lds_dwordx4 v[218:219], off
	v_lshl_add_u64 v[218:219], s[46:47], 0, v[132:133]
	s_mov_b32 m0, s48
	s_nop 0
	global_load_lds_dwordx4 v[218:219], off
	v_lshl_add_u64 v[218:219], s[46:47], 0, v[136:137]
	s_add_i32 m0, s48, 0x2000
	s_nop 0
	global_load_lds_dwordx4 v[218:219], off
	v_lshl_add_u64 v[218:219], v[222:223], 0, s[20:21]
	s_mov_b32 m0, s61
	s_nop 0
	global_load_lds_dwordx4 v[218:219], off
	v_lshl_add_u64 v[218:219], v[224:225], 0, s[20:21]
	s_mov_b32 m0, s62
	s_nop 0
	global_load_lds_dwordx4 v[218:219], off
	s_waitcnt vmcnt(8)
	s_waitcnt lgkmcnt(0)
	s_setprio 1
	s_barrier
	v_mfma_f32_16x16x32_bf16 v[62:65], v[146:149], v[186:189], v[62:65]
	v_mfma_f32_16x16x32_bf16 v[58:61], v[154:157], v[186:189], v[58:61]
	v_mfma_f32_16x16x32_bf16 v[54:57], v[146:149], v[194:197], v[54:57]
	v_mfma_f32_16x16x32_bf16 v[50:53], v[154:157], v[194:197], v[50:53]
	v_mfma_f32_16x16x32_bf16 v[46:49], v[146:149], v[202:205], v[46:49]
	v_mfma_f32_16x16x32_bf16 v[42:45], v[154:157], v[202:205], v[42:45]
	v_mfma_f32_16x16x32_bf16 v[38:41], v[146:149], v[210:213], v[38:41]
	v_mfma_f32_16x16x32_bf16 v[34:37], v[154:157], v[210:213], v[34:37]
	v_mfma_f32_16x16x32_bf16 v[62:65], v[150:153], v[190:193], v[62:65]
	v_mfma_f32_16x16x32_bf16 v[58:61], v[158:161], v[190:193], v[58:61]
	v_mfma_f32_16x16x32_bf16 v[54:57], v[150:153], v[198:201], v[54:57]
	v_mfma_f32_16x16x32_bf16 v[50:53], v[158:161], v[198:201], v[50:53]
	v_mfma_f32_16x16x32_bf16 v[46:49], v[150:153], v[206:209], v[46:49]
	v_mfma_f32_16x16x32_bf16 v[42:45], v[158:161], v[206:209], v[42:45]
	v_mfma_f32_16x16x32_bf16 v[38:41], v[150:153], v[214:217], v[38:41]
	v_mfma_f32_16x16x32_bf16 v[34:37], v[158:161], v[214:217], v[34:37]
	v_mfma_f32_16x16x32_bf16 v[30:33], v[168:171], v[186:189], v[30:33]
	v_mfma_f32_16x16x32_bf16 v[26:29], v[176:179], v[186:189], v[26:29]
	v_mfma_f32_16x16x32_bf16 v[22:25], v[168:171], v[194:197], v[22:25]
	v_mfma_f32_16x16x32_bf16 v[18:21], v[176:179], v[194:197], v[18:21]
	v_mfma_f32_16x16x32_bf16 v[14:17], v[168:171], v[202:205], v[14:17]
	v_mfma_f32_16x16x32_bf16 v[10:13], v[176:179], v[202:205], v[10:13]
	v_mfma_f32_16x16x32_bf16 v[6:9], v[168:171], v[210:213], v[6:9]
	v_mfma_f32_16x16x32_bf16 v[2:5], v[176:179], v[210:213], v[2:5]
	v_mfma_f32_16x16x32_bf16 v[30:33], v[172:175], v[190:193], v[30:33]
	v_mfma_f32_16x16x32_bf16 v[26:29], v[180:183], v[190:193], v[26:29]
	v_mfma_f32_16x16x32_bf16 v[22:25], v[172:175], v[198:201], v[22:25]
	v_mfma_f32_16x16x32_bf16 v[18:21], v[180:183], v[198:201], v[18:21]
	v_mfma_f32_16x16x32_bf16 v[14:17], v[172:175], v[206:209], v[14:17]
	v_mfma_f32_16x16x32_bf16 v[10:13], v[180:183], v[206:209], v[10:13]
	v_mfma_f32_16x16x32_bf16 v[6:9], v[172:175], v[214:217], v[6:9]
	v_mfma_f32_16x16x32_bf16 v[2:5], v[180:183], v[214:217], v[2:5]
	s_barrier
	s_setprio 0
	s_add_i32 s72, s72, 2
	s_add_u32 s44, s44, 0x100
	s_addc_u32 s45, s45, 0
	s_add_u32 s70, s70, 0x100
	s_addc_u32 s71, s71, 0
	s_cmp_gt_u32 s72, 5
	s_cbranch_scc0 .LBB0_972
	s_and_b64 vcc, exec, s[34:35]
	s_cbranch_vccz .LBB0_975
	s_barrier

; #define PG8_STAGE(bufoff, gbase, voff) do { _Pragma("unroll") for (int _i = 0; _i < 2; ++_i) \
;         __builtin_amdgcn_global_load_lds((const unsigned*)((const char*)(gbase) + (voff)[_i]), (LAS unsigned*)(lds + (bufoff) + ldsw + _i * 8192), 16, 0, 0); } while (0)
; #define PG8_LDA(dst, b, h) do { _Pragma("unroll") for (int m = 0; m < 4; ++m) _Pragma("unroll") for (int k = 0; k < 2; ++k) dst[m][k] = *(const LAS bf16x8*)(lds + PG8_SA(b, h) + aoff + m * 2048 + k * 1024); } while (0)
; #define PG8_LDB(dst, b, h) do { _Pragma("unroll") for (int n = 0; n < 2; ++n) _Pragma("unroll") for (int k = 0; k < 2; ++k) dst[n][k] = *(const LAS bf16x8*)(lds + PG8_SB(b, h) + boff + n * 2048 + k * 1024); } while (0)
; #define PG8_MMA(ai, bj, At, Bt) do { __builtin_amdgcn_s_setprio(1); _Pragma("unroll") for (int m = 0; m < 4; ++m) _Pragma("unroll") for (int n = 0; n < 2; ++n) _Pragma("unroll") for (int k = 0; k < 2; ++k) \
;         acc[ai][bj][m][n] = __builtin_amdgcn_mfma_f32_16x16x32_bf16(Bt[n][k], At[m][k], acc[ai][bj][m][n], 0, 0, 0); __builtin_amdgcn_s_setprio(0); } while (0)
; #define PG8_WAIT_V(n) asm volatile("s_waitcnt vmcnt(" #n ")" ::: "memory")
; #define PG8_WAIT_L(n) asm volatile("s_waitcnt lgkmcnt(" #n ")" ::: "memory")
; #define PG8_BAR __builtin_amdgcn_s_barrier()
; #define PG8_SCHED __builtin_amdgcn_sched_barrier(0)
; template <class Epi, class Sched>
; DI void gemm_phase(LAS unsigned char* lds, const Gemm g, const Sched& S, const Epi& E) {
;     ...
;             PG8_LDB(B0, 0, 0); PG8_LDB(B1, 0, 1); PG8_SCHED; PG8_LDA(At, 0, 0); PG8_STAGE(PG8_SA(1, 1), a1 + hstepA, voffA);
;             PG8_WAIT_V(8); PG8_WAIT_L(0); PG8_BAR; PG8_MMA(0, 0, At, B0); PG8_MMA(0, 1, At, B1); PG8_BAR; PG8_SCHED;
;             PG8_LDA(At, 0, 1); PG8_STAGE(PG8_SB(0, 0), b2, voffB); PG8_STAGE(PG8_SB(0, 1), b2 + hstepB, voffB); PG8_STAGE(PG8_SA(0, 0), a2, voffA);
.LBB0_1133:
	ds_read_b128 v[146:149], v152
	ds_read_b128 v[156:159], v152 offset:1024
	ds_read_b128 v[160:163], v152 offset:2048
	ds_read_b128 v[164:167], v152 offset:3072
	ds_read_b128 v[168:171], v153
	ds_read_b128 v[172:175], v153 offset:1024
	ds_read_b128 v[176:179], v153 offset:2048
	ds_read_b128 v[180:183], v153 offset:3072
	s_add_u32 s46, s44, 0xfffc0080
	s_addc_u32 s47, s45, -1
	s_cmp_eq_u32 s66, 12
	s_cselect_b32 s49, s35, s47
	s_cselect_b32 s48, s41, s46
	s_cselect_b32 s47, s21, s65
	s_cselect_b32 s46, s63, s64
	v_lshl_add_u64 v[218:219], s[44:45], 0, v[138:139]
	s_add_i32 m0, s43, 0xc000
	ds_read_b128 v[186:189], v154
	ds_read_b128 v[190:193], v154 offset:1024
	ds_read_b128 v[194:197], v154 offset:2048
	ds_read_b128 v[198:201], v154 offset:3072
	ds_read_b128 v[202:205], v154 offset:4096
	ds_read_b128 v[206:209], v154 offset:5120
	ds_read_b128 v[210:213], v154 offset:6144
	ds_read_b128 v[214:217], v154 offset:7168
	global_load_lds_dwordx4 v[218:219], off
	v_lshl_add_u64 v[218:219], s[44:45], 0, v[140:141]
	s_add_i32 m0, s43, 0xe000
	s_nop 0
	global_load_lds_dwordx4 v[218:219], off
	s_waitcnt vmcnt(8)
	s_waitcnt lgkmcnt(0)
	s_setprio 1
	s_barrier
	v_mfma_f32_16x16x32_bf16 v[126:129], v[146:149], v[186:189], v[126:129]
	v_mfma_f32_16x16x32_bf16 v[122:125], v[160:163], v[186:189], v[122:125]
	v_mfma_f32_16x16x32_bf16 v[110:113], v[146:149], v[194:197], v[110:113]
	v_mfma_f32_16x16x32_bf16 v[106:109], v[160:163], v[194:197], v[106:109]
	v_mfma_f32_16x16x32_bf16 v[94:97], v[146:149], v[202:205], v[94:97]
	v_mfma_f32_16x16x32_bf16 v[90:93], v[160:163], v[202:205], v[90:93]
	v_mfma_f32_16x16x32_bf16 v[78:81], v[146:149], v[210:213], v[78:81]
	v_mfma_f32_16x16x32_bf16 v[74:77], v[160:163], v[210:213], v[74:77]
	v_mfma_f32_16x16x32_bf16 v[126:129], v[156:159], v[190:193], v[126:129]
	v_mfma_f32_16x16x32_bf16 v[122:125], v[164:167], v[190:193], v[122:125]
	v_mfma_f32_16x16x32_bf16 v[110:113], v[156:159], v[198:201], v[110:113]
	v_mfma_f32_16x16x32_bf16 v[106:109], v[164:167], v[198:201], v[106:109]
	v_mfma_f32_16x16x32_bf16 v[94:97], v[156:159], v[206:209], v[94:97]
	v_mfma_f32_16x16x32_bf16 v[90:93], v[164:167], v[206:209], v[90:93]
	v_mfma_f32_16x16x32_bf16 v[78:81], v[156:159], v[214:217], v[78:81]
	v_mfma_f32_16x16x32_bf16 v[74:77], v[164:167], v[214:217], v[74:77]
	v_mfma_f32_16x16x32_bf16 v[118:121], v[168:171], v[186:189], v[118:121]
	v_mfma_f32_16x16x32_bf16 v[114:117], v[176:179], v[186:189], v[114:117]
	v_mfma_f32_16x16x32_bf16 v[102:105], v[168:171], v[194:197], v[102:105]
	v_mfma_f32_16x16x32_bf16 v[98:101], v[176:179], v[194:197], v[98:101]
	v_mfma_f32_16x16x32_bf16 v[86:89], v[168:171], v[202:205], v[86:89]
	v_mfma_f32_16x16x32_bf16 v[82:85], v[176:179], v[202:205], v[82:85]
	v_mfma_f32_16x16x32_bf16 v[70:73], v[168:171], v[210:213], v[70:73]
	v_mfma_f32_16x16x32_bf16 v[66:69], v[176:179], v[210:213], v[66:69]
	v_mfma_f32_16x16x32_bf16 v[118:121], v[172:175], v[190:193], v[118:121]
	v_mfma_f32_16x16x32_bf16 v[114:117], v[180:183], v[190:193], v[114:117]
	v_mfma_f32_16x16x32_bf16 v[102:105], v[172:175], v[198:201], v[102:105]
	v_mfma_f32_16x16x32_bf16 v[98:101], v[180:183], v[198:201], v[98:101]
	v_mfma_f32_16x16x32_bf16 v[86:89], v[172:175], v[206:209], v[86:89]
	v_mfma_f32_16x16x32_bf16 v[82:85], v[180:183], v[206:209], v[82:85]
	v_mfma_f32_16x16x32_bf16 v[70:73], v[172:175], v[214:217], v[70:73]
	v_mfma_f32_16x16x32_bf16 v[66:69], v[180:183], v[214:217], v[66:69]
	s_barrier
	s_setprio 0
	s_add_i32 s67, s61, s52
	v_lshl_add_u64 v[218:219], s[46:47], 0, v[132:133]
	s_mov_b32 m0, s67
	ds_read_b128 v[186:189], v154 offset:16384
	ds_read_b128 v[190:193], v154 offset:17408
	ds_read_b128 v[194:197], v154 offset:18432
	ds_read_b128 v[198:201], v154 offset:19456
	ds_read_b128 v[202:205], v154 offset:20480
	ds_read_b128 v[206:209], v154 offset:21504
	ds_read_b128 v[210:213], v154 offset:22528
	ds_read_b128 v[214:217], v154 offset:23552
	global_load_lds_dwordx4 v[218:219], off
	s_add_i32 m0, s67, 0x2000
	s_add_u32 s68, s46, 0x40000
	v_lshl_add_u64 v[220:221], s[46:47], 0, v[136:137]
	s_addc_u32 s69, s47, 0
	s_add_i32 s67, s62, s52
	global_load_lds_dwordx4 v[220:221], off
	v_lshl_add_u64 v[222:223], s[68:69], 0, v[132:133]
	s_mov_b32 m0, s67
	v_lshl_add_u64 v[224:225], s[48:49], 0, v[134:135]
	global_load_lds_dwordx4 v[222:223], off
	v_lshl_add_u64 v[222:223], s[68:69], 0, v[136:137]
	s_add_i32 m0, s67, 0x2000
	s_nop 0
	global_load_lds_dwordx4 v[222:223], off
	v_lshl_add_u64 v[222:223], s[48:49], 0, v[130:131]
	s_mov_b32 m0, s43
	s_nop 0
	global_load_lds_dwordx4 v[222:223], off
	s_mov_b32 m0, s53
	s_nop 0
	global_load_lds_dwordx4 v[224:225], off
	s_waitcnt vmcnt(8)
	s_waitcnt lgkmcnt(0)
	s_setprio 1
	s_barrier
; #define PG8_STAGE(bufoff, gbase, voff) do { _Pragma("unroll") for (int _i = 0; _i < 2; ++_i) \
;         __builtin_amdgcn_global_load_lds((const unsigned*)((const char*)(gbase) + (voff)[_i]), (LAS unsigned*)(lds + (bufoff) + ldsw + _i * 8192), 16, 0, 0); } while (0)
; #define PG8_LDA(dst, b, h) do { _Pragma("unroll") for (int m = 0; m < 4; ++m) _Pragma("unroll") for (int k = 0; k < 2; ++k) dst[m][k] = *(const LAS bf16x8*)(lds + PG8_SA(b, h) + aoff + m * 2048 + k * 1024); } while (0)
; #define PG8_LDB(dst, b, h) do { _Pragma("unroll") for (int n = 0; n < 2; ++n) _Pragma("unroll") for (int k = 0; k < 2; ++k) dst[n][k] = *(const LAS bf16x8*)(lds + PG8_SB(b, h) + boff + n * 2048 + k * 1024); } while (0)
; #define PG8_MMA(ai, bj, At, Bt) do { __builtin_amdgcn_s_setprio(1); _Pragma("unroll") for (int m = 0; m < 4; ++m) _Pragma("unroll") for (int n = 0; n < 2; ++n) _Pragma("unroll") for (int k = 0; k < 2; ++k) \
;         acc[ai][bj][m][n] = __builtin_amdgcn_mfma_f32_16x16x32_bf16(Bt[n][k], At[m][k], acc[ai][bj][m][n], 0, 0, 0); __builtin_amdgcn_s_setprio(0); } while (0)
; #define PG8_WAIT_V(n) asm volatile("s_waitcnt vmcnt(" #n ")" ::: "memory")
; #define PG8_WAIT_L(n) asm volatile("s_waitcnt lgkmcnt(" #n ")" ::: "memory")
; #define PG8_BAR __builtin_amdgcn_s_barrier()
; #define PG8_SCHED __builtin_amdgcn_sched_barrier(0)
; template <class Epi, class Sched>
; DI void gemm_phase(LAS unsigned char* lds, const Gemm g, const Sched& S, const Epi& E) {
;     ...
;             PG8_WAIT_V(8); PG8_WAIT_L(0); PG8_BAR; PG8_MMA(1, 0, At, B0); PG8_MMA(1, 1, At, B1); PG8_BAR; PG8_SCHED;
;             PG8_LDB(B0, 1, 0); PG8_LDB(B1, 1, 1); PG8_SCHED; PG8_LDA(At, 1, 0); PG8_STAGE(PG8_SA(0, 1), a2 + hstepA, voffA);
;             PG8_WAIT_V(8); PG8_WAIT_L(0); PG8_BAR; PG8_MMA(0, 0, At, B0); PG8_MMA(0, 1, At, B1); PG8_BAR; PG8_SCHED;
	v_mfma_f32_16x16x32_bf16 v[62:65], v[146:149], v[186:189], v[62:65]
	v_mfma_f32_16x16x32_bf16 v[58:61], v[160:163], v[186:189], v[58:61]
	v_mfma_f32_16x16x32_bf16 v[46:49], v[146:149], v[194:197], v[46:49]
	v_mfma_f32_16x16x32_bf16 v[42:45], v[160:163], v[194:197], v[42:45]
	v_mfma_f32_16x16x32_bf16 v[30:33], v[146:149], v[202:205], v[30:33]
	v_mfma_f32_16x16x32_bf16 v[26:29], v[160:163], v[202:205], v[26:29]
	v_mfma_f32_16x16x32_bf16 v[14:17], v[146:149], v[210:213], v[14:17]
	v_mfma_f32_16x16x32_bf16 v[10:13], v[160:163], v[210:213], v[10:13]
	v_mfma_f32_16x16x32_bf16 v[62:65], v[156:159], v[190:193], v[62:65]
	v_mfma_f32_16x16x32_bf16 v[58:61], v[164:167], v[190:193], v[58:61]
	v_mfma_f32_16x16x32_bf16 v[46:49], v[156:159], v[198:201], v[46:49]
	v_mfma_f32_16x16x32_bf16 v[42:45], v[164:167], v[198:201], v[42:45]
	v_mfma_f32_16x16x32_bf16 v[30:33], v[156:159], v[206:209], v[30:33]
	v_mfma_f32_16x16x32_bf16 v[26:29], v[164:167], v[206:209], v[26:29]
	v_mfma_f32_16x16x32_bf16 v[14:17], v[156:159], v[214:217], v[14:17]
	v_mfma_f32_16x16x32_bf16 v[10:13], v[164:167], v[214:217], v[10:13]
	v_mfma_f32_16x16x32_bf16 v[54:57], v[168:171], v[186:189], v[54:57]
	v_mfma_f32_16x16x32_bf16 v[50:53], v[176:179], v[186:189], v[50:53]
	v_mfma_f32_16x16x32_bf16 v[38:41], v[168:171], v[194:197], v[38:41]
	v_mfma_f32_16x16x32_bf16 v[34:37], v[176:179], v[194:197], v[34:37]
	v_mfma_f32_16x16x32_bf16 v[22:25], v[168:171], v[202:205], v[22:25]
	v_mfma_f32_16x16x32_bf16 v[18:21], v[176:179], v[202:205], v[18:21]
	v_mfma_f32_16x16x32_bf16 v[6:9], v[168:171], v[210:213], v[6:9]
	v_mfma_f32_16x16x32_bf16 v[2:5], v[176:179], v[210:213], v[2:5]
	v_mfma_f32_16x16x32_bf16 v[54:57], v[172:175], v[190:193], v[54:57]
	v_mfma_f32_16x16x32_bf16 v[50:53], v[180:183], v[190:193], v[50:53]
	v_mfma_f32_16x16x32_bf16 v[38:41], v[172:175], v[198:201], v[38:41]
	v_mfma_f32_16x16x32_bf16 v[34:37], v[180:183], v[198:201], v[34:37]
	v_mfma_f32_16x16x32_bf16 v[22:25], v[172:175], v[206:209], v[22:25]
	v_mfma_f32_16x16x32_bf16 v[18:21], v[180:183], v[206:209], v[18:21]
	v_mfma_f32_16x16x32_bf16 v[6:9], v[172:175], v[214:217], v[6:9]
	v_mfma_f32_16x16x32_bf16 v[2:5], v[180:183], v[214:217], v[2:5]
	s_barrier
	s_setprio 0
	s_add_i32 s67, 0, 0x18000
	s_add_i32 s68, 0, 0x1c000
	v_add_u32_e32 v164, s67, v150
	v_add_u32_e32 v180, s68, v150
	ds_read_b128 v[146:149], v164
	ds_read_b128 v[156:159], v164 offset:1024
	ds_read_b128 v[160:163], v164 offset:2048
	ds_read_b128 v[164:167], v164 offset:3072
	ds_read_b128 v[168:171], v180
	ds_read_b128 v[172:175], v180 offset:1024
	ds_read_b128 v[176:179], v180 offset:2048
	ds_read_b128 v[180:183], v180 offset:3072
	s_add_u32 s48, s48, 0x40000
	s_addc_u32 s49, s49, 0
	s_mov_b32 m0, s54
	v_lshl_add_u64 v[226:227], s[48:49], 0, v[130:131]
	ds_read_b128 v[186:189], v154 offset:32768
	ds_read_b128 v[190:193], v154 offset:33792
	ds_read_b128 v[194:197], v154 offset:34816
	ds_read_b128 v[198:201], v154 offset:35840
	ds_read_b128 v[202:205], v154 offset:36864
	ds_read_b128 v[206:209], v154 offset:37888
	ds_read_b128 v[210:213], v154 offset:38912
	ds_read_b128 v[214:217], v154 offset:39936
	global_load_lds_dwordx4 v[226:227], off
	v_lshl_add_u64 v[226:227], s[48:49], 0, v[134:135]
	s_mov_b32 m0, s55
	s_nop 0
	global_load_lds_dwordx4 v[226:227], off
	s_waitcnt vmcnt(8)
	s_waitcnt lgkmcnt(0)
	s_setprio 1
	s_barrier
	v_mfma_f32_16x16x32_bf16 v[126:129], v[146:149], v[186:189], v[126:129]
	v_mfma_f32_16x16x32_bf16 v[122:125], v[160:163], v[186:189], v[122:125]
	v_mfma_f32_16x16x32_bf16 v[110:113], v[146:149], v[194:197], v[110:113]
	v_mfma_f32_16x16x32_bf16 v[106:109], v[160:163], v[194:197], v[106:109]
	v_mfma_f32_16x16x32_bf16 v[94:97], v[146:149], v[202:205], v[94:97]
	v_mfma_f32_16x16x32_bf16 v[90:93], v[160:163], v[202:205], v[90:93]
	v_mfma_f32_16x16x32_bf16 v[78:81], v[146:149], v[210:213], v[78:81]
	v_mfma_f32_16x16x32_bf16 v[74:77], v[160:163], v[210:213], v[74:77]
	v_mfma_f32_16x16x32_bf16 v[126:129], v[156:159], v[190:193], v[126:129]
	v_mfma_f32_16x16x32_bf16 v[122:125], v[164:167], v[190:193], v[122:125]
	v_mfma_f32_16x16x32_bf16 v[110:113], v[156:159], v[198:201], v[110:113]
	v_mfma_f32_16x16x32_bf16 v[106:109], v[164:167], v[198:201], v[106:109]
	v_mfma_f32_16x16x32_bf16 v[94:97], v[156:159], v[206:209], v[94:97]
	v_mfma_f32_16x16x32_bf16 v[90:93], v[164:167], v[206:209], v[90:93]
	v_mfma_f32_16x16x32_bf16 v[78:81], v[156:159], v[214:217], v[78:81]
	v_mfma_f32_16x16x32_bf16 v[74:77], v[164:167], v[214:217], v[74:77]
	v_mfma_f32_16x16x32_bf16 v[118:121], v[168:171], v[186:189], v[118:121]
	v_mfma_f32_16x16x32_bf16 v[114:117], v[176:179], v[186:189], v[114:117]
	v_mfma_f32_16x16x32_bf16 v[102:105], v[168:171], v[194:197], v[102:105]
	v_mfma_f32_16x16x32_bf16 v[98:101], v[176:179], v[194:197], v[98:101]
	v_mfma_f32_16x16x32_bf16 v[86:89], v[168:171], v[202:205], v[86:89]
	v_mfma_f32_16x16x32_bf16 v[82:85], v[176:179], v[202:205], v[82:85]
	v_mfma_f32_16x16x32_bf16 v[70:73], v[168:171], v[210:213], v[70:73]
	v_mfma_f32_16x16x32_bf16 v[66:69], v[176:179], v[210:213], v[66:69]
	v_mfma_f32_16x16x32_bf16 v[118:121], v[172:175], v[190:193], v[118:121]
	v_mfma_f32_16x16x32_bf16 v[114:117], v[180:183], v[190:193], v[114:117]
	v_mfma_f32_16x16x32_bf16 v[102:105], v[172:175], v[198:201], v[102:105]
	v_mfma_f32_16x16x32_bf16 v[98:101], v[180:183], v[198:201], v[98:101]
	v_mfma_f32_16x16x32_bf16 v[86:89], v[172:175], v[206:209], v[86:89]
	v_mfma_f32_16x16x32_bf16 v[82:85], v[180:183], v[206:209], v[82:85]
	v_mfma_f32_16x16x32_bf16 v[70:73], v[172:175], v[214:217], v[70:73]
	v_mfma_f32_16x16x32_bf16 v[66:69], v[180:183], v[214:217], v[66:69]
	s_barrier
; #define PG8_STAGE(bufoff, gbase, voff) do { _Pragma("unroll") for (int _i = 0; _i < 2; ++_i) \
;         __builtin_amdgcn_global_load_lds((const unsigned*)((const char*)(gbase) + (voff)[_i]), (LAS unsigned*)(lds + (bufoff) + ldsw + _i * 8192), 16, 0, 0); } while (0)
; #define PG8_LDA(dst, b, h) do { _Pragma("unroll") for (int m = 0; m < 4; ++m) _Pragma("unroll") for (int k = 0; k < 2; ++k) dst[m][k] = *(const LAS bf16x8*)(lds + PG8_SA(b, h) + aoff + m * 2048 + k * 1024); } while (0)
; #define PG8_MMA(ai, bj, At, Bt) do { __builtin_amdgcn_s_setprio(1); _Pragma("unroll") for (int m = 0; m < 4; ++m) _Pragma("unroll") for (int n = 0; n < 2; ++n) _Pragma("unroll") for (int k = 0; k < 2; ++k) \
;         acc[ai][bj][m][n] = __builtin_amdgcn_mfma_f32_16x16x32_bf16(Bt[n][k], At[m][k], acc[ai][bj][m][n], 0, 0, 0); __builtin_amdgcn_s_setprio(0); } while (0)
; #define PG8_WAIT_V(n) asm volatile("s_waitcnt vmcnt(" #n ")" ::: "memory")
; #define PG8_WAIT_L(n) asm volatile("s_waitcnt lgkmcnt(" #n ")" ::: "memory")
; #define PG8_BAR __builtin_amdgcn_s_barrier()
; #define PG8_SCHED __builtin_amdgcn_sched_barrier(0)
; template <class Epi, class Sched>
; DI void gemm_phase(LAS unsigned char* lds, const Gemm g, const Sched& S, const Epi& E) {
;     ...
;             PG8_LDA(At, 1, 1); PG8_STAGE(PG8_SB(1, 0), b3, voffB); PG8_STAGE(PG8_SB(1, 1), b3 + hstepB, voffB); PG8_STAGE(PG8_SA(1, 0), a3, voffA);
;             PG8_WAIT_V(8); PG8_WAIT_L(0); PG8_BAR; PG8_MMA(1, 0, At, B0); PG8_MMA(1, 1, At, B1); PG8_BAR; PG8_SCHED;
;         }
;         if (wr == 0) PG8_BAR;
	s_setprio 0
	s_add_i32 s48, s67, s52
	v_lshl_add_u64 v[218:219], v[218:219], 0, s[16:17]
	s_mov_b32 m0, s48
	ds_read_b128 v[186:189], v154 offset:49152
	ds_read_b128 v[190:193], v154 offset:50176
	ds_read_b128 v[194:197], v154 offset:51200
	ds_read_b128 v[198:201], v154 offset:52224
	ds_read_b128 v[202:205], v154 offset:53248
	ds_read_b128 v[206:209], v154 offset:54272
	ds_read_b128 v[210:213], v154 offset:55296
	ds_read_b128 v[214:217], v154 offset:56320
	global_load_lds_dwordx4 v[218:219], off
	s_add_i32 m0, s48, 0x2000
	s_add_u32 s46, s46, 0x40080
	v_lshl_add_u64 v[218:219], v[220:221], 0, s[16:17]
	s_addc_u32 s47, s47, 0
	s_add_i32 s48, s68, s52
	global_load_lds_dwordx4 v[218:219], off
	v_lshl_add_u64 v[218:219], s[46:47], 0, v[132:133]
	s_mov_b32 m0, s48
	s_nop 0
	global_load_lds_dwordx4 v[218:219], off
	v_lshl_add_u64 v[218:219], s[46:47], 0, v[136:137]
	s_add_i32 m0, s48, 0x2000
	s_nop 0
	global_load_lds_dwordx4 v[218:219], off
	v_lshl_add_u64 v[218:219], v[222:223], 0, s[16:17]
	s_mov_b32 m0, s57
	s_nop 0
	global_load_lds_dwordx4 v[218:219], off
	v_lshl_add_u64 v[218:219], v[224:225], 0, s[16:17]
	s_mov_b32 m0, s58
	s_nop 0
	global_load_lds_dwordx4 v[218:219], off
	s_waitcnt vmcnt(8)
	s_waitcnt lgkmcnt(0)
	s_setprio 1
	s_barrier
	v_mfma_f32_16x16x32_bf16 v[62:65], v[146:149], v[186:189], v[62:65]
	v_mfma_f32_16x16x32_bf16 v[58:61], v[160:163], v[186:189], v[58:61]
	v_mfma_f32_16x16x32_bf16 v[46:49], v[146:149], v[194:197], v[46:49]
	v_mfma_f32_16x16x32_bf16 v[42:45], v[160:163], v[194:197], v[42:45]
	v_mfma_f32_16x16x32_bf16 v[30:33], v[146:149], v[202:205], v[30:33]
	v_mfma_f32_16x16x32_bf16 v[26:29], v[160:163], v[202:205], v[26:29]
	v_mfma_f32_16x16x32_bf16 v[14:17], v[146:149], v[210:213], v[14:17]
	v_mfma_f32_16x16x32_bf16 v[10:13], v[160:163], v[210:213], v[10:13]
	v_mfma_f32_16x16x32_bf16 v[62:65], v[156:159], v[190:193], v[62:65]
	v_mfma_f32_16x16x32_bf16 v[58:61], v[164:167], v[190:193], v[58:61]
	v_mfma_f32_16x16x32_bf16 v[46:49], v[156:159], v[198:201], v[46:49]
	v_mfma_f32_16x16x32_bf16 v[42:45], v[164:167], v[198:201], v[42:45]
	v_mfma_f32_16x16x32_bf16 v[30:33], v[156:159], v[206:209], v[30:33]
	v_mfma_f32_16x16x32_bf16 v[26:29], v[164:167], v[206:209], v[26:29]
	v_mfma_f32_16x16x32_bf16 v[14:17], v[156:159], v[214:217], v[14:17]
	v_mfma_f32_16x16x32_bf16 v[10:13], v[164:167], v[214:217], v[10:13]
	v_mfma_f32_16x16x32_bf16 v[54:57], v[168:171], v[186:189], v[54:57]
	v_mfma_f32_16x16x32_bf16 v[50:53], v[176:179], v[186:189], v[50:53]
	v_mfma_f32_16x16x32_bf16 v[38:41], v[168:171], v[194:197], v[38:41]
	v_mfma_f32_16x16x32_bf16 v[34:37], v[176:179], v[194:197], v[34:37]
	v_mfma_f32_16x16x32_bf16 v[22:25], v[168:171], v[202:205], v[22:25]
	v_mfma_f32_16x16x32_bf16 v[18:21], v[176:179], v[202:205], v[18:21]
	v_mfma_f32_16x16x32_bf16 v[6:9], v[168:171], v[210:213], v[6:9]
	v_mfma_f32_16x16x32_bf16 v[2:5], v[176:179], v[210:213], v[2:5]
	v_mfma_f32_16x16x32_bf16 v[54:57], v[172:175], v[190:193], v[54:57]
	v_mfma_f32_16x16x32_bf16 v[50:53], v[180:183], v[190:193], v[50:53]
	v_mfma_f32_16x16x32_bf16 v[38:41], v[172:175], v[198:201], v[38:41]
	v_mfma_f32_16x16x32_bf16 v[34:37], v[180:183], v[198:201], v[34:37]
	v_mfma_f32_16x16x32_bf16 v[22:25], v[172:175], v[206:209], v[22:25]
	v_mfma_f32_16x16x32_bf16 v[18:21], v[180:183], v[206:209], v[18:21]
	v_mfma_f32_16x16x32_bf16 v[6:9], v[172:175], v[214:217], v[6:9]
	v_mfma_f32_16x16x32_bf16 v[2:5], v[180:183], v[214:217], v[2:5]
	s_barrier
	s_setprio 0
	s_add_i32 s66, s66, 2
	s_add_u32 s44, s44, 0x100
	s_addc_u32 s45, s45, 0
	s_add_u32 s64, s64, 0x100
	s_addc_u32 s65, s65, 0
	s_cmp_gt_u32 s66, 13
	s_cbranch_scc0 .LBB0_1133
	s_and_b64 vcc, exec, s[18:19]
	s_cbranch_vccz .LBB0_1136
	s_barrier

; #define PG8_STAGE(bufoff, gbase, voff) do { _Pragma("unroll") for (int _i = 0; _i < 2; ++_i) \
;         __builtin_amdgcn_global_load_lds((const unsigned*)((const char*)(gbase) + (voff)[_i]), (LAS unsigned*)(lds + (bufoff) + ldsw + _i * 8192), 16, 0, 0); } while (0)
; #define PG8_LDA(dst, b, h) do { _Pragma("unroll") for (int m = 0; m < 4; ++m) _Pragma("unroll") for (int k = 0; k < 2; ++k) dst[m][k] = *(const LAS bf16x8*)(lds + PG8_SA(b, h) + aoff + m * 2048 + k * 1024); } while (0)
; #define PG8_LDB(dst, b, h) do { _Pragma("unroll") for (int n = 0; n < 2; ++n) _Pragma("unroll") for (int k = 0; k < 2; ++k) dst[n][k] = *(const LAS bf16x8*)(lds + PG8_SB(b, h) + boff + n * 2048 + k * 1024); } while (0)
; #define PG8_MMA(ai, bj, At, Bt) do { __builtin_amdgcn_s_setprio(1); _Pragma("unroll") for (int m = 0; m < 4; ++m) _Pragma("unroll") for (int n = 0; n < 2; ++n) _Pragma("unroll") for (int k = 0; k < 2; ++k) \
;         acc[ai][bj][m][n] = __builtin_amdgcn_mfma_f32_16x16x32_bf16(Bt[n][k], At[m][k], acc[ai][bj][m][n], 0, 0, 0); __builtin_amdgcn_s_setprio(0); } while (0)
; #define PG8_WAIT_V(n) asm volatile("s_waitcnt vmcnt(" #n ")" ::: "memory")
; #define PG8_WAIT_L(n) asm volatile("s_waitcnt lgkmcnt(" #n ")" ::: "memory")
; #define PG8_BAR __builtin_amdgcn_s_barrier()
; #define PG8_SCHED __builtin_amdgcn_sched_barrier(0)
; template <class Epi, class Sched>
; DI void gemm_phase(LAS unsigned char* lds, const Gemm g, const Sched& S, const Epi& E) {
;     ...
;             PG8_LDB(B0, 0, 0); PG8_LDB(B1, 0, 1); PG8_SCHED; PG8_LDA(At, 0, 0); PG8_STAGE(PG8_SA(1, 1), a1 + hstepA, voffA);
;             PG8_WAIT_V(8); PG8_WAIT_L(0); PG8_BAR; PG8_MMA(0, 0, At, B0); PG8_MMA(0, 1, At, B1); PG8_BAR; PG8_SCHED;
;             PG8_LDA(At, 0, 1); PG8_STAGE(PG8_SB(0, 0), b2, voffB); PG8_STAGE(PG8_SB(0, 1), b2 + hstepB, voffB); PG8_STAGE(PG8_SA(0, 0), a2, voffA);
.LBB0_1234:
	ds_read_b128 v[166:169], v160
	ds_read_b128 v[170:173], v160 offset:1024
	ds_read_b128 v[174:177], v160 offset:2048
	ds_read_b128 v[178:181], v160 offset:3072
	ds_read_b128 v[186:189], v161
	ds_read_b128 v[190:193], v161 offset:1024
	ds_read_b128 v[194:197], v161 offset:2048
	ds_read_b128 v[198:201], v161 offset:3072
	s_add_u32 s42, s40, 0xfffc0080
	s_addc_u32 s43, s41, -1
	s_cmp_eq_u32 s65, 12
	s_cselect_b32 s45, s35, s43
	s_cselect_b32 s44, s61, s42
	s_cselect_b32 s43, s21, s64
	s_cselect_b32 s42, s62, s63
	v_lshl_add_u64 v[182:183], s[40:41], 0, v[138:139]
	s_add_i32 m0, s49, 0xc000
	ds_read_b128 v[202:205], v158
	ds_read_b128 v[206:209], v158 offset:1024
	ds_read_b128 v[210:213], v158 offset:2048
	ds_read_b128 v[214:217], v158 offset:3072
	ds_read_b128 v[218:221], v158 offset:4096
	ds_read_b128 v[222:225], v158 offset:5120
	ds_read_b128 v[226:229], v158 offset:6144
	ds_read_b128 v[230:233], v158 offset:7168
	global_load_lds_dwordx4 v[182:183], off
	v_lshl_add_u64 v[182:183], s[40:41], 0, v[140:141]
	s_add_i32 m0, s49, 0xe000
	s_nop 0
	global_load_lds_dwordx4 v[182:183], off
	s_waitcnt vmcnt(8)
	s_waitcnt lgkmcnt(0)
	s_setprio 1
	s_barrier
	v_mfma_f32_16x16x32_bf16 v[126:129], v[166:169], v[202:205], v[126:129]
	v_mfma_f32_16x16x32_bf16 v[118:121], v[174:177], v[202:205], v[118:121]
	v_mfma_f32_16x16x32_bf16 v[110:113], v[166:169], v[210:213], v[110:113]
	v_mfma_f32_16x16x32_bf16 v[102:105], v[174:177], v[210:213], v[102:105]
	v_mfma_f32_16x16x32_bf16 v[94:97], v[166:169], v[218:221], v[94:97]
	v_mfma_f32_16x16x32_bf16 v[86:89], v[174:177], v[218:221], v[86:89]
	v_mfma_f32_16x16x32_bf16 v[78:81], v[166:169], v[226:229], v[78:81]
	v_mfma_f32_16x16x32_bf16 v[70:73], v[174:177], v[226:229], v[70:73]
	v_mfma_f32_16x16x32_bf16 v[126:129], v[170:173], v[206:209], v[126:129]
	v_mfma_f32_16x16x32_bf16 v[118:121], v[178:181], v[206:209], v[118:121]
	v_mfma_f32_16x16x32_bf16 v[110:113], v[170:173], v[214:217], v[110:113]
	v_mfma_f32_16x16x32_bf16 v[102:105], v[178:181], v[214:217], v[102:105]
	v_mfma_f32_16x16x32_bf16 v[94:97], v[170:173], v[222:225], v[94:97]
	v_mfma_f32_16x16x32_bf16 v[86:89], v[178:181], v[222:225], v[86:89]
	v_mfma_f32_16x16x32_bf16 v[78:81], v[170:173], v[230:233], v[78:81]
	v_mfma_f32_16x16x32_bf16 v[70:73], v[178:181], v[230:233], v[70:73]
	v_mfma_f32_16x16x32_bf16 v[122:125], v[186:189], v[202:205], v[122:125]
	v_mfma_f32_16x16x32_bf16 v[114:117], v[194:197], v[202:205], v[114:117]
	v_mfma_f32_16x16x32_bf16 v[106:109], v[186:189], v[210:213], v[106:109]
	v_mfma_f32_16x16x32_bf16 v[98:101], v[194:197], v[210:213], v[98:101]
	v_mfma_f32_16x16x32_bf16 v[90:93], v[186:189], v[218:221], v[90:93]
	v_mfma_f32_16x16x32_bf16 v[82:85], v[194:197], v[218:221], v[82:85]
	v_mfma_f32_16x16x32_bf16 v[74:77], v[186:189], v[226:229], v[74:77]
	v_mfma_f32_16x16x32_bf16 v[66:69], v[194:197], v[226:229], v[66:69]
	v_mfma_f32_16x16x32_bf16 v[122:125], v[190:193], v[206:209], v[122:125]
	v_mfma_f32_16x16x32_bf16 v[114:117], v[198:201], v[206:209], v[114:117]
	v_mfma_f32_16x16x32_bf16 v[106:109], v[190:193], v[214:217], v[106:109]
	v_mfma_f32_16x16x32_bf16 v[98:101], v[198:201], v[214:217], v[98:101]
	v_mfma_f32_16x16x32_bf16 v[90:93], v[190:193], v[222:225], v[90:93]
	v_mfma_f32_16x16x32_bf16 v[82:85], v[198:201], v[222:225], v[82:85]
	v_mfma_f32_16x16x32_bf16 v[74:77], v[190:193], v[230:233], v[74:77]
	v_mfma_f32_16x16x32_bf16 v[66:69], v[198:201], v[230:233], v[66:69]
	s_barrier
	s_setprio 0
	s_add_i32 s66, s57, s46
	v_lshl_add_u64 v[182:183], s[42:43], 0, v[134:135]
	s_mov_b32 m0, s66
	ds_read_b128 v[202:205], v158 offset:16384
	ds_read_b128 v[206:209], v158 offset:17408
	ds_read_b128 v[210:213], v158 offset:18432
	ds_read_b128 v[214:217], v158 offset:19456
	ds_read_b128 v[218:221], v158 offset:20480
	ds_read_b128 v[222:225], v158 offset:21504
	ds_read_b128 v[226:229], v158 offset:22528
	ds_read_b128 v[230:233], v158 offset:23552
	global_load_lds_dwordx4 v[182:183], off
	s_add_i32 m0, s66, 0x2000
	s_add_u32 s66, s42, 0x40000
	v_lshl_add_u64 v[234:235], s[42:43], 0, v[130:131]
	s_addc_u32 s67, s43, 0
	s_add_i32 s68, s58, s46
	global_load_lds_dwordx4 v[234:235], off
	v_lshl_add_u64 v[236:237], s[66:67], 0, v[134:135]
	s_mov_b32 m0, s68
	v_lshl_add_u64 v[238:239], s[44:45], 0, v[132:133]
	global_load_lds_dwordx4 v[236:237], off
	v_lshl_add_u64 v[236:237], s[66:67], 0, v[130:131]
	s_add_i32 m0, s68, 0x2000
	s_nop 0
	global_load_lds_dwordx4 v[236:237], off
	v_lshl_add_u64 v[236:237], s[44:45], 0, v[136:137]
	s_mov_b32 m0, s49
	s_nop 0
	global_load_lds_dwordx4 v[236:237], off
	s_mov_b32 m0, s50
	s_nop 0
	global_load_lds_dwordx4 v[238:239], off
	s_waitcnt vmcnt(8)
	s_waitcnt lgkmcnt(0)
	s_setprio 1
	s_barrier
; #define PG8_STAGE(bufoff, gbase, voff) do { _Pragma("unroll") for (int _i = 0; _i < 2; ++_i) \
;         __builtin_amdgcn_global_load_lds((const unsigned*)((const char*)(gbase) + (voff)[_i]), (LAS unsigned*)(lds + (bufoff) + ldsw + _i * 8192), 16, 0, 0); } while (0)
; #define PG8_LDA(dst, b, h) do { _Pragma("unroll") for (int m = 0; m < 4; ++m) _Pragma("unroll") for (int k = 0; k < 2; ++k) dst[m][k] = *(const LAS bf16x8*)(lds + PG8_SA(b, h) + aoff + m * 2048 + k * 1024); } while (0)
; #define PG8_LDB(dst, b, h) do { _Pragma("unroll") for (int n = 0; n < 2; ++n) _Pragma("unroll") for (int k = 0; k < 2; ++k) dst[n][k] = *(const LAS bf16x8*)(lds + PG8_SB(b, h) + boff + n * 2048 + k * 1024); } while (0)
; #define PG8_MMA(ai, bj, At, Bt) do { __builtin_amdgcn_s_setprio(1); _Pragma("unroll") for (int m = 0; m < 4; ++m) _Pragma("unroll") for (int n = 0; n < 2; ++n) _Pragma("unroll") for (int k = 0; k < 2; ++k) \
;         acc[ai][bj][m][n] = __builtin_amdgcn_mfma_f32_16x16x32_bf16(Bt[n][k], At[m][k], acc[ai][bj][m][n], 0, 0, 0); __builtin_amdgcn_s_setprio(0); } while (0)
; #define PG8_WAIT_V(n) asm volatile("s_waitcnt vmcnt(" #n ")" ::: "memory")
; #define PG8_WAIT_L(n) asm volatile("s_waitcnt lgkmcnt(" #n ")" ::: "memory")
; #define PG8_BAR __builtin_amdgcn_s_barrier()
; #define PG8_SCHED __builtin_amdgcn_sched_barrier(0)
; template <class Epi, class Sched>
; DI void gemm_phase(LAS unsigned char* lds, const Gemm g, const Sched& S, const Epi& E) {
;     ...
;             PG8_WAIT_V(8); PG8_WAIT_L(0); PG8_BAR; PG8_MMA(1, 0, At, B0); PG8_MMA(1, 1, At, B1); PG8_BAR; PG8_SCHED;
;             PG8_LDB(B0, 1, 0); PG8_LDB(B1, 1, 1); PG8_SCHED; PG8_LDA(At, 1, 0); PG8_STAGE(PG8_SA(0, 1), a2 + hstepA, voffA);
;             PG8_WAIT_V(8); PG8_WAIT_L(0); PG8_BAR; PG8_MMA(0, 0, At, B0); PG8_MMA(0, 1, At, B1); PG8_BAR; PG8_SCHED;
	v_mfma_f32_16x16x32_bf16 v[62:65], v[166:169], v[202:205], v[62:65]
	v_mfma_f32_16x16x32_bf16 v[54:57], v[174:177], v[202:205], v[54:57]
	v_mfma_f32_16x16x32_bf16 v[46:49], v[166:169], v[210:213], v[46:49]
	v_mfma_f32_16x16x32_bf16 v[38:41], v[174:177], v[210:213], v[38:41]
	v_mfma_f32_16x16x32_bf16 v[30:33], v[166:169], v[218:221], v[30:33]
	v_mfma_f32_16x16x32_bf16 v[22:25], v[174:177], v[218:221], v[22:25]
	v_mfma_f32_16x16x32_bf16 v[14:17], v[166:169], v[226:229], v[14:17]
	v_mfma_f32_16x16x32_bf16 v[6:9], v[174:177], v[226:229], v[6:9]
	v_mfma_f32_16x16x32_bf16 v[62:65], v[170:173], v[206:209], v[62:65]
	v_mfma_f32_16x16x32_bf16 v[54:57], v[178:181], v[206:209], v[54:57]
	v_mfma_f32_16x16x32_bf16 v[46:49], v[170:173], v[214:217], v[46:49]
	v_mfma_f32_16x16x32_bf16 v[38:41], v[178:181], v[214:217], v[38:41]
	v_mfma_f32_16x16x32_bf16 v[30:33], v[170:173], v[222:225], v[30:33]
	v_mfma_f32_16x16x32_bf16 v[22:25], v[178:181], v[222:225], v[22:25]
	v_mfma_f32_16x16x32_bf16 v[14:17], v[170:173], v[230:233], v[14:17]
	v_mfma_f32_16x16x32_bf16 v[6:9], v[178:181], v[230:233], v[6:9]
	v_mfma_f32_16x16x32_bf16 v[58:61], v[186:189], v[202:205], v[58:61]
	v_mfma_f32_16x16x32_bf16 v[50:53], v[194:197], v[202:205], v[50:53]
	v_mfma_f32_16x16x32_bf16 v[42:45], v[186:189], v[210:213], v[42:45]
	v_mfma_f32_16x16x32_bf16 v[34:37], v[194:197], v[210:213], v[34:37]
	v_mfma_f32_16x16x32_bf16 v[26:29], v[186:189], v[218:221], v[26:29]
	v_mfma_f32_16x16x32_bf16 v[18:21], v[194:197], v[218:221], v[18:21]
	v_mfma_f32_16x16x32_bf16 v[10:13], v[186:189], v[226:229], v[10:13]
	v_mfma_f32_16x16x32_bf16 v[2:5], v[194:197], v[226:229], v[2:5]
	v_mfma_f32_16x16x32_bf16 v[58:61], v[190:193], v[206:209], v[58:61]
	v_mfma_f32_16x16x32_bf16 v[50:53], v[198:201], v[206:209], v[50:53]
	v_mfma_f32_16x16x32_bf16 v[42:45], v[190:193], v[214:217], v[42:45]
	v_mfma_f32_16x16x32_bf16 v[34:37], v[198:201], v[214:217], v[34:37]
	v_mfma_f32_16x16x32_bf16 v[26:29], v[190:193], v[222:225], v[26:29]
	v_mfma_f32_16x16x32_bf16 v[18:21], v[198:201], v[222:225], v[18:21]
	v_mfma_f32_16x16x32_bf16 v[10:13], v[190:193], v[230:233], v[10:13]
	v_mfma_f32_16x16x32_bf16 v[2:5], v[198:201], v[230:233], v[2:5]
	s_barrier
	s_setprio 0
	s_add_i32 s66, 0, 0x18000
	v_add_u32_e32 v165, s66, v156
	s_add_i32 s67, 0, 0x1c000
	ds_read_b128 v[166:169], v165
	ds_read_b128 v[170:173], v165 offset:1024
	ds_read_b128 v[174:177], v165 offset:2048
	ds_read_b128 v[178:181], v165 offset:3072
	v_add_u32_e32 v165, s67, v156
	ds_read_b128 v[186:189], v165
	ds_read_b128 v[190:193], v165 offset:1024
	ds_read_b128 v[194:197], v165 offset:2048
	ds_read_b128 v[198:201], v165 offset:3072
	s_add_u32 s44, s44, 0x40000
	s_addc_u32 s45, s45, 0
	s_mov_b32 m0, s51
	v_lshl_add_u64 v[240:241], s[44:45], 0, v[136:137]
	ds_read_b128 v[202:205], v158 offset:32768
	ds_read_b128 v[206:209], v158 offset:33792
	ds_read_b128 v[210:213], v158 offset:34816
	ds_read_b128 v[214:217], v158 offset:35840
	ds_read_b128 v[218:221], v158 offset:36864
	ds_read_b128 v[222:225], v158 offset:37888
	ds_read_b128 v[226:229], v158 offset:38912
	ds_read_b128 v[230:233], v158 offset:39936
	global_load_lds_dwordx4 v[240:241], off
	v_lshl_add_u64 v[240:241], s[44:45], 0, v[132:133]
	s_mov_b32 m0, s52
	s_nop 0
	global_load_lds_dwordx4 v[240:241], off
	s_waitcnt vmcnt(8)
	s_waitcnt lgkmcnt(0)
	s_setprio 1
	s_barrier
	v_mfma_f32_16x16x32_bf16 v[126:129], v[166:169], v[202:205], v[126:129]
	v_mfma_f32_16x16x32_bf16 v[118:121], v[174:177], v[202:205], v[118:121]
	v_mfma_f32_16x16x32_bf16 v[110:113], v[166:169], v[210:213], v[110:113]
	v_mfma_f32_16x16x32_bf16 v[102:105], v[174:177], v[210:213], v[102:105]
	v_mfma_f32_16x16x32_bf16 v[94:97], v[166:169], v[218:221], v[94:97]
	v_mfma_f32_16x16x32_bf16 v[86:89], v[174:177], v[218:221], v[86:89]
	v_mfma_f32_16x16x32_bf16 v[78:81], v[166:169], v[226:229], v[78:81]
	v_mfma_f32_16x16x32_bf16 v[70:73], v[174:177], v[226:229], v[70:73]
	v_mfma_f32_16x16x32_bf16 v[126:129], v[170:173], v[206:209], v[126:129]
	v_mfma_f32_16x16x32_bf16 v[118:121], v[178:181], v[206:209], v[118:121]
	v_mfma_f32_16x16x32_bf16 v[110:113], v[170:173], v[214:217], v[110:113]
	v_mfma_f32_16x16x32_bf16 v[102:105], v[178:181], v[214:217], v[102:105]
	v_mfma_f32_16x16x32_bf16 v[94:97], v[170:173], v[222:225], v[94:97]
	v_mfma_f32_16x16x32_bf16 v[86:89], v[178:181], v[222:225], v[86:89]
	v_mfma_f32_16x16x32_bf16 v[78:81], v[170:173], v[230:233], v[78:81]
	v_mfma_f32_16x16x32_bf16 v[70:73], v[178:181], v[230:233], v[70:73]
	v_mfma_f32_16x16x32_bf16 v[122:125], v[186:189], v[202:205], v[122:125]
	v_mfma_f32_16x16x32_bf16 v[114:117], v[194:197], v[202:205], v[114:117]
	v_mfma_f32_16x16x32_bf16 v[106:109], v[186:189], v[210:213], v[106:109]
	v_mfma_f32_16x16x32_bf16 v[98:101], v[194:197], v[210:213], v[98:101]
	v_mfma_f32_16x16x32_bf16 v[90:93], v[186:189], v[218:221], v[90:93]
	v_mfma_f32_16x16x32_bf16 v[82:85], v[194:197], v[218:221], v[82:85]
	v_mfma_f32_16x16x32_bf16 v[74:77], v[186:189], v[226:229], v[74:77]
	v_mfma_f32_16x16x32_bf16 v[66:69], v[194:197], v[226:229], v[66:69]
	v_mfma_f32_16x16x32_bf16 v[122:125], v[190:193], v[206:209], v[122:125]
	v_mfma_f32_16x16x32_bf16 v[114:117], v[198:201], v[206:209], v[114:117]
	v_mfma_f32_16x16x32_bf16 v[106:109], v[190:193], v[214:217], v[106:109]
	v_mfma_f32_16x16x32_bf16 v[98:101], v[198:201], v[214:217], v[98:101]
	v_mfma_f32_16x16x32_bf16 v[90:93], v[190:193], v[222:225], v[90:93]
	v_mfma_f32_16x16x32_bf16 v[82:85], v[198:201], v[222:225], v[82:85]
	v_mfma_f32_16x16x32_bf16 v[74:77], v[190:193], v[230:233], v[74:77]
	v_mfma_f32_16x16x32_bf16 v[66:69], v[198:201], v[230:233], v[66:69]
	s_barrier
; #define PG8_STAGE(bufoff, gbase, voff) do { _Pragma("unroll") for (int _i = 0; _i < 2; ++_i) \
;         __builtin_amdgcn_global_load_lds((const unsigned*)((const char*)(gbase) + (voff)[_i]), (LAS unsigned*)(lds + (bufoff) + ldsw + _i * 8192), 16, 0, 0); } while (0)
; #define PG8_LDA(dst, b, h) do { _Pragma("unroll") for (int m = 0; m < 4; ++m) _Pragma("unroll") for (int k = 0; k < 2; ++k) dst[m][k] = *(const LAS bf16x8*)(lds + PG8_SA(b, h) + aoff + m * 2048 + k * 1024); } while (0)
; #define PG8_MMA(ai, bj, At, Bt) do { __builtin_amdgcn_s_setprio(1); _Pragma("unroll") for (int m = 0; m < 4; ++m) _Pragma("unroll") for (int n = 0; n < 2; ++n) _Pragma("unroll") for (int k = 0; k < 2; ++k) \
;         acc[ai][bj][m][n] = __builtin_amdgcn_mfma_f32_16x16x32_bf16(Bt[n][k], At[m][k], acc[ai][bj][m][n], 0, 0, 0); __builtin_amdgcn_s_setprio(0); } while (0)
; #define PG8_WAIT_V(n) asm volatile("s_waitcnt vmcnt(" #n ")" ::: "memory")
; #define PG8_WAIT_L(n) asm volatile("s_waitcnt lgkmcnt(" #n ")" ::: "memory")
; #define PG8_BAR __builtin_amdgcn_s_barrier()
; #define PG8_SCHED __builtin_amdgcn_sched_barrier(0)
; template <class Epi, class Sched>
; DI void gemm_phase(LAS unsigned char* lds, const Gemm g, const Sched& S, const Epi& E) {
;     ...
;             PG8_LDA(At, 1, 1); PG8_STAGE(PG8_SB(1, 0), b3, voffB); PG8_STAGE(PG8_SB(1, 1), b3 + hstepB, voffB); PG8_STAGE(PG8_SA(1, 0), a3, voffA);
;             PG8_WAIT_V(8); PG8_WAIT_L(0); PG8_BAR; PG8_MMA(1, 0, At, B0); PG8_MMA(1, 1, At, B1); PG8_BAR; PG8_SCHED;
;         }
;         if (wr == 0) PG8_BAR;
	s_setprio 0
	s_add_i32 s44, s66, s46
	v_lshl_add_u64 v[182:183], v[182:183], 0, s[16:17]
	s_mov_b32 m0, s44
	ds_read_b128 v[202:205], v158 offset:49152
	ds_read_b128 v[206:209], v158 offset:50176
	ds_read_b128 v[210:213], v158 offset:51200
	ds_read_b128 v[214:217], v158 offset:52224
	ds_read_b128 v[218:221], v158 offset:53248
	ds_read_b128 v[222:225], v158 offset:54272
	ds_read_b128 v[226:229], v158 offset:55296
	ds_read_b128 v[230:233], v158 offset:56320
	global_load_lds_dwordx4 v[182:183], off
	s_add_i32 m0, s44, 0x2000
	s_add_u32 s42, s42, 0x40080
	v_lshl_add_u64 v[182:183], v[234:235], 0, s[16:17]
	s_addc_u32 s43, s43, 0
	s_add_i32 s44, s67, s46
	global_load_lds_dwordx4 v[182:183], off
	v_lshl_add_u64 v[182:183], s[42:43], 0, v[134:135]
	s_mov_b32 m0, s44
	s_nop 0
	global_load_lds_dwordx4 v[182:183], off
	v_lshl_add_u64 v[182:183], s[42:43], 0, v[130:131]
	s_add_i32 m0, s44, 0x2000
	s_nop 0
	global_load_lds_dwordx4 v[182:183], off
	v_lshl_add_u64 v[182:183], v[236:237], 0, s[16:17]
	s_mov_b32 m0, s54
	s_nop 0
	global_load_lds_dwordx4 v[182:183], off
	v_lshl_add_u64 v[182:183], v[238:239], 0, s[16:17]
	s_mov_b32 m0, s55
	s_nop 0
	global_load_lds_dwordx4 v[182:183], off
	s_waitcnt vmcnt(8)
	s_waitcnt lgkmcnt(0)
	s_setprio 1
	s_barrier
	v_mfma_f32_16x16x32_bf16 v[62:65], v[166:169], v[202:205], v[62:65]
	v_mfma_f32_16x16x32_bf16 v[54:57], v[174:177], v[202:205], v[54:57]
	v_mfma_f32_16x16x32_bf16 v[46:49], v[166:169], v[210:213], v[46:49]
	v_mfma_f32_16x16x32_bf16 v[38:41], v[174:177], v[210:213], v[38:41]
	v_mfma_f32_16x16x32_bf16 v[30:33], v[166:169], v[218:221], v[30:33]
	v_mfma_f32_16x16x32_bf16 v[22:25], v[174:177], v[218:221], v[22:25]
	v_mfma_f32_16x16x32_bf16 v[14:17], v[166:169], v[226:229], v[14:17]
	v_mfma_f32_16x16x32_bf16 v[6:9], v[174:177], v[226:229], v[6:9]
	v_mfma_f32_16x16x32_bf16 v[62:65], v[170:173], v[206:209], v[62:65]
	v_mfma_f32_16x16x32_bf16 v[54:57], v[178:181], v[206:209], v[54:57]
	v_mfma_f32_16x16x32_bf16 v[46:49], v[170:173], v[214:217], v[46:49]
	v_mfma_f32_16x16x32_bf16 v[38:41], v[178:181], v[214:217], v[38:41]
	v_mfma_f32_16x16x32_bf16 v[30:33], v[170:173], v[222:225], v[30:33]
	v_mfma_f32_16x16x32_bf16 v[22:25], v[178:181], v[222:225], v[22:25]
	v_mfma_f32_16x16x32_bf16 v[14:17], v[170:173], v[230:233], v[14:17]
	v_mfma_f32_16x16x32_bf16 v[6:9], v[178:181], v[230:233], v[6:9]
	v_mfma_f32_16x16x32_bf16 v[58:61], v[186:189], v[202:205], v[58:61]
	v_mfma_f32_16x16x32_bf16 v[50:53], v[194:197], v[202:205], v[50:53]
	v_mfma_f32_16x16x32_bf16 v[42:45], v[186:189], v[210:213], v[42:45]
	v_mfma_f32_16x16x32_bf16 v[34:37], v[194:197], v[210:213], v[34:37]
	v_mfma_f32_16x16x32_bf16 v[26:29], v[186:189], v[218:221], v[26:29]
	v_mfma_f32_16x16x32_bf16 v[18:21], v[194:197], v[218:221], v[18:21]
	v_mfma_f32_16x16x32_bf16 v[10:13], v[186:189], v[226:229], v[10:13]
	v_mfma_f32_16x16x32_bf16 v[2:5], v[194:197], v[226:229], v[2:5]
	v_mfma_f32_16x16x32_bf16 v[58:61], v[190:193], v[206:209], v[58:61]
	v_mfma_f32_16x16x32_bf16 v[50:53], v[198:201], v[206:209], v[50:53]
	v_mfma_f32_16x16x32_bf16 v[42:45], v[190:193], v[214:217], v[42:45]
	v_mfma_f32_16x16x32_bf16 v[34:37], v[198:201], v[214:217], v[34:37]
	v_mfma_f32_16x16x32_bf16 v[26:29], v[190:193], v[222:225], v[26:29]
	v_mfma_f32_16x16x32_bf16 v[18:21], v[198:201], v[222:225], v[18:21]
	v_mfma_f32_16x16x32_bf16 v[10:13], v[190:193], v[230:233], v[10:13]
	v_mfma_f32_16x16x32_bf16 v[2:5], v[198:201], v[230:233], v[2:5]
	s_barrier
	s_setprio 0
	s_add_i32 s65, s65, 2
	s_add_u32 s40, s40, 0x100
	s_addc_u32 s41, s41, 0
	s_add_u32 s63, s63, 0x100
	s_addc_u32 s64, s64, 0
	s_cmp_gt_u32 s65, 13
	s_cbranch_scc0 .LBB0_1234
	s_and_b64 vcc, exec, s[18:19]
	s_cbranch_vccz .LBB0_1237
	s_barrier

; #define PG8_STAGE(bufoff, gbase, voff) do { _Pragma("unroll") for (int _i = 0; _i < 2; ++_i) \
;         __builtin_amdgcn_global_load_lds((const unsigned*)((const char*)(gbase) + (voff)[_i]), (LAS unsigned*)(lds + (bufoff) + ldsw + _i * 8192), 16, 0, 0); } while (0)
; #define PG8_LDA(dst, b, h) do { _Pragma("unroll") for (int m = 0; m < 4; ++m) _Pragma("unroll") for (int k = 0; k < 2; ++k) dst[m][k] = *(const LAS bf16x8*)(lds + PG8_SA(b, h) + aoff + m * 2048 + k * 1024); } while (0)
; #define PG8_LDB(dst, b, h) do { _Pragma("unroll") for (int n = 0; n < 2; ++n) _Pragma("unroll") for (int k = 0; k < 2; ++k) dst[n][k] = *(const LAS bf16x8*)(lds + PG8_SB(b, h) + boff + n * 2048 + k * 1024); } while (0)
; #define PG8_MMA(ai, bj, At, Bt) do { __builtin_amdgcn_s_setprio(1); _Pragma("unroll") for (int m = 0; m < 4; ++m) _Pragma("unroll") for (int n = 0; n < 2; ++n) _Pragma("unroll") for (int k = 0; k < 2; ++k) \
;         acc[ai][bj][m][n] = __builtin_amdgcn_mfma_f32_16x16x32_bf16(Bt[n][k], At[m][k], acc[ai][bj][m][n], 0, 0, 0); __builtin_amdgcn_s_setprio(0); } while (0)
; #define PG8_WAIT_V(n) asm volatile("s_waitcnt vmcnt(" #n ")" ::: "memory")
; #define PG8_WAIT_L(n) asm volatile("s_waitcnt lgkmcnt(" #n ")" ::: "memory")
; #define PG8_BAR __builtin_amdgcn_s_barrier()
; #define PG8_SCHED __builtin_amdgcn_sched_barrier(0)
; template <class Epi, class Sched>
; DI void gemm_phase(LAS unsigned char* lds, const Gemm g, const Sched& S, const Epi& E) {
;     ...
;             PG8_LDB(B0, 0, 0); PG8_LDB(B1, 0, 1); PG8_SCHED; PG8_LDA(At, 0, 0); PG8_STAGE(PG8_SA(1, 1), a1 + hstepA, voffA);
;             PG8_WAIT_V(8); PG8_WAIT_L(0); PG8_BAR; PG8_MMA(0, 0, At, B0); PG8_MMA(0, 1, At, B1); PG8_BAR; PG8_SCHED;
;             PG8_LDA(At, 0, 1); PG8_STAGE(PG8_SB(0, 0), b2, voffB); PG8_STAGE(PG8_SB(0, 1), b2 + hstepB, voffB); PG8_STAGE(PG8_SA(0, 0), a2, voffA);
.LBB0_1331:
	ds_read_b128 v[144:147], v151
	ds_read_b128 v[154:157], v151 offset:1024
	ds_read_b128 v[158:161], v151 offset:2048
	ds_read_b128 v[162:165], v151 offset:3072
	ds_read_b128 v[166:169], v152
	ds_read_b128 v[170:173], v152 offset:1024
	ds_read_b128 v[174:177], v152 offset:2048
	ds_read_b128 v[178:181], v152 offset:3072
	s_add_u32 s18, s16, 0xfff50080
	s_addc_u32 s19, s17, -1
	s_cmp_eq_u32 s47, 40
	s_cselect_b32 s21, s5, s19
	s_cselect_b32 s20, s4, s18
	s_cselect_b32 s19, s15, s46
	s_cselect_b32 s18, s14, s45
	v_lshl_add_u64 v[214:215], s[16:17], 0, v[136:137]
	s_add_i32 m0, s28, 0xc000
	ds_read_b128 v[182:185], v153
	ds_read_b128 v[186:189], v153 offset:1024
	ds_read_b128 v[190:193], v153 offset:2048
	ds_read_b128 v[194:197], v153 offset:3072
	ds_read_b128 v[198:201], v153 offset:4096
	ds_read_b128 v[202:205], v153 offset:5120
	ds_read_b128 v[206:209], v153 offset:6144
	ds_read_b128 v[210:213], v153 offset:7168
	global_load_lds_dwordx4 v[214:215], off
	v_lshl_add_u64 v[214:215], s[16:17], 0, v[138:139]
	s_add_i32 m0, s28, 0xe000
	s_nop 0
	global_load_lds_dwordx4 v[214:215], off
	s_waitcnt vmcnt(8)
	s_waitcnt lgkmcnt(0)
	s_setprio 1
	s_barrier
	v_mfma_f32_16x16x32_bf16 v[124:127], v[144:147], v[182:185], v[124:127]
	v_mfma_f32_16x16x32_bf16 v[120:123], v[158:161], v[182:185], v[120:123]
	v_mfma_f32_16x16x32_bf16 v[108:111], v[144:147], v[190:193], v[108:111]
	v_mfma_f32_16x16x32_bf16 v[104:107], v[158:161], v[190:193], v[104:107]
	v_mfma_f32_16x16x32_bf16 v[92:95], v[144:147], v[198:201], v[92:95]
	v_mfma_f32_16x16x32_bf16 v[88:91], v[158:161], v[198:201], v[88:91]
	v_mfma_f32_16x16x32_bf16 v[76:79], v[144:147], v[206:209], v[76:79]
	v_mfma_f32_16x16x32_bf16 v[72:75], v[158:161], v[206:209], v[72:75]
	v_mfma_f32_16x16x32_bf16 v[124:127], v[154:157], v[186:189], v[124:127]
	v_mfma_f32_16x16x32_bf16 v[120:123], v[162:165], v[186:189], v[120:123]
	v_mfma_f32_16x16x32_bf16 v[108:111], v[154:157], v[194:197], v[108:111]
	v_mfma_f32_16x16x32_bf16 v[104:107], v[162:165], v[194:197], v[104:107]
	v_mfma_f32_16x16x32_bf16 v[92:95], v[154:157], v[202:205], v[92:95]
	v_mfma_f32_16x16x32_bf16 v[88:91], v[162:165], v[202:205], v[88:91]
	v_mfma_f32_16x16x32_bf16 v[76:79], v[154:157], v[210:213], v[76:79]
	v_mfma_f32_16x16x32_bf16 v[72:75], v[162:165], v[210:213], v[72:75]
	v_mfma_f32_16x16x32_bf16 v[116:119], v[166:169], v[182:185], v[116:119]
	v_mfma_f32_16x16x32_bf16 v[112:115], v[174:177], v[182:185], v[112:115]
	v_mfma_f32_16x16x32_bf16 v[100:103], v[166:169], v[190:193], v[100:103]
	v_mfma_f32_16x16x32_bf16 v[96:99], v[174:177], v[190:193], v[96:99]
	v_mfma_f32_16x16x32_bf16 v[84:87], v[166:169], v[198:201], v[84:87]
	v_mfma_f32_16x16x32_bf16 v[80:83], v[174:177], v[198:201], v[80:83]
	v_mfma_f32_16x16x32_bf16 v[68:71], v[166:169], v[206:209], v[68:71]
	v_mfma_f32_16x16x32_bf16 v[64:67], v[174:177], v[206:209], v[64:67]
	v_mfma_f32_16x16x32_bf16 v[116:119], v[170:173], v[186:189], v[116:119]
	v_mfma_f32_16x16x32_bf16 v[112:115], v[178:181], v[186:189], v[112:115]
	v_mfma_f32_16x16x32_bf16 v[100:103], v[170:173], v[194:197], v[100:103]
	v_mfma_f32_16x16x32_bf16 v[96:99], v[178:181], v[194:197], v[96:99]
	v_mfma_f32_16x16x32_bf16 v[84:87], v[170:173], v[202:205], v[84:87]
	v_mfma_f32_16x16x32_bf16 v[80:83], v[178:181], v[202:205], v[80:83]
	v_mfma_f32_16x16x32_bf16 v[68:71], v[170:173], v[210:213], v[68:71]
	v_mfma_f32_16x16x32_bf16 v[64:67], v[178:181], v[210:213], v[64:67]
	s_barrier
	s_setprio 0
	s_add_i32 s48, s39, s27
	v_lshl_add_u64 v[214:215], s[18:19], 0, v[130:131]
	s_mov_b32 m0, s48
	ds_read_b128 v[182:185], v153 offset:16384
	ds_read_b128 v[186:189], v153 offset:17408
	ds_read_b128 v[190:193], v153 offset:18432
	ds_read_b128 v[194:197], v153 offset:19456
	ds_read_b128 v[198:201], v153 offset:20480
	ds_read_b128 v[202:205], v153 offset:21504
	ds_read_b128 v[206:209], v153 offset:22528
	ds_read_b128 v[210:213], v153 offset:23552
	global_load_lds_dwordx4 v[214:215], off
	s_add_i32 m0, s48, 0x2000
	s_add_u32 s48, s18, 0xb0000
	v_lshl_add_u64 v[216:217], s[18:19], 0, v[134:135]
	s_addc_u32 s49, s19, 0
	s_add_i32 s50, s40, s27
	global_load_lds_dwordx4 v[216:217], off
	v_lshl_add_u64 v[218:219], s[48:49], 0, v[130:131]
	s_mov_b32 m0, s50
	v_lshl_add_u64 v[220:221], s[20:21], 0, v[132:133]
	global_load_lds_dwordx4 v[218:219], off
	v_lshl_add_u64 v[218:219], s[48:49], 0, v[134:135]
	s_add_i32 m0, s50, 0x2000
	s_nop 0
	global_load_lds_dwordx4 v[218:219], off
	v_lshl_add_u64 v[218:219], s[20:21], 0, v[128:129]
	s_mov_b32 m0, s28
	s_nop 0
	global_load_lds_dwordx4 v[218:219], off
	s_mov_b32 m0, s29
	s_nop 0
	global_load_lds_dwordx4 v[220:221], off
	s_waitcnt vmcnt(8)
	s_waitcnt lgkmcnt(0)
	s_setprio 1
	s_barrier
; #define PG8_STAGE(bufoff, gbase, voff) do { _Pragma("unroll") for (int _i = 0; _i < 2; ++_i) \
;         __builtin_amdgcn_global_load_lds((const unsigned*)((const char*)(gbase) + (voff)[_i]), (LAS unsigned*)(lds + (bufoff) + ldsw + _i * 8192), 16, 0, 0); } while (0)
; #define PG8_LDA(dst, b, h) do { _Pragma("unroll") for (int m = 0; m < 4; ++m) _Pragma("unroll") for (int k = 0; k < 2; ++k) dst[m][k] = *(const LAS bf16x8*)(lds + PG8_SA(b, h) + aoff + m * 2048 + k * 1024); } while (0)
; #define PG8_LDB(dst, b, h) do { _Pragma("unroll") for (int n = 0; n < 2; ++n) _Pragma("unroll") for (int k = 0; k < 2; ++k) dst[n][k] = *(const LAS bf16x8*)(lds + PG8_SB(b, h) + boff + n * 2048 + k * 1024); } while (0)
; #define PG8_MMA(ai, bj, At, Bt) do { __builtin_amdgcn_s_setprio(1); _Pragma("unroll") for (int m = 0; m < 4; ++m) _Pragma("unroll") for (int n = 0; n < 2; ++n) _Pragma("unroll") for (int k = 0; k < 2; ++k) \
;         acc[ai][bj][m][n] = __builtin_amdgcn_mfma_f32_16x16x32_bf16(Bt[n][k], At[m][k], acc[ai][bj][m][n], 0, 0, 0); __builtin_amdgcn_s_setprio(0); } while (0)
; #define PG8_WAIT_V(n) asm volatile("s_waitcnt vmcnt(" #n ")" ::: "memory")
; #define PG8_WAIT_L(n) asm volatile("s_waitcnt lgkmcnt(" #n ")" ::: "memory")
; #define PG8_BAR __builtin_amdgcn_s_barrier()
; #define PG8_SCHED __builtin_amdgcn_sched_barrier(0)
; template <class Epi, class Sched>
; DI void gemm_phase(LAS unsigned char* lds, const Gemm g, const Sched& S, const Epi& E) {
;     ...
;             PG8_WAIT_V(8); PG8_WAIT_L(0); PG8_BAR; PG8_MMA(1, 0, At, B0); PG8_MMA(1, 1, At, B1); PG8_BAR; PG8_SCHED;
;             PG8_LDB(B0, 1, 0); PG8_LDB(B1, 1, 1); PG8_SCHED; PG8_LDA(At, 1, 0); PG8_STAGE(PG8_SA(0, 1), a2 + hstepA, voffA);
;             PG8_WAIT_V(8); PG8_WAIT_L(0); PG8_BAR; PG8_MMA(0, 0, At, B0); PG8_MMA(0, 1, At, B1); PG8_BAR; PG8_SCHED;
	v_mfma_f32_16x16x32_bf16 v[60:63], v[144:147], v[182:185], v[60:63]
	v_mfma_f32_16x16x32_bf16 v[56:59], v[158:161], v[182:185], v[56:59]
	v_mfma_f32_16x16x32_bf16 v[44:47], v[144:147], v[190:193], v[44:47]
	v_mfma_f32_16x16x32_bf16 v[40:43], v[158:161], v[190:193], v[40:43]
	v_mfma_f32_16x16x32_bf16 v[28:31], v[144:147], v[198:201], v[28:31]
	v_mfma_f32_16x16x32_bf16 v[24:27], v[158:161], v[198:201], v[24:27]
	v_mfma_f32_16x16x32_bf16 v[12:15], v[144:147], v[206:209], v[12:15]
	v_mfma_f32_16x16x32_bf16 v[8:11], v[158:161], v[206:209], v[8:11]
	v_mfma_f32_16x16x32_bf16 v[60:63], v[154:157], v[186:189], v[60:63]
	v_mfma_f32_16x16x32_bf16 v[56:59], v[162:165], v[186:189], v[56:59]
	v_mfma_f32_16x16x32_bf16 v[44:47], v[154:157], v[194:197], v[44:47]
	v_mfma_f32_16x16x32_bf16 v[40:43], v[162:165], v[194:197], v[40:43]
	v_mfma_f32_16x16x32_bf16 v[28:31], v[154:157], v[202:205], v[28:31]
	v_mfma_f32_16x16x32_bf16 v[24:27], v[162:165], v[202:205], v[24:27]
	v_mfma_f32_16x16x32_bf16 v[12:15], v[154:157], v[210:213], v[12:15]
	v_mfma_f32_16x16x32_bf16 v[8:11], v[162:165], v[210:213], v[8:11]
	v_mfma_f32_16x16x32_bf16 v[52:55], v[166:169], v[182:185], v[52:55]
	v_mfma_f32_16x16x32_bf16 v[48:51], v[174:177], v[182:185], v[48:51]
	v_mfma_f32_16x16x32_bf16 v[36:39], v[166:169], v[190:193], v[36:39]
	v_mfma_f32_16x16x32_bf16 v[32:35], v[174:177], v[190:193], v[32:35]
	v_mfma_f32_16x16x32_bf16 v[20:23], v[166:169], v[198:201], v[20:23]
	v_mfma_f32_16x16x32_bf16 v[16:19], v[174:177], v[198:201], v[16:19]
	v_mfma_f32_16x16x32_bf16 v[4:7], v[166:169], v[206:209], v[4:7]
	v_mfma_f32_16x16x32_bf16 v[0:3], v[174:177], v[206:209], v[0:3]
	v_mfma_f32_16x16x32_bf16 v[52:55], v[170:173], v[186:189], v[52:55]
	v_mfma_f32_16x16x32_bf16 v[48:51], v[178:181], v[186:189], v[48:51]
	v_mfma_f32_16x16x32_bf16 v[36:39], v[170:173], v[194:197], v[36:39]
	v_mfma_f32_16x16x32_bf16 v[32:35], v[178:181], v[194:197], v[32:35]
	v_mfma_f32_16x16x32_bf16 v[20:23], v[170:173], v[202:205], v[20:23]
	v_mfma_f32_16x16x32_bf16 v[16:19], v[178:181], v[202:205], v[16:19]
	v_mfma_f32_16x16x32_bf16 v[4:7], v[170:173], v[210:213], v[4:7]
	v_mfma_f32_16x16x32_bf16 v[0:3], v[178:181], v[210:213], v[0:3]
	s_barrier
	s_setprio 0
	s_add_i32 s48, 0, 0x18000
	s_add_i32 s49, 0, 0x1c000
	v_add_u32_e32 v162, s48, v149
	v_add_u32_e32 v178, s49, v149
	ds_read_b128 v[144:147], v162
	ds_read_b128 v[154:157], v162 offset:1024
	ds_read_b128 v[158:161], v162 offset:2048
	ds_read_b128 v[162:165], v162 offset:3072
	ds_read_b128 v[166:169], v178
	ds_read_b128 v[170:173], v178 offset:1024
	ds_read_b128 v[174:177], v178 offset:2048
	ds_read_b128 v[178:181], v178 offset:3072
	s_add_u32 s20, s20, 0xb0000
	s_addc_u32 s21, s21, 0
	s_mov_b32 m0, s33
	v_lshl_add_u64 v[222:223], s[20:21], 0, v[128:129]
	ds_read_b128 v[182:185], v153 offset:32768
	ds_read_b128 v[186:189], v153 offset:33792
	ds_read_b128 v[190:193], v153 offset:34816
	ds_read_b128 v[194:197], v153 offset:35840
	ds_read_b128 v[198:201], v153 offset:36864
	ds_read_b128 v[202:205], v153 offset:37888
	ds_read_b128 v[206:209], v153 offset:38912
	ds_read_b128 v[210:213], v153 offset:39936
	global_load_lds_dwordx4 v[222:223], off
	v_lshl_add_u64 v[222:223], s[20:21], 0, v[132:133]
	s_mov_b32 m0, s34
	s_nop 0
	global_load_lds_dwordx4 v[222:223], off
	s_waitcnt vmcnt(8)
	s_waitcnt lgkmcnt(0)
	s_setprio 1
	s_barrier
	v_mfma_f32_16x16x32_bf16 v[124:127], v[144:147], v[182:185], v[124:127]
	v_mfma_f32_16x16x32_bf16 v[120:123], v[158:161], v[182:185], v[120:123]
	v_mfma_f32_16x16x32_bf16 v[108:111], v[144:147], v[190:193], v[108:111]
	v_mfma_f32_16x16x32_bf16 v[104:107], v[158:161], v[190:193], v[104:107]
	v_mfma_f32_16x16x32_bf16 v[92:95], v[144:147], v[198:201], v[92:95]
	v_mfma_f32_16x16x32_bf16 v[88:91], v[158:161], v[198:201], v[88:91]
	v_mfma_f32_16x16x32_bf16 v[76:79], v[144:147], v[206:209], v[76:79]
	v_mfma_f32_16x16x32_bf16 v[72:75], v[158:161], v[206:209], v[72:75]
	v_mfma_f32_16x16x32_bf16 v[124:127], v[154:157], v[186:189], v[124:127]
	v_mfma_f32_16x16x32_bf16 v[120:123], v[162:165], v[186:189], v[120:123]
	v_mfma_f32_16x16x32_bf16 v[108:111], v[154:157], v[194:197], v[108:111]
	v_mfma_f32_16x16x32_bf16 v[104:107], v[162:165], v[194:197], v[104:107]
	v_mfma_f32_16x16x32_bf16 v[92:95], v[154:157], v[202:205], v[92:95]
	v_mfma_f32_16x16x32_bf16 v[88:91], v[162:165], v[202:205], v[88:91]
	v_mfma_f32_16x16x32_bf16 v[76:79], v[154:157], v[210:213], v[76:79]
	v_mfma_f32_16x16x32_bf16 v[72:75], v[162:165], v[210:213], v[72:75]
	v_mfma_f32_16x16x32_bf16 v[116:119], v[166:169], v[182:185], v[116:119]
	v_mfma_f32_16x16x32_bf16 v[112:115], v[174:177], v[182:185], v[112:115]
	v_mfma_f32_16x16x32_bf16 v[100:103], v[166:169], v[190:193], v[100:103]
	v_mfma_f32_16x16x32_bf16 v[96:99], v[174:177], v[190:193], v[96:99]
	v_mfma_f32_16x16x32_bf16 v[84:87], v[166:169], v[198:201], v[84:87]
	v_mfma_f32_16x16x32_bf16 v[80:83], v[174:177], v[198:201], v[80:83]
	v_mfma_f32_16x16x32_bf16 v[68:71], v[166:169], v[206:209], v[68:71]
	v_mfma_f32_16x16x32_bf16 v[64:67], v[174:177], v[206:209], v[64:67]
	v_mfma_f32_16x16x32_bf16 v[116:119], v[170:173], v[186:189], v[116:119]
	v_mfma_f32_16x16x32_bf16 v[112:115], v[178:181], v[186:189], v[112:115]
	v_mfma_f32_16x16x32_bf16 v[100:103], v[170:173], v[194:197], v[100:103]
	v_mfma_f32_16x16x32_bf16 v[96:99], v[178:181], v[194:197], v[96:99]
	v_mfma_f32_16x16x32_bf16 v[84:87], v[170:173], v[202:205], v[84:87]
	v_mfma_f32_16x16x32_bf16 v[80:83], v[178:181], v[202:205], v[80:83]
	v_mfma_f32_16x16x32_bf16 v[68:71], v[170:173], v[210:213], v[68:71]
	v_mfma_f32_16x16x32_bf16 v[64:67], v[178:181], v[210:213], v[64:67]
	s_barrier
; #define PG8_STAGE(bufoff, gbase, voff) do { _Pragma("unroll") for (int _i = 0; _i < 2; ++_i) \
;         __builtin_amdgcn_global_load_lds((const unsigned*)((const char*)(gbase) + (voff)[_i]), (LAS unsigned*)(lds + (bufoff) + ldsw + _i * 8192), 16, 0, 0); } while (0)
; #define PG8_LDA(dst, b, h) do { _Pragma("unroll") for (int m = 0; m < 4; ++m) _Pragma("unroll") for (int k = 0; k < 2; ++k) dst[m][k] = *(const LAS bf16x8*)(lds + PG8_SA(b, h) + aoff + m * 2048 + k * 1024); } while (0)
; #define PG8_MMA(ai, bj, At, Bt) do { __builtin_amdgcn_s_setprio(1); _Pragma("unroll") for (int m = 0; m < 4; ++m) _Pragma("unroll") for (int n = 0; n < 2; ++n) _Pragma("unroll") for (int k = 0; k < 2; ++k) \
;         acc[ai][bj][m][n] = __builtin_amdgcn_mfma_f32_16x16x32_bf16(Bt[n][k], At[m][k], acc[ai][bj][m][n], 0, 0, 0); __builtin_amdgcn_s_setprio(0); } while (0)
; #define PG8_WAIT_V(n) asm volatile("s_waitcnt vmcnt(" #n ")" ::: "memory")
; #define PG8_WAIT_L(n) asm volatile("s_waitcnt lgkmcnt(" #n ")" ::: "memory")
; #define PG8_BAR __builtin_amdgcn_s_barrier()
; #define PG8_SCHED __builtin_amdgcn_sched_barrier(0)
; template <class Epi, class Sched>
; DI void gemm_phase(LAS unsigned char* lds, const Gemm g, const Sched& S, const Epi& E) {
;     ...
;             PG8_LDA(At, 1, 1); PG8_STAGE(PG8_SB(1, 0), b3, voffB); PG8_STAGE(PG8_SB(1, 1), b3 + hstepB, voffB); PG8_STAGE(PG8_SA(1, 0), a3, voffA);
;             PG8_WAIT_V(8); PG8_WAIT_L(0); PG8_BAR; PG8_MMA(1, 0, At, B0); PG8_MMA(1, 1, At, B1); PG8_BAR; PG8_SCHED;
;         }
;         if (wr == 0) PG8_BAR;
	s_setprio 0
	s_add_i32 s20, s48, s27
	v_lshl_add_u64 v[214:215], v[214:215], 0, s[10:11]
	s_mov_b32 m0, s20
	ds_read_b128 v[182:185], v153 offset:49152
	ds_read_b128 v[186:189], v153 offset:50176
	ds_read_b128 v[190:193], v153 offset:51200
	ds_read_b128 v[194:197], v153 offset:52224
	ds_read_b128 v[198:201], v153 offset:53248
	ds_read_b128 v[202:205], v153 offset:54272
	ds_read_b128 v[206:209], v153 offset:55296
	ds_read_b128 v[210:213], v153 offset:56320
	global_load_lds_dwordx4 v[214:215], off
	s_add_i32 m0, s20, 0x2000
	s_add_u32 s18, s18, 0xb0080
	v_lshl_add_u64 v[214:215], v[216:217], 0, s[10:11]
	s_addc_u32 s19, s19, 0
	s_add_i32 s20, s49, s27
	global_load_lds_dwordx4 v[214:215], off
	v_lshl_add_u64 v[214:215], s[18:19], 0, v[130:131]
	s_mov_b32 m0, s20
	s_nop 0
	global_load_lds_dwordx4 v[214:215], off
	v_lshl_add_u64 v[214:215], s[18:19], 0, v[134:135]
	s_add_i32 m0, s20, 0x2000
	s_nop 0
	global_load_lds_dwordx4 v[214:215], off
	v_lshl_add_u64 v[214:215], v[218:219], 0, s[10:11]
	s_mov_b32 m0, s36
	s_nop 0
	global_load_lds_dwordx4 v[214:215], off
	v_lshl_add_u64 v[214:215], v[220:221], 0, s[10:11]
	s_mov_b32 m0, s37
	s_nop 0
	global_load_lds_dwordx4 v[214:215], off
	s_waitcnt vmcnt(8)
	s_waitcnt lgkmcnt(0)
	s_setprio 1
	s_barrier
	v_mfma_f32_16x16x32_bf16 v[60:63], v[144:147], v[182:185], v[60:63]
	v_mfma_f32_16x16x32_bf16 v[56:59], v[158:161], v[182:185], v[56:59]
	v_mfma_f32_16x16x32_bf16 v[44:47], v[144:147], v[190:193], v[44:47]
	v_mfma_f32_16x16x32_bf16 v[40:43], v[158:161], v[190:193], v[40:43]
	v_mfma_f32_16x16x32_bf16 v[28:31], v[144:147], v[198:201], v[28:31]
	v_mfma_f32_16x16x32_bf16 v[24:27], v[158:161], v[198:201], v[24:27]
	v_mfma_f32_16x16x32_bf16 v[12:15], v[144:147], v[206:209], v[12:15]
	v_mfma_f32_16x16x32_bf16 v[8:11], v[158:161], v[206:209], v[8:11]
	v_mfma_f32_16x16x32_bf16 v[60:63], v[154:157], v[186:189], v[60:63]
	v_mfma_f32_16x16x32_bf16 v[56:59], v[162:165], v[186:189], v[56:59]
	v_mfma_f32_16x16x32_bf16 v[44:47], v[154:157], v[194:197], v[44:47]
	v_mfma_f32_16x16x32_bf16 v[40:43], v[162:165], v[194:197], v[40:43]
	v_mfma_f32_16x16x32_bf16 v[28:31], v[154:157], v[202:205], v[28:31]
	v_mfma_f32_16x16x32_bf16 v[24:27], v[162:165], v[202:205], v[24:27]
	v_mfma_f32_16x16x32_bf16 v[12:15], v[154:157], v[210:213], v[12:15]
	v_mfma_f32_16x16x32_bf16 v[8:11], v[162:165], v[210:213], v[8:11]
	v_mfma_f32_16x16x32_bf16 v[52:55], v[166:169], v[182:185], v[52:55]
	v_mfma_f32_16x16x32_bf16 v[48:51], v[174:177], v[182:185], v[48:51]
	v_mfma_f32_16x16x32_bf16 v[36:39], v[166:169], v[190:193], v[36:39]
	v_mfma_f32_16x16x32_bf16 v[32:35], v[174:177], v[190:193], v[32:35]
	v_mfma_f32_16x16x32_bf16 v[20:23], v[166:169], v[198:201], v[20:23]
	v_mfma_f32_16x16x32_bf16 v[16:19], v[174:177], v[198:201], v[16:19]
	v_mfma_f32_16x16x32_bf16 v[4:7], v[166:169], v[206:209], v[4:7]
	v_mfma_f32_16x16x32_bf16 v[0:3], v[174:177], v[206:209], v[0:3]
	v_mfma_f32_16x16x32_bf16 v[52:55], v[170:173], v[186:189], v[52:55]
	v_mfma_f32_16x16x32_bf16 v[48:51], v[178:181], v[186:189], v[48:51]
	v_mfma_f32_16x16x32_bf16 v[36:39], v[170:173], v[194:197], v[36:39]
	v_mfma_f32_16x16x32_bf16 v[32:35], v[178:181], v[194:197], v[32:35]
	v_mfma_f32_16x16x32_bf16 v[20:23], v[170:173], v[202:205], v[20:23]
	v_mfma_f32_16x16x32_bf16 v[16:19], v[178:181], v[202:205], v[16:19]
	v_mfma_f32_16x16x32_bf16 v[4:7], v[170:173], v[210:213], v[4:7]
	v_mfma_f32_16x16x32_bf16 v[0:3], v[178:181], v[210:213], v[0:3]
	s_barrier
	s_setprio 0
	s_add_i32 s47, s47, 2
	s_add_u32 s16, s16, 0x100
	s_addc_u32 s17, s17, 0
	s_add_u32 s45, s45, 0x100
	s_addc_u32 s46, s46, 0
	s_cmp_gt_u32 s47, 41
	s_cbranch_scc0 .LBB0_1331
	s_and_b64 vcc, exec, s[12:13]
	s_cbranch_vccz .LBB0_1334
	s_barrier
